# v025stack
# speedup vs baseline: 1.0647x; 1.0035x over previous
; DEV char* opaque_ptr(char* q) { asm volatile("" : "+s"(q)); return q; }
; __device__ void phase0(const P& p) {
;   char* ws = opaque_ptr(p.ws);
;   const size_t gtid = (size_t)blockIdx.x * 512 + threadIdx.x;
;   const size_t gsz = (size_t)gridDim.x * 512;
;   HALF* x16 = (HALF*)(ws + OFF_X16);
;   const size_t nvec = (size_t)NTOK * 1024 / 8;
;   const size_t npv = (size_t)NPROMPT * 1024 / 8;
;   for (size_t i = gtid; i < nvec; i += gsz) {
;     const float* src = (i < npv) ? (p.xp + i * 8) : (p.xs + (i - npv) * 8);
;     f4 a = *(const f4*)src;
;     f4 b = *(const f4*)(src + 4);
;     h8 o;
;     o[0] = (HALF)a[0]; o[1] = (HALF)a[1]; o[2] = (HALF)a[2]; o[3] = (HALF)a[3];
;     o[4] = (HALF)b[0]; o[5] = (HALF)b[1]; o[6] = (HALF)b[2]; o[7] = (HALF)b[3];
;     *(h8*)(x16 + i * 8) = o;
;   }
_Z4mega1P:
	s_load_dwordx16 s[48:63], s[0:1], 0x0
	s_load_dwordx8 s[24:31], s[0:1], 0x60
	s_load_dwordx8 s[4:11], s[0:1], 0x40
	s_add_u32 s44, s0, 0x78
	s_addc_u32 s45, s1, 0
	s_load_dword s34, s[0:1], 0x80
	s_waitcnt lgkmcnt(0)
	s_mov_b64 s[0:1], s[28:29]
	v_writelane_b32 v254, s4, 0
	s_mov_b32 s3, 0
	v_and_b32_e32 v155, 0x3ff, v0
	v_writelane_b32 v254, s5, 1
	v_writelane_b32 v254, s6, 2
	v_writelane_b32 v254, s7, 3
	v_writelane_b32 v254, s8, 4
	v_writelane_b32 v254, s9, 5
	v_writelane_b32 v254, s10, 6
	v_writelane_b32 v254, s11, 7
	v_writelane_b32 v254, s0, 8
	s_mov_b32 s38, s30
	v_readfirstlane_b32 s33, v155
	v_writelane_b32 v254, s1, 9
	s_lshl_b64 s[0:1], s[2:3], 9
	v_or_b32_e32 v2, s0, v155
	v_mov_b32_e32 v3, s1
	v_writelane_b32 v254, s2, 10
	s_mov_b32 s39, s3
	s_mov_b64 s[0:1], 0xa00000
	s_mov_b64 s[36:37], s[28:29]
	v_mov_b32_e32 v7, 0
	v_writelane_b32 v254, s3, 11
	s_lshl_b64 s[6:7], s[38:39], 9
	v_cmp_gt_u64_e32 vcc, s[0:1], v[2:3]
	s_and_saveexec_b64 s[0:1], vcc
	s_cbranch_execz .LBB0_3
	v_readlane_b32 s2, v254, 10
	v_readlane_b32 s3, v254, 11
	s_lshl_b64 s[4:5], s[2:3], 13
	s_add_u32 s4, s36, s4
	v_lshlrev_b32_e32 v6, 4, v155
	s_addc_u32 s5, s37, s5
	v_lshl_add_u64 v[4:5], s[4:5], 0, v[6:7]
	s_mov_b64 s[4:5], 0x3eb0000
	v_lshl_add_u64 v[4:5], v[4:5], 0, s[4:5]
	s_lshl_b64 s[4:5], s[38:39], 13
	s_add_u32 s8, s50, 0xfc000000
	s_addc_u32 s9, s51, -1
	s_lshl_b64 s[10:11], s[2:3], 14
	v_lshlrev_b32_e32 v6, 5, v155
	v_lshl_add_u64 v[6:7], s[10:11], 0, v[6:7]
	s_lshl_b64 s[10:11], s[38:39], 14
	s_mov_b64 s[12:13], 0
	s_mov_b64 s[14:15], 0x200000
	s_mov_b64 s[16:17], 0x9fffff
	v_mov_b64_e32 v[8:9], v[2:3]
	s_cmp_eq_u32 s38, 0x100
	s_cbranch_scc0 .LBB0_2
	s_mov_b64 s[18:19], s[48:49]
	s_mov_b32 s20, 0
	s_mov_b64 s[22:23], 0x1000000
.Lp0_x4:
	v_lshl_add_u64 v[10:11], s[18:19], 0, v[6:7]
	v_lshl_add_u64 v[12:13], v[10:11], 0, s[10:11]
	v_lshl_add_u64 v[14:15], v[12:13], 0, s[10:11]
	v_lshl_add_u64 v[16:17], v[14:15], 0, s[10:11]
	global_load_dwordx4 v[20:23], v[10:11], off
	global_load_dwordx4 v[24:27], v[10:11], off offset:16
	global_load_dwordx4 v[28:31], v[12:13], off
	global_load_dwordx4 v[32:35], v[12:13], off offset:16
	global_load_dwordx4 v[36:39], v[14:15], off
	global_load_dwordx4 v[40:43], v[14:15], off offset:16
	global_load_dwordx4 v[44:47], v[16:17], off
	global_load_dwordx4 v[48:51], v[16:17], off offset:16
	v_lshl_add_u64 v[6:7], v[6:7], 0, s[22:23]
	s_waitcnt vmcnt(6)
	v_cvt_pk_f16_f32 v52, v20, v21
	v_cvt_pk_f16_f32 v53, v22, v23
	v_cvt_pk_f16_f32 v54, v24, v25
	v_cvt_pk_f16_f32 v55, v26, v27
	global_store_dwordx4 v[4:5], v[52:55], off
	v_lshl_add_u64 v[4:5], v[4:5], 0, s[4:5]
	s_waitcnt vmcnt(5)
	v_cvt_pk_f16_f32 v56, v28, v29
	v_cvt_pk_f16_f32 v57, v30, v31
	v_cvt_pk_f16_f32 v58, v32, v33
	v_cvt_pk_f16_f32 v59, v34, v35
	global_store_dwordx4 v[4:5], v[56:59], off
	v_lshl_add_u64 v[4:5], v[4:5], 0, s[4:5]
	s_waitcnt vmcnt(4)
	v_cvt_pk_f16_f32 v60, v36, v37
	v_cvt_pk_f16_f32 v61, v38, v39
	v_cvt_pk_f16_f32 v62, v40, v41
	v_cvt_pk_f16_f32 v63, v42, v43
	global_store_dwordx4 v[4:5], v[60:63], off
	v_lshl_add_u64 v[4:5], v[4:5], 0, s[4:5]
	s_waitcnt vmcnt(3)
	v_cvt_pk_f16_f32 v52, v44, v45
	v_cvt_pk_f16_f32 v53, v46, v47
	v_cvt_pk_f16_f32 v54, v48, v49
	v_cvt_pk_f16_f32 v55, v50, v51
	global_store_dwordx4 v[4:5], v[52:55], off
	v_lshl_add_u64 v[4:5], v[4:5], 0, s[4:5]
	s_add_i32 s20, s20, 1
	s_cmp_lt_u32 s20, 4
	s_cselect_b32 s18, s48, s8
	s_cselect_b32 s19, s49, s9
	s_cmp_lt_u32 s20, 20
	s_cbranch_scc1 .Lp0_x4
	s_branch .LBB0_3

; #define FOR_R _Pragma("unroll") for (int r = 0; r < 4; ++r)
; #define FOR_AI _Pragma("unroll") for (int ai = 0; ai < 2; ++ai)
; #define FOR_BJ _Pragma("unroll") for (int bj = 0; bj < 2; ++bj)
; #define FOR_M4 _Pragma("unroll") for (int m = 0; m < 4; ++m)
; template <bool ISK>
; __device__ void job_qk_g(const P& p, int l, int g, int ct2, int rt, HALF* sm) {
;     ...
;   const float2* rope = (const float2*)(ws + OFF_ROPE);
;   FOR_AI FOR_BJ {
;     FOR_M4 {
;       const int row0 = ai * 128 + wr * 64 + m * 16 + fq * 4;
;       const int lc = bj * 128 + wc * 32 + fr;
;       const int j = (bj * 4 + wc) * 16 + fr;
;       f4 o1, o2;
;       FOR_R {
;         const int sp = (rt * 256 + row0 + r) & (S - 1);
;         const float2 cs = rope[sp * 128 + j];
;         const float a = acc[ai][bj][m][0][r], b = acc[ai][bj][m][1][r];
;         o1[r] = a * cs.x - b * cs.y;
;         o2[r] = a * cs.y + b * cs.x;
;       }
;       acc[ai][bj][m][0] = o1;
;       acc[ai][bj][m][1] = o2;
;       stage2_rm(sm, row0, lc, to_h4(o1));
;       stage2_rm(sm, row0, lc + 16, to_h4(o2));
;       __builtin_amdgcn_sched_barrier(0);
;     }
;   }
.LBB0_196:
	s_or_b64 exec, exec, s[2:3]
	v_lshrrev_b32_e32 v129, 2, v130
	v_ashrrev_i32_e32 v128, 2, v130
	v_and_b32_e32 v129, 12, v129
	s_movk_i32 s6, 0xffc0
	v_and_or_b32 v142, v128, s6, v129
	v_add_u32_e32 v128, s21, v142
	v_bfe_u32 v140, v130, 6, 2
	v_and_b32_e32 v141, 15, v130
	v_and_b32_e32 v130, s22, v128
	v_lshl_or_b32 v129, v140, 4, v141
	v_lshlrev_b32_e32 v143, 7, v130
	v_bitop3_b32 v132, v128, s22, 1 bitop3:0xc8
	s_add_u32 s2, s0, 0x3680000
	v_or_b32_e32 v130, v143, v129
	v_lshlrev_b32_e32 v144, 7, v132
	s_addc_u32 s3, s1, 0
	v_lshlrev_b32_e32 v152, 3, v130
	v_or_b32_e32 v132, v144, v129
	v_lshl_add_u64 v[130:131], s[2:3], 0, v[152:153]
	v_lshlrev_b32_e32 v152, 3, v132
	v_lshl_add_u64 v[132:133], s[2:3], 0, v[152:153]
	s_waitcnt vmcnt(0)
	s_barrier
	v_lshrrev_b32_e32 v226, 8, v155
	v_lshlrev_b32_e32 v226, 6, v226
	v_bfe_u32 v227, v155, 4, 2
	v_lshl_or_b32 v226, v227, 2, v226
	v_add_u32_e32 v226, s21, v226
	v_and_b32_e32 v226, s22, v226
	v_bfe_u32 v227, v155, 6, 2
	v_lshlrev_b32_e32 v227, 4, v227
	v_and_or_b32 v227, v155, 15, v227
	v_lshl_or_b32 v226, v226, 7, v227
	v_lshlrev_b32_e32 v226, 3, v226
	v_mov_b32_e32 v227, v226
	global_load_dwordx2 v[194:195], v227, s[2:3]
	global_load_dwordx2 v[196:197], v227, s[2:3] offset:1024
	global_load_dwordx2 v[198:199], v227, s[2:3] offset:2048
	global_load_dwordx2 v[200:201], v227, s[2:3] offset:3072
	v_add_u32_e32 v227, 0x4000, v226
	global_load_dwordx2 v[202:203], v227, s[2:3]
	global_load_dwordx2 v[204:205], v227, s[2:3] offset:1024
	global_load_dwordx2 v[206:207], v227, s[2:3] offset:2048
	global_load_dwordx2 v[208:209], v227, s[2:3] offset:3072
	v_add_u32_e32 v227, 0x8000, v226
	global_load_dwordx2 v[210:211], v227, s[2:3]
	global_load_dwordx2 v[212:213], v227, s[2:3] offset:1024
	global_load_dwordx2 v[214:215], v227, s[2:3] offset:2048
	global_load_dwordx2 v[216:217], v227, s[2:3] offset:3072
	v_add_u32_e32 v227, 0xc000, v226
	global_load_dwordx2 v[218:219], v227, s[2:3]
	global_load_dwordx2 v[220:221], v227, s[2:3] offset:1024
	global_load_dwordx2 v[222:223], v227, s[2:3] offset:2048
	global_load_dwordx2 v[224:225], v227, s[2:3] offset:3072
	s_waitcnt vmcnt(15)
	v_mov_b32_e32 v134, v194
	v_mov_b32_e32 v135, v195
	s_nop 0
	s_waitcnt vmcnt(14)
	v_mov_b32_e32 v132, v196
	v_mov_b32_e32 v133, v197
	v_bitop3_b32 v130, v128, s22, 2 bitop3:0xc8
	v_lshlrev_b32_e32 v145, 7, v130
	v_or_b32_e32 v130, v145, v129
	v_lshlrev_b32_e32 v152, 3, v130
	v_lshl_add_u64 v[130:131], s[2:3], 0, v[152:153]
	s_waitcnt vmcnt(13)
	v_mov_b32_e32 v136, v198
	v_mov_b32_e32 v137, v199
	v_bitop3_b32 v130, v128, s22, 3 bitop3:0xc8
	v_lshlrev_b32_e32 v146, 7, v130
	v_or_b32_e32 v130, v146, v129
	v_lshlrev_b32_e32 v152, 3, v130
	v_lshl_add_u64 v[130:131], s[2:3], 0, v[152:153]
	s_waitcnt vmcnt(12)
	v_mov_b32_e32 v138, v200
	v_mov_b32_e32 v139, v201
	v_lshlrev_b32_e32 v130, 1, v141
	v_lshl_or_b32 v130, v140, 6, v130
	v_mul_lo_u32 v131, v142, s64
	v_add_u32_e32 v140, 48, v128
	v_add3_u32 v130, 0, v131, v130
	v_and_b32_e32 v131, s22, v140
	v_lshlrev_b32_e32 v131, 7, v131
	v_mul_f32_e32 v140, v124, v135
	v_mul_f32_e32 v135, v120, v135
	v_mul_f32_e32 v141, v125, v133
	v_mul_f32_e32 v133, v121, v133
	v_fma_mixlo_f16 v120, v120, v134, -v140
	v_fma_mixlo_f16 v124, v124, v134, v135
	v_fma_mixlo_f16 v121, v121, v132, -v141
	v_mul_f32_e32 v134, v126, v137
	v_mul_f32_e32 v135, v122, v137
	ds_write_b16 v130, v120
	v_fma_mixlo_f16 v120, v125, v132, v133
	ds_write_b16 v130, v124 offset:32
	v_fma_mixlo_f16 v122, v122, v136, -v134
	v_mul_f32_e32 v124, v127, v139
	v_mul_f32_e32 v125, v123, v139
	ds_write_b16 v130, v121 offset:528
	v_fma_mixlo_f16 v121, v126, v136, v135
	ds_write_b16 v130, v120 offset:560
	v_fma_mixlo_f16 v120, v123, v138, -v124
	ds_write_b16 v130, v122 offset:1056
	v_fma_mixlo_f16 v122, v127, v138, v125
	ds_write_b16 v130, v121 offset:1088
	ds_write_b16 v130, v120 offset:1584
	ds_write_b16 v130, v122 offset:1616
	v_add_u32_e32 v120, 16, v128
	v_and_b32_e32 v120, s22, v120
	v_add_u32_e32 v122, 17, v128
	v_lshlrev_b32_e32 v132, 7, v120
	v_and_b32_e32 v122, s22, v122
	v_add_u32_e32 v124, 18, v128
	v_or_b32_e32 v120, v132, v129
	v_lshlrev_b32_e32 v133, 7, v122
	v_and_b32_e32 v124, s22, v124
	v_add_u32_e32 v126, 19, v128
	v_lshlrev_b32_e32 v152, 3, v120
	v_or_b32_e32 v122, v133, v129
	v_lshlrev_b32_e32 v134, 7, v124
	v_and_b32_e32 v126, s22, v126
	v_lshl_add_u64 v[120:121], s[2:3], 0, v[152:153]
	v_lshlrev_b32_e32 v152, 3, v122
	v_or_b32_e32 v124, v134, v129
	v_lshlrev_b32_e32 v135, 7, v126
	v_lshl_add_u64 v[122:123], s[2:3], 0, v[152:153]
	v_lshlrev_b32_e32 v152, 3, v124
	v_or_b32_e32 v126, v135, v129
	s_waitcnt vmcnt(11)
	v_mov_b32_e32 v120, v202
	v_mov_b32_e32 v121, v203
	s_nop 0
	s_waitcnt vmcnt(10)
	v_mov_b32_e32 v122, v204
	v_mov_b32_e32 v123, v205
	v_lshl_add_u64 v[124:125], s[2:3], 0, v[152:153]
	v_lshlrev_b32_e32 v152, 3, v126
	s_waitcnt vmcnt(9)
	v_mov_b32_e32 v124, v206
	v_mov_b32_e32 v125, v207
	v_lshl_add_u64 v[126:127], s[2:3], 0, v[152:153]
	s_waitcnt vmcnt(8)
; #define FOR_R _Pragma("unroll") for (int r = 0; r < 4; ++r)
; #define FOR_AI _Pragma("unroll") for (int ai = 0; ai < 2; ++ai)
; #define FOR_BJ _Pragma("unroll") for (int bj = 0; bj < 2; ++bj)
; #define FOR_M4 _Pragma("unroll") for (int m = 0; m < 4; ++m)
; template <bool ISK>
; __device__ void job_qk_g(const P& p, int l, int g, int ct2, int rt, HALF* sm) {
;     ...
;   const float2* rope = (const float2*)(ws + OFF_ROPE);
;   FOR_AI FOR_BJ {
;     FOR_M4 {
;       const int row0 = ai * 128 + wr * 64 + m * 16 + fq * 4;
;       const int lc = bj * 128 + wc * 32 + fr;
;       const int j = (bj * 4 + wc) * 16 + fr;
;       f4 o1, o2;
;       FOR_R {
;         const int sp = (rt * 256 + row0 + r) & (S - 1);
;         const float2 cs = rope[sp * 128 + j];
;         const float a = acc[ai][bj][m][0][r], b = acc[ai][bj][m][1][r];
;         o1[r] = a * cs.x - b * cs.y;
;         o2[r] = a * cs.y + b * cs.x;
;       }
;       acc[ai][bj][m][0] = o1;
;       acc[ai][bj][m][1] = o2;
;       stage2_rm(sm, row0, lc, to_h4(o1));
;       stage2_rm(sm, row0, lc + 16, to_h4(o2));
;       __builtin_amdgcn_sched_barrier(0);
;     }
;   }
	v_mov_b32_e32 v126, v208
	v_mov_b32_e32 v127, v209
	v_mul_f32_e32 v136, v116, v121
	v_mul_f32_e32 v121, v112, v121
	v_mul_f32_e32 v137, v117, v123
	v_mul_f32_e32 v123, v113, v123
	v_fma_mixlo_f16 v112, v112, v120, -v136
	v_fma_mixlo_f16 v116, v116, v120, v121
	v_mul_f32_e32 v120, v118, v125
	v_mul_f32_e32 v121, v114, v125
	v_fma_mixlo_f16 v113, v113, v122, -v137
	ds_write_b16 v130, v112 offset:8448
	v_fma_mixlo_f16 v112, v117, v122, v123
	ds_write_b16 v130, v116 offset:8480
	v_mul_f32_e32 v116, v119, v127
	v_mul_f32_e32 v117, v115, v127
	v_fma_mixlo_f16 v114, v114, v124, -v120
	ds_write_b16 v130, v113 offset:8976
	v_fma_mixlo_f16 v113, v118, v124, v121
	ds_write_b16 v130, v112 offset:9008
	v_fma_mixlo_f16 v112, v115, v126, -v116
	ds_write_b16 v130, v114 offset:9504
	v_fma_mixlo_f16 v114, v119, v126, v117
	ds_write_b16 v130, v113 offset:9536
	ds_write_b16 v130, v112 offset:10032
	ds_write_b16 v130, v114 offset:10064
	v_add_u32_e32 v112, 32, v128
	v_and_b32_e32 v112, s22, v112
	v_add_u32_e32 v114, 33, v128
	v_lshlrev_b32_e32 v120, 7, v112
	v_and_b32_e32 v114, s22, v114
	v_add_u32_e32 v116, 34, v128
	v_or_b32_e32 v112, v120, v129
	v_lshlrev_b32_e32 v121, 7, v114
	v_and_b32_e32 v116, s22, v116
	v_add_u32_e32 v118, 35, v128
	v_lshlrev_b32_e32 v152, 3, v112
	v_or_b32_e32 v114, v121, v129
	v_lshlrev_b32_e32 v122, 7, v116
	v_and_b32_e32 v118, s22, v118
	v_lshl_add_u64 v[112:113], s[2:3], 0, v[152:153]
	v_lshlrev_b32_e32 v152, 3, v114
	v_or_b32_e32 v116, v122, v129
	v_lshlrev_b32_e32 v123, 7, v118
	v_lshl_add_u64 v[114:115], s[2:3], 0, v[152:153]
	v_lshlrev_b32_e32 v152, 3, v116
	v_or_b32_e32 v118, v123, v129
	v_add_u32_e32 v227, 0x200, v226
	global_load_dwordx2 v[194:195], v227, s[2:3]
	global_load_dwordx2 v[196:197], v227, s[2:3] offset:1024
	global_load_dwordx2 v[198:199], v227, s[2:3] offset:2048
	global_load_dwordx2 v[200:201], v227, s[2:3] offset:3072
	v_add_u32_e32 v227, 0x4200, v226
	global_load_dwordx2 v[202:203], v227, s[2:3]
	global_load_dwordx2 v[204:205], v227, s[2:3] offset:1024
	global_load_dwordx2 v[206:207], v227, s[2:3] offset:2048
	global_load_dwordx2 v[208:209], v227, s[2:3] offset:3072
	s_waitcnt vmcnt(15)
	v_mov_b32_e32 v112, v210
	v_mov_b32_e32 v113, v211
	s_nop 0
	s_waitcnt vmcnt(14)
	v_mov_b32_e32 v114, v212
	v_mov_b32_e32 v115, v213
	v_lshl_add_u64 v[116:117], s[2:3], 0, v[152:153]
	v_lshlrev_b32_e32 v152, 3, v118
	s_waitcnt vmcnt(13)
	v_mov_b32_e32 v116, v214
	v_mov_b32_e32 v117, v215
	v_lshl_add_u64 v[118:119], s[2:3], 0, v[152:153]
	s_waitcnt vmcnt(12)
	v_mov_b32_e32 v118, v216
	v_mov_b32_e32 v119, v217
	v_mul_f32_e32 v124, v108, v113
	v_mul_f32_e32 v113, v104, v113
	v_mul_f32_e32 v125, v109, v115
	v_mul_f32_e32 v115, v105, v115
	v_fma_mixlo_f16 v104, v104, v112, -v124
	v_fma_mixlo_f16 v108, v108, v112, v113
	v_mul_f32_e32 v112, v110, v117
	v_mul_f32_e32 v113, v106, v117
	v_fma_mixlo_f16 v105, v105, v114, -v125
	ds_write_b16 v130, v104 offset:16896
	v_fma_mixlo_f16 v104, v109, v114, v115
	ds_write_b16 v130, v108 offset:16928
	v_mul_f32_e32 v108, v111, v119
	v_mul_f32_e32 v109, v107, v119
	v_fma_mixlo_f16 v106, v106, v116, -v112
	ds_write_b16 v130, v105 offset:17424
	v_fma_mixlo_f16 v105, v110, v116, v113
	ds_write_b16 v130, v104 offset:17456
	v_fma_mixlo_f16 v104, v107, v118, -v108
	ds_write_b16 v130, v106 offset:17952
	v_fma_mixlo_f16 v106, v111, v118, v109
	ds_write_b16 v130, v105 offset:17984
	ds_write_b16 v130, v104 offset:18480
	ds_write_b16 v130, v106 offset:18512
	v_add_u32_e32 v106, 49, v128
	v_or_b32_e32 v104, v131, v129
	v_and_b32_e32 v106, s22, v106
	v_add_u32_e32 v108, 50, v128
	v_lshlrev_b32_e32 v152, 3, v104
	v_lshlrev_b32_e32 v112, 7, v106
	v_and_b32_e32 v108, s22, v108
	v_add_u32_e32 v110, 51, v128
	v_lshl_add_u64 v[104:105], s[2:3], 0, v[152:153]
	v_or_b32_e32 v106, v112, v129
	v_lshlrev_b32_e32 v113, 7, v108
	v_and_b32_e32 v110, s22, v110
	s_waitcnt vmcnt(11)
	v_mov_b32_e32 v104, v218
	v_mov_b32_e32 v105, v219
	v_lshlrev_b32_e32 v152, 3, v106
	v_or_b32_e32 v108, v113, v129
	v_lshlrev_b32_e32 v114, 7, v110
	v_lshl_add_u64 v[106:107], s[2:3], 0, v[152:153]
	v_lshlrev_b32_e32 v152, 3, v108
	v_or_b32_e32 v110, v114, v129
	v_lshl_add_u64 v[108:109], s[2:3], 0, v[152:153]
	v_lshlrev_b32_e32 v152, 3, v110
	s_waitcnt vmcnt(10)
	v_mov_b32_e32 v106, v220
	v_mov_b32_e32 v107, v221
	s_nop 0
	s_waitcnt vmcnt(9)
	v_mov_b32_e32 v108, v222
	v_mov_b32_e32 v109, v223
	v_lshl_add_u64 v[110:111], s[2:3], 0, v[152:153]
	s_waitcnt vmcnt(8)
	v_mov_b32_e32 v110, v224
	v_mov_b32_e32 v111, v225
	v_mul_f32_e32 v115, v100, v105
	v_mul_f32_e32 v105, v96, v105
	v_fma_mixlo_f16 v96, v96, v104, -v115
	v_fma_mixlo_f16 v100, v100, v104, v105
	ds_write_b16 v130, v96 offset:25344
	ds_write_b16 v130, v100 offset:25376
	v_mul_f32_e32 v96, v101, v107
	v_mul_f32_e32 v100, v97, v107
	v_mul_f32_e32 v104, v102, v109
	v_mul_f32_e32 v105, v98, v109
	v_fma_mixlo_f16 v96, v97, v106, -v96
	v_fma_mixlo_f16 v97, v101, v106, v100
	v_mul_f32_e32 v100, v103, v111
	v_mul_f32_e32 v101, v99, v111
	v_fma_mixlo_f16 v98, v98, v108, -v104
	ds_write_b16 v130, v96 offset:25872
	v_fma_mixlo_f16 v96, v102, v108, v105
	ds_write_b16 v130, v97 offset:25904
	v_fma_mixlo_f16 v97, v99, v110, -v100
	ds_write_b16 v130, v98 offset:26400
	v_fma_mixlo_f16 v98, v103, v110, v101
	ds_write_b16 v130, v96 offset:26432
	ds_write_b16 v130, v97 offset:26928
	ds_write_b16 v130, v98 offset:26960
	v_or_b32_e32 v96, 64, v129
	v_or_b32_e32 v97, v143, v96
	v_lshlrev_b32_e32 v152, 3, v97
	v_or_b32_e32 v97, v144, v96
	v_lshl_add_u64 v[98:99], s[2:3], 0, v[152:153]
	v_lshlrev_b32_e32 v152, 3, v97
	v_or_b32_e32 v97, v145, v96
	v_lshl_add_u64 v[100:101], s[2:3], 0, v[152:153]
	v_lshlrev_b32_e32 v152, 3, v97
	v_or_b32_e32 v97, v146, v96
	v_add_u32_e32 v227, 0x8200, v226
	global_load_dwordx2 v[210:211], v227, s[2:3]
	global_load_dwordx2 v[212:213], v227, s[2:3] offset:1024
	global_load_dwordx2 v[214:215], v227, s[2:3] offset:2048
	global_load_dwordx2 v[216:217], v227, s[2:3] offset:3072
	v_add_u32_e32 v227, 0xc200, v226
	global_load_dwordx2 v[218:219], v227, s[2:3]
	global_load_dwordx2 v[220:221], v227, s[2:3] offset:1024
	global_load_dwordx2 v[222:223], v227, s[2:3] offset:2048
	global_load_dwordx2 v[224:225], v227, s[2:3] offset:3072
	s_waitcnt vmcnt(15)
; #define FOR_R _Pragma("unroll") for (int r = 0; r < 4; ++r)
; #define FOR_AI _Pragma("unroll") for (int ai = 0; ai < 2; ++ai)
; #define FOR_BJ _Pragma("unroll") for (int bj = 0; bj < 2; ++bj)
; #define FOR_M4 _Pragma("unroll") for (int m = 0; m < 4; ++m)
; template <bool ISK>
; __device__ void job_qk_g(const P& p, int l, int g, int ct2, int rt, HALF* sm) {
;     ...
;   const float2* rope = (const float2*)(ws + OFF_ROPE);
;   FOR_AI FOR_BJ {
;     FOR_M4 {
;       const int row0 = ai * 128 + wr * 64 + m * 16 + fq * 4;
;       const int lc = bj * 128 + wc * 32 + fr;
;       const int j = (bj * 4 + wc) * 16 + fr;
;       f4 o1, o2;
;       FOR_R {
;         const int sp = (rt * 256 + row0 + r) & (S - 1);
;         const float2 cs = rope[sp * 128 + j];
;         const float a = acc[ai][bj][m][0][r], b = acc[ai][bj][m][1][r];
;         o1[r] = a * cs.x - b * cs.y;
;         o2[r] = a * cs.y + b * cs.x;
;       }
;       acc[ai][bj][m][0] = o1;
;       acc[ai][bj][m][1] = o2;
;       stage2_rm(sm, row0, lc, to_h4(o1));
;       stage2_rm(sm, row0, lc + 16, to_h4(o2));
;       __builtin_amdgcn_sched_barrier(0);
;     }
;   }
	v_mov_b32_e32 v98, v194
	v_mov_b32_e32 v99, v195
	v_lshl_add_u64 v[102:103], s[2:3], 0, v[152:153]
	s_waitcnt vmcnt(14)
	v_mov_b32_e32 v100, v196
	v_mov_b32_e32 v101, v197
	v_lshlrev_b32_e32 v152, 3, v97
	s_waitcnt vmcnt(13)
	v_mov_b32_e32 v102, v198
	v_mov_b32_e32 v103, v199
	v_lshl_add_u64 v[104:105], s[2:3], 0, v[152:153]
	s_waitcnt vmcnt(12)
	v_mov_b32_e32 v104, v200
	v_mov_b32_e32 v105, v201
	v_mul_f32_e32 v97, v92, v99
	v_mul_f32_e32 v99, v88, v99
	v_mul_f32_e32 v106, v93, v101
	v_mul_f32_e32 v101, v89, v101
	v_fma_mixlo_f16 v88, v88, v98, -v97
	v_fma_mixlo_f16 v92, v92, v98, v99
	v_mul_f32_e32 v97, v94, v103
	v_mul_f32_e32 v98, v90, v103
	v_fma_mixlo_f16 v89, v89, v100, -v106
	ds_write_b16 v130, v88 offset:256
	v_fma_mixlo_f16 v88, v93, v100, v101
	ds_write_b16 v130, v92 offset:288
	v_mul_f32_e32 v92, v95, v105
	v_mul_f32_e32 v93, v91, v105
	v_fma_mixlo_f16 v90, v90, v102, -v97
	ds_write_b16 v130, v89 offset:784
	v_fma_mixlo_f16 v89, v94, v102, v98
	ds_write_b16 v130, v88 offset:816
	v_fma_mixlo_f16 v88, v91, v104, -v92
	ds_write_b16 v130, v90 offset:1312
	v_fma_mixlo_f16 v90, v95, v104, v93
	ds_write_b16 v130, v89 offset:1344
	ds_write_b16 v130, v88 offset:1840
	ds_write_b16 v130, v90 offset:1872
	v_or_b32_e32 v88, v132, v96
	v_lshlrev_b32_e32 v152, 3, v88
	v_or_b32_e32 v90, v133, v96
	v_lshl_add_u64 v[88:89], s[2:3], 0, v[152:153]
	v_lshlrev_b32_e32 v152, 3, v90
	v_or_b32_e32 v92, v134, v96
	v_lshl_add_u64 v[90:91], s[2:3], 0, v[152:153]
	v_lshlrev_b32_e32 v152, 3, v92
	v_or_b32_e32 v94, v135, v96
	s_waitcnt vmcnt(11)
	v_mov_b32_e32 v88, v202
	v_mov_b32_e32 v89, v203
	v_lshl_add_u64 v[92:93], s[2:3], 0, v[152:153]
	s_waitcnt vmcnt(10)
	v_mov_b32_e32 v90, v204
	v_mov_b32_e32 v91, v205
	v_lshlrev_b32_e32 v152, 3, v94
	s_waitcnt vmcnt(9)
	v_mov_b32_e32 v92, v206
	v_mov_b32_e32 v93, v207
	v_lshl_add_u64 v[94:95], s[2:3], 0, v[152:153]
	s_waitcnt vmcnt(8)
	v_mov_b32_e32 v94, v208
	v_mov_b32_e32 v95, v209
	v_mul_f32_e32 v97, v84, v89
	v_mul_f32_e32 v89, v80, v89
	v_mul_f32_e32 v98, v85, v91
	v_mul_f32_e32 v91, v81, v91
	v_fma_mixlo_f16 v80, v80, v88, -v97
	v_fma_mixlo_f16 v84, v84, v88, v89
	v_mul_f32_e32 v88, v86, v93
	v_mul_f32_e32 v89, v82, v93
	v_fma_mixlo_f16 v81, v81, v90, -v98
	ds_write_b16 v130, v80 offset:8704
	v_fma_mixlo_f16 v80, v85, v90, v91
	ds_write_b16 v130, v84 offset:8736
	v_mul_f32_e32 v84, v87, v95
	v_mul_f32_e32 v85, v83, v95
	v_fma_mixlo_f16 v82, v82, v92, -v88
	ds_write_b16 v130, v81 offset:9232
	v_fma_mixlo_f16 v81, v86, v92, v89
	ds_write_b16 v130, v80 offset:9264
	v_fma_mixlo_f16 v80, v83, v94, -v84
	ds_write_b16 v130, v82 offset:9760
	v_fma_mixlo_f16 v82, v87, v94, v85
	ds_write_b16 v130, v81 offset:9792
	ds_write_b16 v130, v80 offset:10288
	ds_write_b16 v130, v82 offset:10320
	v_or_b32_e32 v80, v120, v96
	v_lshlrev_b32_e32 v152, 3, v80
	v_or_b32_e32 v82, v121, v96
	v_lshl_add_u64 v[80:81], s[2:3], 0, v[152:153]
	v_lshlrev_b32_e32 v152, 3, v82
	v_or_b32_e32 v84, v122, v96
	v_lshl_add_u64 v[82:83], s[2:3], 0, v[152:153]
	v_lshlrev_b32_e32 v152, 3, v84
	v_or_b32_e32 v86, v123, v96
	v_add_u32_e32 v227, 0x20000, v226
	global_load_dwordx2 v[194:195], v227, s[2:3]
	global_load_dwordx2 v[196:197], v227, s[2:3] offset:1024
	global_load_dwordx2 v[198:199], v227, s[2:3] offset:2048
	global_load_dwordx2 v[200:201], v227, s[2:3] offset:3072
	v_add_u32_e32 v227, 0x24000, v226
	global_load_dwordx2 v[202:203], v227, s[2:3]
	global_load_dwordx2 v[204:205], v227, s[2:3] offset:1024
	global_load_dwordx2 v[206:207], v227, s[2:3] offset:2048
	global_load_dwordx2 v[208:209], v227, s[2:3] offset:3072
	s_waitcnt vmcnt(15)
	v_mov_b32_e32 v80, v210
	v_mov_b32_e32 v81, v211
	v_lshl_add_u64 v[84:85], s[2:3], 0, v[152:153]
	s_waitcnt vmcnt(14)
	v_mov_b32_e32 v82, v212
	v_mov_b32_e32 v83, v213
	v_lshlrev_b32_e32 v152, 3, v86
	s_waitcnt vmcnt(13)
	v_mov_b32_e32 v84, v214
	v_mov_b32_e32 v85, v215
	v_lshl_add_u64 v[86:87], s[2:3], 0, v[152:153]
	s_waitcnt vmcnt(12)
	v_mov_b32_e32 v86, v216
	v_mov_b32_e32 v87, v217
	v_mul_f32_e32 v88, v76, v81
	v_mul_f32_e32 v81, v72, v81
	v_mul_f32_e32 v89, v77, v83
	v_mul_f32_e32 v83, v73, v83
	v_fma_mixlo_f16 v72, v72, v80, -v88
	v_fma_mixlo_f16 v76, v76, v80, v81
	v_mul_f32_e32 v80, v78, v85
	v_mul_f32_e32 v81, v74, v85
	v_fma_mixlo_f16 v73, v73, v82, -v89
	ds_write_b16 v130, v72 offset:17152
	v_fma_mixlo_f16 v72, v77, v82, v83
	ds_write_b16 v130, v76 offset:17184
	v_mul_f32_e32 v76, v79, v87
	v_mul_f32_e32 v77, v75, v87
	v_fma_mixlo_f16 v74, v74, v84, -v80
	ds_write_b16 v130, v73 offset:17680
	v_fma_mixlo_f16 v73, v78, v84, v81
	ds_write_b16 v130, v72 offset:17712
	v_fma_mixlo_f16 v72, v75, v86, -v76
	ds_write_b16 v130, v74 offset:18208
	v_fma_mixlo_f16 v74, v79, v86, v77
	ds_write_b16 v130, v73 offset:18240
	ds_write_b16 v130, v72 offset:18736
	ds_write_b16 v130, v74 offset:18768
	v_or_b32_e32 v72, v131, v96
	v_lshlrev_b32_e32 v152, 3, v72
	v_or_b32_e32 v74, v112, v96
	v_lshl_add_u64 v[72:73], s[2:3], 0, v[152:153]
	v_lshlrev_b32_e32 v152, 3, v74
	v_or_b32_e32 v76, v113, v96
	v_lshl_add_u64 v[74:75], s[2:3], 0, v[152:153]
	v_lshlrev_b32_e32 v152, 3, v76
	v_or_b32_e32 v78, v114, v96
	s_waitcnt vmcnt(11)
	v_mov_b32_e32 v72, v218
	v_mov_b32_e32 v73, v219
	v_lshl_add_u64 v[76:77], s[2:3], 0, v[152:153]
	s_waitcnt vmcnt(10)
	v_mov_b32_e32 v74, v220
	v_mov_b32_e32 v75, v221
	v_lshlrev_b32_e32 v152, 3, v78
	s_waitcnt vmcnt(9)
	v_mov_b32_e32 v76, v222
	v_mov_b32_e32 v77, v223
	v_lshl_add_u64 v[78:79], s[2:3], 0, v[152:153]
	s_waitcnt vmcnt(8)
; #define FOR_R _Pragma("unroll") for (int r = 0; r < 4; ++r)
; #define FOR_AI _Pragma("unroll") for (int ai = 0; ai < 2; ++ai)
; #define FOR_BJ _Pragma("unroll") for (int bj = 0; bj < 2; ++bj)
; #define FOR_M4 _Pragma("unroll") for (int m = 0; m < 4; ++m)
; template <bool ISK>
; __device__ void job_qk_g(const P& p, int l, int g, int ct2, int rt, HALF* sm) {
;     ...
;   const float2* rope = (const float2*)(ws + OFF_ROPE);
;   FOR_AI FOR_BJ {
;     FOR_M4 {
;       const int row0 = ai * 128 + wr * 64 + m * 16 + fq * 4;
;       const int lc = bj * 128 + wc * 32 + fr;
;       const int j = (bj * 4 + wc) * 16 + fr;
;       f4 o1, o2;
;       FOR_R {
;         const int sp = (rt * 256 + row0 + r) & (S - 1);
;         const float2 cs = rope[sp * 128 + j];
;         const float a = acc[ai][bj][m][0][r], b = acc[ai][bj][m][1][r];
;         o1[r] = a * cs.x - b * cs.y;
;         o2[r] = a * cs.y + b * cs.x;
;       }
;       acc[ai][bj][m][0] = o1;
;       acc[ai][bj][m][1] = o2;
;       stage2_rm(sm, row0, lc, to_h4(o1));
;       stage2_rm(sm, row0, lc + 16, to_h4(o2));
;       __builtin_amdgcn_sched_barrier(0);
;     }
;   }
	v_mov_b32_e32 v78, v224
	v_mov_b32_e32 v79, v225
	v_mul_f32_e32 v80, v68, v73
	v_mul_f32_e32 v73, v64, v73
	v_mul_f32_e32 v81, v69, v75
	v_mul_f32_e32 v75, v65, v75
	v_fma_mixlo_f16 v64, v64, v72, -v80
	v_fma_mixlo_f16 v68, v68, v72, v73
	v_mul_f32_e32 v72, v70, v77
	v_mul_f32_e32 v73, v66, v77
	v_fma_mixlo_f16 v65, v65, v74, -v81
	ds_write_b16 v130, v64 offset:25600
	v_fma_mixlo_f16 v64, v69, v74, v75
	ds_write_b16 v130, v68 offset:25632
	v_mul_f32_e32 v68, v71, v79
	v_mul_f32_e32 v69, v67, v79
	v_fma_mixlo_f16 v66, v66, v76, -v72
	ds_write_b16 v130, v65 offset:26128
	v_fma_mixlo_f16 v65, v70, v76, v73
	ds_write_b16 v130, v64 offset:26160
	v_fma_mixlo_f16 v64, v67, v78, -v68
	ds_write_b16 v130, v66 offset:26656
	v_fma_mixlo_f16 v66, v71, v78, v69
	ds_write_b16 v130, v65 offset:26688
	ds_write_b16 v130, v64 offset:27184
	ds_write_b16 v130, v66 offset:27216
	v_add_u32_e32 v64, 0x80, v128
	v_and_b32_e32 v64, s22, v64
	v_add_u32_e32 v66, 0x81, v128
	v_lshlrev_b32_e32 v74, 7, v64
	v_and_b32_e32 v66, s22, v66
	v_or_b32_e32 v64, v74, v129
	v_lshlrev_b32_e32 v75, 7, v66
	v_lshlrev_b32_e32 v152, 3, v64
	v_or_b32_e32 v66, v75, v129
	v_lshl_add_u64 v[64:65], s[2:3], 0, v[152:153]
	v_lshlrev_b32_e32 v152, 3, v66
	v_lshl_add_u64 v[66:67], s[2:3], 0, v[152:153]
	v_add_u32_e32 v227, 0x28000, v226
	global_load_dwordx2 v[210:211], v227, s[2:3]
	global_load_dwordx2 v[212:213], v227, s[2:3] offset:1024
	global_load_dwordx2 v[214:215], v227, s[2:3] offset:2048
	global_load_dwordx2 v[216:217], v227, s[2:3] offset:3072
	v_add_u32_e32 v227, 0x2c000, v226
	global_load_dwordx2 v[218:219], v227, s[2:3]
	global_load_dwordx2 v[220:221], v227, s[2:3] offset:1024
	global_load_dwordx2 v[222:223], v227, s[2:3] offset:2048
	global_load_dwordx2 v[224:225], v227, s[2:3] offset:3072
	s_waitcnt vmcnt(15)
	v_mov_b32_e32 v68, v194
	v_mov_b32_e32 v69, v195
	s_nop 0
	s_waitcnt vmcnt(14)
	v_mov_b32_e32 v66, v196
	v_mov_b32_e32 v67, v197
	v_add_u32_e32 v64, 0x82, v128
	v_and_b32_e32 v64, s22, v64
	v_lshlrev_b32_e32 v76, 7, v64
	v_or_b32_e32 v64, v76, v129
	v_lshlrev_b32_e32 v152, 3, v64
	v_lshl_add_u64 v[64:65], s[2:3], 0, v[152:153]
	s_waitcnt vmcnt(13)
	v_mov_b32_e32 v70, v198
	v_mov_b32_e32 v71, v199
	v_add_u32_e32 v64, 0x83, v128
	v_and_b32_e32 v64, s22, v64
	v_lshlrev_b32_e32 v77, 7, v64
	v_or_b32_e32 v64, v77, v129
	v_lshlrev_b32_e32 v152, 3, v64
	v_lshl_add_u64 v[64:65], s[2:3], 0, v[152:153]
	s_waitcnt vmcnt(12)
	v_mov_b32_e32 v72, v200
	v_mov_b32_e32 v73, v201
	v_add_u32_e32 v65, 0xb0, v128
	v_add_u32_e32 v64, 0x10800, v130
	v_and_b32_e32 v65, s22, v65
	v_lshlrev_b32_e32 v65, 7, v65
	v_mul_f32_e32 v78, v60, v69
	v_mul_f32_e32 v69, v56, v69
	v_mul_f32_e32 v79, v61, v67
	v_mul_f32_e32 v67, v57, v67
	v_fma_mixlo_f16 v56, v56, v68, -v78
	v_fma_mixlo_f16 v60, v60, v68, v69
	v_fma_mixlo_f16 v57, v57, v66, -v79
	ds_write_b16 v64, v56
	v_mul_f32_e32 v68, v62, v71
	v_mul_f32_e32 v69, v58, v71
	v_fma_mixlo_f16 v56, v61, v66, v67
	ds_write_b16 v64, v60 offset:32
	v_fma_mixlo_f16 v58, v58, v70, -v68
	ds_write_b16 v64, v57 offset:528
	v_fma_mixlo_f16 v57, v62, v70, v69
	v_mul_f32_e32 v60, v63, v73
	v_mul_f32_e32 v61, v59, v73
	ds_write_b16 v64, v56 offset:560
	v_fma_mixlo_f16 v56, v59, v72, -v60
	ds_write_b16 v64, v58 offset:1056
	v_fma_mixlo_f16 v58, v63, v72, v61
	ds_write_b16 v64, v57 offset:1088
	ds_write_b16 v64, v56 offset:1584
	ds_write_b16 v64, v58 offset:1616
	v_add_u32_e32 v56, 0x90, v128
	v_and_b32_e32 v56, s22, v56
	v_add_u32_e32 v58, 0x91, v128
	v_lshlrev_b32_e32 v66, 7, v56
	v_and_b32_e32 v58, s22, v58
	v_add_u32_e32 v60, 0x92, v128
	v_or_b32_e32 v56, v66, v129
	v_lshlrev_b32_e32 v67, 7, v58
	v_and_b32_e32 v60, s22, v60
	v_add_u32_e32 v62, 0x93, v128
	v_lshlrev_b32_e32 v152, 3, v56
	v_or_b32_e32 v58, v67, v129
	v_lshlrev_b32_e32 v68, 7, v60
	v_and_b32_e32 v62, s22, v62
	v_lshl_add_u64 v[56:57], s[2:3], 0, v[152:153]
	v_lshlrev_b32_e32 v152, 3, v58
	v_or_b32_e32 v60, v68, v129
	v_lshlrev_b32_e32 v69, 7, v62
	v_lshl_add_u64 v[58:59], s[2:3], 0, v[152:153]
	v_lshlrev_b32_e32 v152, 3, v60
	v_or_b32_e32 v62, v69, v129
	s_waitcnt vmcnt(11)
	v_mov_b32_e32 v56, v202
	v_mov_b32_e32 v57, v203
	s_nop 0
	s_waitcnt vmcnt(10)
	v_mov_b32_e32 v58, v204
	v_mov_b32_e32 v59, v205
	v_lshl_add_u64 v[60:61], s[2:3], 0, v[152:153]
	v_lshlrev_b32_e32 v152, 3, v62
	s_waitcnt vmcnt(9)
	v_mov_b32_e32 v60, v206
	v_mov_b32_e32 v61, v207
	v_lshl_add_u64 v[62:63], s[2:3], 0, v[152:153]
	s_waitcnt vmcnt(8)
	v_mov_b32_e32 v62, v208
	v_mov_b32_e32 v63, v209
	v_mul_f32_e32 v70, v52, v57
	v_mul_f32_e32 v57, v48, v57
	v_mul_f32_e32 v71, v53, v59
	v_mul_f32_e32 v59, v49, v59
	v_fma_mixlo_f16 v48, v48, v56, -v70
	v_fma_mixlo_f16 v52, v52, v56, v57
	v_mul_f32_e32 v56, v54, v61
	v_mul_f32_e32 v57, v50, v61
	v_fma_mixlo_f16 v49, v49, v58, -v71
	ds_write_b16 v64, v48 offset:8448
	v_fma_mixlo_f16 v48, v53, v58, v59
	ds_write_b16 v64, v52 offset:8480
	v_mul_f32_e32 v52, v55, v63
	v_mul_f32_e32 v53, v51, v63
	v_fma_mixlo_f16 v50, v50, v60, -v56
	ds_write_b16 v64, v49 offset:8976
	v_fma_mixlo_f16 v49, v54, v60, v57
	ds_write_b16 v64, v48 offset:9008
	v_fma_mixlo_f16 v48, v51, v62, -v52
	ds_write_b16 v64, v50 offset:9504
	v_fma_mixlo_f16 v50, v55, v62, v53
	ds_write_b16 v64, v49 offset:9536
	ds_write_b16 v64, v48 offset:10032
	ds_write_b16 v64, v50 offset:10064
	v_add_u32_e32 v48, 0xa0, v128
	v_and_b32_e32 v48, s22, v48
	v_add_u32_e32 v50, 0xa1, v128
	v_lshlrev_b32_e32 v56, 7, v48
	v_and_b32_e32 v50, s22, v50
	v_add_u32_e32 v52, 0xa2, v128
	v_or_b32_e32 v48, v56, v129
	v_lshlrev_b32_e32 v57, 7, v50
	v_and_b32_e32 v52, s22, v52
	v_add_u32_e32 v54, 0xa3, v128
	v_lshlrev_b32_e32 v152, 3, v48
	v_or_b32_e32 v50, v57, v129
	v_lshlrev_b32_e32 v58, 7, v52
	v_and_b32_e32 v54, s22, v54
	v_lshl_add_u64 v[48:49], s[2:3], 0, v[152:153]
	v_lshlrev_b32_e32 v152, 3, v50
	v_or_b32_e32 v52, v58, v129
	v_lshlrev_b32_e32 v59, 7, v54
	v_lshl_add_u64 v[50:51], s[2:3], 0, v[152:153]
	v_lshlrev_b32_e32 v152, 3, v52
	v_or_b32_e32 v54, v59, v129
	v_add_u32_e32 v227, 0x20200, v226
	global_load_dwordx2 v[194:195], v227, s[2:3]
	global_load_dwordx2 v[196:197], v227, s[2:3] offset:1024
	global_load_dwordx2 v[198:199], v227, s[2:3] offset:2048
	global_load_dwordx2 v[200:201], v227, s[2:3] offset:3072
	v_add_u32_e32 v227, 0x24200, v226
	global_load_dwordx2 v[202:203], v227, s[2:3]
	global_load_dwordx2 v[204:205], v227, s[2:3] offset:1024
	global_load_dwordx2 v[206:207], v227, s[2:3] offset:2048
	global_load_dwordx2 v[208:209], v227, s[2:3] offset:3072
	s_waitcnt vmcnt(15)
; #define FOR_R _Pragma("unroll") for (int r = 0; r < 4; ++r)
; #define FOR_AI _Pragma("unroll") for (int ai = 0; ai < 2; ++ai)
; #define FOR_BJ _Pragma("unroll") for (int bj = 0; bj < 2; ++bj)
; #define FOR_M4 _Pragma("unroll") for (int m = 0; m < 4; ++m)
; template <bool ISK>
; __device__ void job_qk_g(const P& p, int l, int g, int ct2, int rt, HALF* sm) {
;     ...
;   const float2* rope = (const float2*)(ws + OFF_ROPE);
;   FOR_AI FOR_BJ {
;     FOR_M4 {
;       const int row0 = ai * 128 + wr * 64 + m * 16 + fq * 4;
;       const int lc = bj * 128 + wc * 32 + fr;
;       const int j = (bj * 4 + wc) * 16 + fr;
;       f4 o1, o2;
;       FOR_R {
;         const int sp = (rt * 256 + row0 + r) & (S - 1);
;         const float2 cs = rope[sp * 128 + j];
;         const float a = acc[ai][bj][m][0][r], b = acc[ai][bj][m][1][r];
;         o1[r] = a * cs.x - b * cs.y;
;         o2[r] = a * cs.y + b * cs.x;
;       }
;       acc[ai][bj][m][0] = o1;
;       acc[ai][bj][m][1] = o2;
;       stage2_rm(sm, row0, lc, to_h4(o1));
;       stage2_rm(sm, row0, lc + 16, to_h4(o2));
;       __builtin_amdgcn_sched_barrier(0);
;     }
;   }
	v_mov_b32_e32 v48, v210
	v_mov_b32_e32 v49, v211
	s_nop 0
	s_waitcnt vmcnt(14)
	v_mov_b32_e32 v50, v212
	v_mov_b32_e32 v51, v213
	v_lshl_add_u64 v[52:53], s[2:3], 0, v[152:153]
	v_lshlrev_b32_e32 v152, 3, v54
	s_waitcnt vmcnt(13)
	v_mov_b32_e32 v52, v214
	v_mov_b32_e32 v53, v215
	v_lshl_add_u64 v[54:55], s[2:3], 0, v[152:153]
	s_waitcnt vmcnt(12)
	v_mov_b32_e32 v54, v216
	v_mov_b32_e32 v55, v217
	v_mul_f32_e32 v60, v44, v49
	v_mul_f32_e32 v49, v40, v49
	v_mul_f32_e32 v61, v45, v51
	v_mul_f32_e32 v51, v41, v51
	v_fma_mixlo_f16 v40, v40, v48, -v60
	v_fma_mixlo_f16 v44, v44, v48, v49
	v_mul_f32_e32 v48, v46, v53
	v_mul_f32_e32 v49, v42, v53
	v_fma_mixlo_f16 v41, v41, v50, -v61
	ds_write_b16 v64, v40 offset:16896
	v_fma_mixlo_f16 v40, v45, v50, v51
	ds_write_b16 v64, v44 offset:16928
	v_mul_f32_e32 v44, v47, v55
	v_mul_f32_e32 v45, v43, v55
	v_fma_mixlo_f16 v42, v42, v52, -v48
	ds_write_b16 v64, v41 offset:17424
	v_fma_mixlo_f16 v41, v46, v52, v49
	ds_write_b16 v64, v40 offset:17456
	v_fma_mixlo_f16 v40, v43, v54, -v44
	ds_write_b16 v64, v42 offset:17952
	v_fma_mixlo_f16 v42, v47, v54, v45
	ds_write_b16 v64, v41 offset:17984
	ds_write_b16 v64, v40 offset:18480
	ds_write_b16 v64, v42 offset:18512
	v_add_u32_e32 v42, 0xb1, v128
	v_or_b32_e32 v40, v65, v129
	v_and_b32_e32 v42, s22, v42
	v_add_u32_e32 v44, 0xb2, v128
	v_lshlrev_b32_e32 v152, 3, v40
	v_lshlrev_b32_e32 v48, 7, v42
	v_and_b32_e32 v44, s22, v44
	v_add_u32_e32 v46, 0xb3, v128
	v_lshl_add_u64 v[40:41], s[2:3], 0, v[152:153]
	v_or_b32_e32 v42, v48, v129
	v_lshlrev_b32_e32 v49, 7, v44
	v_and_b32_e32 v46, s22, v46
	s_waitcnt vmcnt(11)
	v_mov_b32_e32 v40, v218
	v_mov_b32_e32 v41, v219
	v_lshlrev_b32_e32 v152, 3, v42
	v_or_b32_e32 v44, v49, v129
	v_lshlrev_b32_e32 v50, 7, v46
	v_lshl_add_u64 v[42:43], s[2:3], 0, v[152:153]
	v_lshlrev_b32_e32 v152, 3, v44
	v_or_b32_e32 v46, v50, v129
	v_lshl_add_u64 v[44:45], s[2:3], 0, v[152:153]
	v_lshlrev_b32_e32 v152, 3, v46
	s_waitcnt vmcnt(10)
	v_mov_b32_e32 v42, v220
	v_mov_b32_e32 v43, v221
	s_nop 0
	s_waitcnt vmcnt(9)
	v_mov_b32_e32 v44, v222
	v_mov_b32_e32 v45, v223
	v_lshl_add_u64 v[46:47], s[2:3], 0, v[152:153]
	s_waitcnt vmcnt(8)
	v_mov_b32_e32 v46, v224
	v_mov_b32_e32 v47, v225
	v_mul_f32_e32 v51, v36, v41
	v_mul_f32_e32 v41, v32, v41
	v_fma_mixlo_f16 v32, v32, v40, -v51
	v_fma_mixlo_f16 v36, v36, v40, v41
	ds_write_b16 v64, v32 offset:25344
	ds_write_b16 v64, v36 offset:25376
	v_mul_f32_e32 v32, v37, v43
	v_mul_f32_e32 v36, v33, v43
	v_mul_f32_e32 v40, v38, v45
	v_mul_f32_e32 v41, v34, v45
	v_fma_mixlo_f16 v32, v33, v42, -v32
	v_fma_mixlo_f16 v33, v37, v42, v36
	v_mul_f32_e32 v36, v39, v47
	v_mul_f32_e32 v37, v35, v47
	v_fma_mixlo_f16 v34, v34, v44, -v40
	ds_write_b16 v64, v32 offset:25872
	v_fma_mixlo_f16 v32, v38, v44, v41
	ds_write_b16 v64, v33 offset:25904
	v_fma_mixlo_f16 v33, v35, v46, -v36
	ds_write_b16 v64, v34 offset:26400
	v_fma_mixlo_f16 v34, v39, v46, v37
	ds_write_b16 v64, v32 offset:26432
	ds_write_b16 v64, v33 offset:26928
	ds_write_b16 v64, v34 offset:26960
	v_or_b32_e32 v32, v74, v96
	v_lshlrev_b32_e32 v152, 3, v32
	v_or_b32_e32 v34, v75, v96
	v_lshl_add_u64 v[32:33], s[2:3], 0, v[152:153]
	v_lshlrev_b32_e32 v152, 3, v34
	v_or_b32_e32 v36, v76, v96
	v_lshl_add_u64 v[34:35], s[2:3], 0, v[152:153]
	v_lshlrev_b32_e32 v152, 3, v36
	v_or_b32_e32 v38, v77, v96
	v_add_u32_e32 v227, 0x28200, v226
	global_load_dwordx2 v[210:211], v227, s[2:3]
	global_load_dwordx2 v[212:213], v227, s[2:3] offset:1024
	global_load_dwordx2 v[214:215], v227, s[2:3] offset:2048
	global_load_dwordx2 v[216:217], v227, s[2:3] offset:3072
	v_add_u32_e32 v227, 0x2c200, v226
	global_load_dwordx2 v[218:219], v227, s[2:3]
	global_load_dwordx2 v[220:221], v227, s[2:3] offset:1024
	global_load_dwordx2 v[222:223], v227, s[2:3] offset:2048
	global_load_dwordx2 v[224:225], v227, s[2:3] offset:3072
	s_waitcnt vmcnt(15)
	v_mov_b32_e32 v32, v194
	v_mov_b32_e32 v33, v195
	v_lshl_add_u64 v[36:37], s[2:3], 0, v[152:153]
	s_waitcnt vmcnt(14)
	v_mov_b32_e32 v34, v196
	v_mov_b32_e32 v35, v197
	v_lshlrev_b32_e32 v152, 3, v38
	s_waitcnt vmcnt(13)
	v_mov_b32_e32 v36, v198
	v_mov_b32_e32 v37, v199
	v_lshl_add_u64 v[38:39], s[2:3], 0, v[152:153]
	s_waitcnt vmcnt(12)
	v_mov_b32_e32 v38, v200
	v_mov_b32_e32 v39, v201
	v_mul_f32_e32 v40, v28, v33
	v_mul_f32_e32 v33, v24, v33
	v_mul_f32_e32 v41, v29, v35
	v_mul_f32_e32 v35, v25, v35
	v_fma_mixlo_f16 v24, v24, v32, -v40
	v_fma_mixlo_f16 v28, v28, v32, v33
	v_mul_f32_e32 v32, v30, v37
	v_mul_f32_e32 v33, v26, v37
	v_fma_mixlo_f16 v25, v25, v34, -v41
	ds_write_b16 v64, v24 offset:256
	v_fma_mixlo_f16 v24, v29, v34, v35
	ds_write_b16 v64, v28 offset:288
	v_mul_f32_e32 v28, v31, v39
	v_mul_f32_e32 v29, v27, v39
	v_fma_mixlo_f16 v26, v26, v36, -v32
	ds_write_b16 v64, v25 offset:784
	v_fma_mixlo_f16 v25, v30, v36, v33
	ds_write_b16 v64, v24 offset:816
	v_fma_mixlo_f16 v24, v27, v38, -v28
	ds_write_b16 v64, v26 offset:1312
	v_fma_mixlo_f16 v26, v31, v38, v29
	ds_write_b16 v64, v25 offset:1344
	ds_write_b16 v64, v24 offset:1840
	ds_write_b16 v64, v26 offset:1872
	v_or_b32_e32 v24, v66, v96
	v_lshlrev_b32_e32 v152, 3, v24
	v_or_b32_e32 v26, v67, v96
	v_lshl_add_u64 v[24:25], s[2:3], 0, v[152:153]
	v_lshlrev_b32_e32 v152, 3, v26
	v_or_b32_e32 v28, v68, v96
	v_lshl_add_u64 v[26:27], s[2:3], 0, v[152:153]
	v_lshlrev_b32_e32 v152, 3, v28
	v_or_b32_e32 v30, v69, v96
	s_waitcnt vmcnt(11)
; DEV int opaque_tid512() { int t = threadIdx.x; asm volatile("" : "+v"(t)); return t; }
; #define FOR_R _Pragma("unroll") for (int r = 0; r < 4; ++r)
; #define FOR_AI _Pragma("unroll") for (int ai = 0; ai < 2; ++ai)
; #define FOR_BJ _Pragma("unroll") for (int bj = 0; bj < 2; ++bj)
; #define FOR_M4 _Pragma("unroll") for (int m = 0; m < 4; ++m)
; template <int CPR, class F>
; DEV void flush2(HALF* S, int NR, F fn) {
; #pragma unroll 4
;   for (int id = opaque_tid512(); id < NR * CPR; id += 512) {
;     const int row = id / CPR, ch = id % CPR;
;     const u4 v = *(const u4*)(S + row * SST2 + ch * 8);
;     __builtin_nontemporal_store(v, (u4*)(fn(row, ch)));
;   }
; template <bool ISK>
; __device__ void job_qk_g(const P& p, int l, int g, int ct2, int rt, HALF* sm) {
;     ...
;   const float2* rope = (const float2*)(ws + OFF_ROPE);
;   FOR_AI FOR_BJ {
;     FOR_M4 {
;       const int row0 = ai * 128 + wr * 64 + m * 16 + fq * 4;
;       const int lc = bj * 128 + wc * 32 + fr;
;       const int j = (bj * 4 + wc) * 16 + fr;
;       f4 o1, o2;
;       FOR_R {
;         const int sp = (rt * 256 + row0 + r) & (S - 1);
;         const float2 cs = rope[sp * 128 + j];
;         const float a = acc[ai][bj][m][0][r], b = acc[ai][bj][m][1][r];
;         o1[r] = a * cs.x - b * cs.y;
;         o2[r] = a * cs.y + b * cs.x;
;       }
;       acc[ai][bj][m][0] = o1;
;       acc[ai][bj][m][1] = o2;
;       stage2_rm(sm, row0, lc, to_h4(o1));
;       stage2_rm(sm, row0, lc + 16, to_h4(o2));
;       __builtin_amdgcn_sched_barrier(0);
;     }
;   }
;   __syncthreads();
;   HALF* dst = (HALF*)(ws + (ISK ? G_K : G_Q));
;   flush2<32>(sm, 256, [&](int row, int ch) { return dst + (size_t)(rt * 256 + row) * 1024 + hh * 256 + ch * 8; });
	v_mov_b32_e32 v24, v202
	v_mov_b32_e32 v25, v203
	v_lshl_add_u64 v[28:29], s[2:3], 0, v[152:153]
	s_waitcnt vmcnt(10)
	v_mov_b32_e32 v26, v204
	v_mov_b32_e32 v27, v205
	v_lshlrev_b32_e32 v152, 3, v30
	s_waitcnt vmcnt(9)
	v_mov_b32_e32 v28, v206
	v_mov_b32_e32 v29, v207
	v_lshl_add_u64 v[30:31], s[2:3], 0, v[152:153]
	s_waitcnt vmcnt(8)
	v_mov_b32_e32 v30, v208
	v_mov_b32_e32 v31, v209
	v_mul_f32_e32 v32, v20, v25
	v_mul_f32_e32 v25, v16, v25
	v_mul_f32_e32 v33, v21, v27
	v_mul_f32_e32 v27, v17, v27
	v_fma_mixlo_f16 v16, v16, v24, -v32
	v_fma_mixlo_f16 v20, v20, v24, v25
	v_mul_f32_e32 v24, v22, v29
	v_mul_f32_e32 v25, v18, v29
	v_fma_mixlo_f16 v17, v17, v26, -v33
	ds_write_b16 v64, v16 offset:8704
	v_fma_mixlo_f16 v16, v21, v26, v27
	ds_write_b16 v64, v20 offset:8736
	v_mul_f32_e32 v20, v23, v31
	v_mul_f32_e32 v21, v19, v31
	v_fma_mixlo_f16 v18, v18, v28, -v24
	ds_write_b16 v64, v17 offset:9232
	v_fma_mixlo_f16 v17, v22, v28, v25
	ds_write_b16 v64, v16 offset:9264
	v_fma_mixlo_f16 v16, v19, v30, -v20
	ds_write_b16 v64, v18 offset:9760
	v_fma_mixlo_f16 v18, v23, v30, v21
	ds_write_b16 v64, v17 offset:9792
	ds_write_b16 v64, v16 offset:10288
	ds_write_b16 v64, v18 offset:10320
	v_or_b32_e32 v16, v56, v96
	v_lshlrev_b32_e32 v152, 3, v16
	v_or_b32_e32 v18, v57, v96
	v_lshl_add_u64 v[16:17], s[2:3], 0, v[152:153]
	v_lshlrev_b32_e32 v152, 3, v18
	v_or_b32_e32 v20, v58, v96
	v_lshl_add_u64 v[18:19], s[2:3], 0, v[152:153]
	v_lshlrev_b32_e32 v152, 3, v20
	v_or_b32_e32 v22, v59, v96
	v_lshl_add_u64 v[20:21], s[2:3], 0, v[152:153]
	v_lshlrev_b32_e32 v152, 3, v22
	s_waitcnt vmcnt(7)
	v_mov_b32_e32 v16, v210
	v_mov_b32_e32 v17, v211
	v_lshl_add_u64 v[22:23], s[2:3], 0, v[152:153]
	s_waitcnt vmcnt(6)
	v_mov_b32_e32 v18, v212
	v_mov_b32_e32 v19, v213
	s_nop 0
	s_waitcnt vmcnt(5)
	v_mov_b32_e32 v20, v214
	v_mov_b32_e32 v21, v215
	s_nop 0
	s_waitcnt vmcnt(4)
	v_mov_b32_e32 v22, v216
	v_mov_b32_e32 v23, v217
	v_mul_f32_e32 v24, v8, v17
	v_mul_f32_e32 v17, v12, v17
	v_mul_f32_e32 v25, v9, v19
	v_mul_f32_e32 v19, v13, v19
	v_mul_f32_e32 v26, v10, v21
	v_mul_f32_e32 v21, v14, v21
	v_mul_f32_e32 v27, v11, v23
	v_mul_f32_e32 v23, v15, v23
	v_fma_mixlo_f16 v12, v12, v16, -v24
	v_fma_mixlo_f16 v8, v8, v16, v17
	v_fma_mixlo_f16 v13, v13, v18, -v25
	v_fma_mixlo_f16 v14, v14, v20, -v26
	v_fma_mixlo_f16 v15, v15, v22, -v27
	ds_write_b16 v64, v12 offset:17152
	ds_write_b16 v64, v13 offset:17680
	ds_write_b16 v64, v14 offset:18208
	ds_write_b16 v64, v15 offset:18736
	v_fma_mixlo_f16 v9, v9, v18, v19
	v_fma_mixlo_f16 v10, v10, v20, v21
	v_fma_mixlo_f16 v11, v11, v22, v23
	ds_write_b16 v64, v8 offset:17184
	ds_write_b16 v64, v9 offset:17712
	ds_write_b16 v64, v10 offset:18240
	ds_write_b16 v64, v11 offset:18768
	v_or_b32_e32 v8, v65, v96
	v_lshlrev_b32_e32 v152, 3, v8
	v_or_b32_e32 v10, v48, v96
	v_lshl_add_u64 v[8:9], s[2:3], 0, v[152:153]
	v_lshlrev_b32_e32 v152, 3, v10
	v_or_b32_e32 v12, v49, v96
	v_lshl_add_u64 v[10:11], s[2:3], 0, v[152:153]
	v_lshlrev_b32_e32 v152, 3, v12
	v_or_b32_e32 v14, v50, v96
	v_lshl_add_u64 v[12:13], s[2:3], 0, v[152:153]
	v_lshlrev_b32_e32 v152, 3, v14
	s_waitcnt vmcnt(3)
	v_mov_b32_e32 v8, v218
	v_mov_b32_e32 v9, v219
	v_lshl_add_u64 v[14:15], s[2:3], 0, v[152:153]
	s_waitcnt vmcnt(2)
	v_mov_b32_e32 v10, v220
	v_mov_b32_e32 v11, v221
	s_nop 0
	s_waitcnt vmcnt(1)
	v_mov_b32_e32 v12, v222
	v_mov_b32_e32 v13, v223
	s_nop 0
	s_waitcnt vmcnt(0)
	v_mov_b32_e32 v14, v224
	v_mov_b32_e32 v15, v225
	v_mul_f32_e32 v16, v0, v9
	v_mul_f32_e32 v9, v4, v9
	v_mul_f32_e32 v17, v1, v11
	v_mul_f32_e32 v11, v5, v11
	v_mul_f32_e32 v18, v2, v13
	v_mul_f32_e32 v13, v6, v13
	v_mul_f32_e32 v19, v3, v15
	v_mul_f32_e32 v15, v7, v15
	v_fma_mixlo_f16 v4, v4, v8, -v16
	v_fma_mixlo_f16 v0, v0, v8, v9
	v_fma_mixlo_f16 v5, v5, v10, -v17
	v_fma_mixlo_f16 v6, v6, v12, -v18
	v_fma_mixlo_f16 v7, v7, v14, -v19
	ds_write_b16 v64, v4 offset:25600
	ds_write_b16 v64, v5 offset:26128
	ds_write_b16 v64, v6 offset:26656
	ds_write_b16 v64, v7 offset:27184
	v_fma_mixlo_f16 v1, v1, v10, v11
	v_fma_mixlo_f16 v2, v2, v12, v13
	v_fma_mixlo_f16 v3, v3, v14, v15
	ds_write_b16 v64, v0 offset:25632
	ds_write_b16 v64, v1 offset:26160
	ds_write_b16 v64, v2 offset:26688
	ds_write_b16 v64, v3 offset:27216
	v_mov_b32_e32 v0, v155
	s_movk_i32 s2, 0x2000
	s_waitcnt lgkmcnt(0)
	s_barrier
	s_nop 0
	v_cmp_gt_i32_e32 vcc, s2, v0
	s_and_saveexec_b64 s[2:3], vcc
	s_cbranch_execz .LBB0_204
	s_lshl_b32 s6, s8, 9
	s_and_b32 s6, s6, 0x600
	v_max_i32_e32 v1, 0x1e00, v0
	s_add_u32 s0, s0, s6
	v_sub_u32_e32 v1, v1, v0
	s_addc_u32 s1, s1, 0
	v_add_u32_e32 v1, 0x1ff, v1
	s_add_u32 s0, s0, 0x19eb0000
	v_and_b32_e32 v2, 0x600, v1
	s_movk_i32 s6, 0x600
	s_addc_u32 s1, s1, 0
	v_cmp_ne_u32_e32 vcc, s6, v2
	s_and_saveexec_b64 s[6:7], vcc
	s_cbranch_execz .LBB0_201
	v_lshrrev_b32_e32 v2, 9, v1
	v_add_u32_e32 v2, 1, v2
	v_and_b32_e32 v4, 3, v2
	v_lshl_add_u32 v2, v0, 4, 0
	v_lshlrev_b32_e32 v3, 3, v0
	v_sub_u32_e32 v4, 0, v4
	s_mov_b64 s[12:13], 0

; #define FOR_R _Pragma("unroll") for (int r = 0; r < 4; ++r)
; #define FOR_AI _Pragma("unroll") for (int ai = 0; ai < 2; ++ai)
; #define FOR_BJ _Pragma("unroll") for (int bj = 0; bj < 2; ++bj)
; #define FOR_M4 _Pragma("unroll") for (int m = 0; m < 4; ++m)
; template <bool ISK>
; __device__ void job_qk_g(const P& p, int l, int g, int ct2, int rt, HALF* sm) {
;     ...
;   const float2* rope = (const float2*)(ws + OFF_ROPE);
;   FOR_AI FOR_BJ {
;     FOR_M4 {
;       const int row0 = ai * 128 + wr * 64 + m * 16 + fq * 4;
;       const int lc = bj * 128 + wc * 32 + fr;
;       const int j = (bj * 4 + wc) * 16 + fr;
;       f4 o1, o2;
;       FOR_R {
;         const int sp = (rt * 256 + row0 + r) & (S - 1);
;         const float2 cs = rope[sp * 128 + j];
;         const float a = acc[ai][bj][m][0][r], b = acc[ai][bj][m][1][r];
;         o1[r] = a * cs.x - b * cs.y;
;         o2[r] = a * cs.y + b * cs.x;
;       }
;       acc[ai][bj][m][0] = o1;
;       acc[ai][bj][m][1] = o2;
;       stage2_rm(sm, row0, lc, to_h4(o1));
;       stage2_rm(sm, row0, lc + 16, to_h4(o2));
;       __builtin_amdgcn_sched_barrier(0);
;     }
;   }
.LBB0_212:
	s_or_b64 exec, exec, s[2:3]
	v_bfe_u32 v128, v130, 6, 2
	v_and_b32_e32 v129, 15, v130
	v_ashrrev_i32_e32 v131, 2, v130
	v_lshrrev_b32_e32 v130, 2, v130
	v_and_b32_e32 v130, 12, v130
	s_movk_i32 s6, 0xffc0
	v_and_or_b32 v133, v131, s6, v130
	v_or_b32_e32 v132, 48, v133
	v_add_u32_e32 v142, s21, v132
	v_add_u32_e32 v139, s21, v133
	v_and_b32_e32 v130, s22, v142
	v_lshl_or_b32 v134, v128, 5, v129
	v_lshl_or_b32 v141, v128, 4, v129
	v_and_b32_e32 v128, s22, v139
	s_and_b32 s44, s8, 3
	v_lshlrev_b32_e32 v135, 7, v130
	v_lshlrev_b32_e32 v138, 7, v128
	v_bitop3_b32 v130, v139, s22, 1 bitop3:0xc8
	s_add_u32 s2, s0, 0x3680000
	v_or_b32_e32 v128, v138, v141
	v_lshlrev_b32_e32 v140, 7, v130
	s_addc_u32 s3, s1, 0
	v_lshlrev_b32_e32 v152, 3, v128
	v_or_b32_e32 v130, v140, v141
	v_lshl_add_u64 v[128:129], s[2:3], 0, v[152:153]
	v_lshlrev_b32_e32 v152, 3, v130
	s_waitcnt vmcnt(0)
	s_barrier
	v_lshl_add_u64 v[130:131], s[2:3], 0, v[152:153]
	v_lshrrev_b32_e32 v226, 8, v155
	v_lshlrev_b32_e32 v226, 6, v226
	v_bfe_u32 v227, v155, 4, 2
	v_lshl_or_b32 v226, v227, 2, v226
	v_add_u32_e32 v226, s21, v226
	v_and_b32_e32 v226, s22, v226
	v_bfe_u32 v227, v155, 6, 2
	v_lshlrev_b32_e32 v227, 4, v227
	v_and_or_b32 v227, v155, 15, v227
	v_lshl_or_b32 v226, v226, 7, v227
	v_lshlrev_b32_e32 v226, 3, v226
	v_mov_b32_e32 v227, v226
	global_load_dwordx2 v[194:195], v227, s[2:3]
	global_load_dwordx2 v[196:197], v227, s[2:3] offset:1024
	global_load_dwordx2 v[198:199], v227, s[2:3] offset:2048
	global_load_dwordx2 v[200:201], v227, s[2:3] offset:3072
	v_add_u32_e32 v227, 0x4000, v226
	global_load_dwordx2 v[202:203], v227, s[2:3]
	global_load_dwordx2 v[204:205], v227, s[2:3] offset:1024
	global_load_dwordx2 v[206:207], v227, s[2:3] offset:2048
	global_load_dwordx2 v[208:209], v227, s[2:3] offset:3072
	v_add_u32_e32 v227, 0x8000, v226
	global_load_dwordx2 v[210:211], v227, s[2:3]
	global_load_dwordx2 v[212:213], v227, s[2:3] offset:1024
	global_load_dwordx2 v[214:215], v227, s[2:3] offset:2048
	global_load_dwordx2 v[216:217], v227, s[2:3] offset:3072
	v_add_u32_e32 v227, 0xc000, v226
	global_load_dwordx2 v[218:219], v227, s[2:3]
	global_load_dwordx2 v[220:221], v227, s[2:3] offset:1024
	global_load_dwordx2 v[222:223], v227, s[2:3] offset:2048
	global_load_dwordx2 v[224:225], v227, s[2:3] offset:3072
	s_waitcnt vmcnt(15)
	v_mov_b32_e32 v136, v194
	v_mov_b32_e32 v137, v195
	s_nop 0
	s_waitcnt vmcnt(14)
	v_mov_b32_e32 v128, v196
	v_mov_b32_e32 v129, v197
	v_mov_b32_e32 v130, v137
	v_mov_b32_e32 v131, v129
	v_pk_mul_f32 v[144:145], v[120:121], v[130:131]
	v_mov_b32_e32 v137, v128
	v_pk_fma_f32 v[128:129], v[124:125], v[136:137], v[144:145]
	v_pk_mul_f32 v[124:125], v[124:125], v[130:131]
	v_bitop3_b32 v130, v139, s22, 3 bitop3:0xc8
	v_pk_fma_f32 v[120:121], v[120:121], v[136:137], v[124:125] neg_lo:[0,0,1] neg_hi:[0,0,1]
	v_bitop3_b32 v124, v139, s22, 2 bitop3:0xc8
	v_lshlrev_b32_e32 v143, 7, v124
	v_or_b32_e32 v124, v143, v141
	v_lshlrev_b32_e32 v144, 7, v130
	v_lshlrev_b32_e32 v152, 3, v124
	v_or_b32_e32 v130, v144, v141
	v_lshl_add_u64 v[124:125], s[2:3], 0, v[152:153]
	v_lshlrev_b32_e32 v152, 3, v130
	v_lshl_add_u64 v[130:131], s[2:3], 0, v[152:153]
	s_waitcnt vmcnt(13)
	v_mov_b32_e32 v136, v198
	v_mov_b32_e32 v137, v199
	s_nop 0
	s_waitcnt vmcnt(12)
	v_mov_b32_e32 v124, v200
	v_mov_b32_e32 v125, v201
	v_mov_b32_e32 v130, v137
	v_mov_b32_e32 v131, v125
	v_pk_mul_f32 v[146:147], v[122:123], v[130:131]
	v_mov_b32_e32 v137, v124
	v_pk_fma_f32 v[124:125], v[126:127], v[136:137], v[146:147]
	v_pk_mul_f32 v[126:127], v[126:127], v[130:131]
	s_nop 0
	v_pk_fma_f32 v[126:127], v[122:123], v[136:137], v[126:127] neg_lo:[0,0,1] neg_hi:[0,0,1]
	v_cvt_f16_f32_e32 v122, v120
	v_cvt_f16_f32_e32 v123, v121
	v_cvt_f16_f32_e32 v130, v126
	v_mul_lo_u32 v136, v133, s64
	v_lshlrev_b32_e32 v137, 1, v134
	v_cvt_f16_f32_e32 v131, v127
	v_add3_u32 v139, 0, v136, v137
	ds_write_b16 v139, v122
	ds_write_b16 v139, v123 offset:528
	ds_write_b16 v139, v130 offset:1056
	ds_write_b16 v139, v131 offset:1584
	v_cvt_f16_f32_e32 v122, v128
	v_cvt_f16_f32_e32 v123, v129
	v_cvt_f16_f32_e32 v130, v124
	v_cvt_f16_f32_e32 v131, v125
	ds_write_b16 v139, v122 offset:32
	ds_write_b16 v139, v123 offset:560
	ds_write_b16 v139, v130 offset:1088
	ds_write_b16 v139, v131 offset:1616
	v_or_b32_e32 v137, 16, v133
	v_add_u32_e32 v136, s21, v137
	v_and_b32_e32 v122, s22, v136
	v_lshlrev_b32_e32 v145, 7, v122
	v_bitop3_b32 v130, v136, s22, 1 bitop3:0xc8
	v_or_b32_e32 v122, v145, v141
	v_lshlrev_b32_e32 v146, 7, v130
	v_lshlrev_b32_e32 v152, 3, v122
	v_or_b32_e32 v130, v146, v141
	v_lshl_add_u64 v[122:123], s[2:3], 0, v[152:153]
	v_lshlrev_b32_e32 v152, 3, v130
	v_lshl_add_u64 v[130:131], s[2:3], 0, v[152:153]
	s_waitcnt vmcnt(11)
	v_mov_b32_e32 v148, v202
	v_mov_b32_e32 v149, v203
	s_nop 0
	s_waitcnt vmcnt(10)
	v_mov_b32_e32 v122, v204
	v_mov_b32_e32 v123, v205
	v_mov_b32_e32 v130, v149
	v_mov_b32_e32 v131, v123
	v_pk_mul_f32 v[150:151], v[112:113], v[130:131]
	v_mov_b32_e32 v149, v122
	v_pk_fma_f32 v[122:123], v[116:117], v[148:149], v[150:151]
	v_pk_mul_f32 v[116:117], v[116:117], v[130:131]
	v_bitop3_b32 v130, v136, s22, 3 bitop3:0xc8
	v_pk_fma_f32 v[116:117], v[112:113], v[148:149], v[116:117] neg_lo:[0,0,1] neg_hi:[0,0,1]
	v_bitop3_b32 v112, v136, s22, 2 bitop3:0xc8
	v_lshlrev_b32_e32 v147, 7, v112
	v_or_b32_e32 v112, v147, v141
	v_lshlrev_b32_e32 v148, 7, v130
	v_lshlrev_b32_e32 v152, 3, v112
	v_or_b32_e32 v130, v148, v141
	v_lshl_add_u64 v[112:113], s[2:3], 0, v[152:153]
	v_lshlrev_b32_e32 v152, 3, v130
	v_lshl_add_u64 v[130:131], s[2:3], 0, v[152:153]
	s_waitcnt vmcnt(9)
; #define FOR_R _Pragma("unroll") for (int r = 0; r < 4; ++r)
; #define FOR_AI _Pragma("unroll") for (int ai = 0; ai < 2; ++ai)
; #define FOR_BJ _Pragma("unroll") for (int bj = 0; bj < 2; ++bj)
; #define FOR_M4 _Pragma("unroll") for (int m = 0; m < 4; ++m)
; template <bool ISK>
; __device__ void job_qk_g(const P& p, int l, int g, int ct2, int rt, HALF* sm) {
;     ...
;   const float2* rope = (const float2*)(ws + OFF_ROPE);
;   FOR_AI FOR_BJ {
;     FOR_M4 {
;       const int row0 = ai * 128 + wr * 64 + m * 16 + fq * 4;
;       const int lc = bj * 128 + wc * 32 + fr;
;       const int j = (bj * 4 + wc) * 16 + fr;
;       f4 o1, o2;
;       FOR_R {
;         const int sp = (rt * 256 + row0 + r) & (S - 1);
;         const float2 cs = rope[sp * 128 + j];
;         const float a = acc[ai][bj][m][0][r], b = acc[ai][bj][m][1][r];
;         o1[r] = a * cs.x - b * cs.y;
;         o2[r] = a * cs.y + b * cs.x;
;       }
;       acc[ai][bj][m][0] = o1;
;       acc[ai][bj][m][1] = o2;
;       stage2_rm(sm, row0, lc, to_h4(o1));
;       stage2_rm(sm, row0, lc + 16, to_h4(o2));
;       __builtin_amdgcn_sched_barrier(0);
;     }
;   }
	v_mov_b32_e32 v112, v206
	v_mov_b32_e32 v113, v207
	s_nop 0
	s_waitcnt vmcnt(8)
	v_mov_b32_e32 v130, v208
	v_mov_b32_e32 v131, v209
	v_mov_b32_e32 v150, v113
	v_mov_b32_e32 v151, v131
	v_pk_mul_f32 v[158:159], v[114:115], v[150:151]
	v_mov_b32_e32 v113, v130
	v_pk_fma_f32 v[130:131], v[118:119], v[112:113], v[158:159]
	v_pk_mul_f32 v[118:119], v[118:119], v[150:151]
	s_nop 0
	v_pk_fma_f32 v[118:119], v[114:115], v[112:113], v[118:119] neg_lo:[0,0,1] neg_hi:[0,0,1]
	v_cvt_f16_f32_e32 v112, v116
	v_cvt_f16_f32_e32 v113, v117
	v_cvt_f16_f32_e32 v114, v118
	v_cvt_f16_f32_e32 v115, v119
	ds_write_b16 v139, v112 offset:8448
	ds_write_b16 v139, v113 offset:8976
	ds_write_b16 v139, v114 offset:9504
	ds_write_b16 v139, v115 offset:10032
	v_cvt_f16_f32_e32 v112, v122
	v_cvt_f16_f32_e32 v113, v123
	v_cvt_f16_f32_e32 v114, v130
	v_cvt_f16_f32_e32 v115, v131
	ds_write_b16 v139, v112 offset:8480
	ds_write_b16 v139, v113 offset:9008
	ds_write_b16 v139, v114 offset:9536
	ds_write_b16 v139, v115 offset:10064
	v_or_b32_e32 v136, 32, v133
	v_add_u32_e32 v157, s21, v136
	v_and_b32_e32 v112, s22, v157
	v_lshlrev_b32_e32 v149, 7, v112
	v_bitop3_b32 v114, v157, s22, 1 bitop3:0xc8
	v_or_b32_e32 v112, v149, v141
	v_lshlrev_b32_e32 v150, 7, v114
	v_lshlrev_b32_e32 v152, 3, v112
	v_or_b32_e32 v114, v150, v141
	v_lshl_add_u64 v[112:113], s[2:3], 0, v[152:153]
	v_lshlrev_b32_e32 v152, 3, v114
	v_lshl_add_u64 v[114:115], s[2:3], 0, v[152:153]
	v_add_u32_e32 v227, 0x200, v226
	global_load_dwordx2 v[194:195], v227, s[2:3]
	global_load_dwordx2 v[196:197], v227, s[2:3] offset:1024
	global_load_dwordx2 v[198:199], v227, s[2:3] offset:2048
	global_load_dwordx2 v[200:201], v227, s[2:3] offset:3072
	v_add_u32_e32 v227, 0x4200, v226
	global_load_dwordx2 v[202:203], v227, s[2:3]
	global_load_dwordx2 v[204:205], v227, s[2:3] offset:1024
	global_load_dwordx2 v[206:207], v227, s[2:3] offset:2048
	global_load_dwordx2 v[208:209], v227, s[2:3] offset:3072
	s_waitcnt vmcnt(15)
	v_mov_b32_e32 v158, v210
	v_mov_b32_e32 v159, v211
	s_nop 0
	s_waitcnt vmcnt(14)
	v_mov_b32_e32 v112, v212
	v_mov_b32_e32 v113, v213
	v_mov_b32_e32 v114, v159
	v_mov_b32_e32 v115, v113
	v_pk_mul_f32 v[160:161], v[104:105], v[114:115]
	v_mov_b32_e32 v159, v112
	v_pk_fma_f32 v[112:113], v[108:109], v[158:159], v[160:161]
	v_pk_mul_f32 v[108:109], v[108:109], v[114:115]
	v_bitop3_b32 v114, v157, s22, 3 bitop3:0xc8
	v_pk_fma_f32 v[108:109], v[104:105], v[158:159], v[108:109] neg_lo:[0,0,1] neg_hi:[0,0,1]
	v_bitop3_b32 v104, v157, s22, 2 bitop3:0xc8
	v_lshlrev_b32_e32 v151, 7, v104
	v_or_b32_e32 v104, v151, v141
	v_lshlrev_b32_e32 v157, 7, v114
	v_lshlrev_b32_e32 v152, 3, v104
	v_or_b32_e32 v114, v157, v141
	v_lshl_add_u64 v[104:105], s[2:3], 0, v[152:153]
	v_lshlrev_b32_e32 v152, 3, v114
	v_lshl_add_u64 v[114:115], s[2:3], 0, v[152:153]
	s_waitcnt vmcnt(13)
	v_mov_b32_e32 v104, v214
	v_mov_b32_e32 v105, v215
	s_nop 0
	s_waitcnt vmcnt(12)
	v_mov_b32_e32 v114, v216
	v_mov_b32_e32 v115, v217
	v_mov_b32_e32 v158, v105
	v_mov_b32_e32 v159, v115
	v_pk_mul_f32 v[160:161], v[106:107], v[158:159]
	v_mov_b32_e32 v105, v114
	v_pk_fma_f32 v[114:115], v[110:111], v[104:105], v[160:161]
	v_pk_mul_f32 v[110:111], v[110:111], v[158:159]
	s_nop 0
	v_pk_fma_f32 v[106:107], v[106:107], v[104:105], v[110:111] neg_lo:[0,0,1] neg_hi:[0,0,1]
	v_cvt_f16_f32_e32 v104, v108
	v_cvt_f16_f32_e32 v105, v109
	v_cvt_f16_f32_e32 v110, v106
	v_cvt_f16_f32_e32 v111, v107
	ds_write_b16 v139, v104 offset:16896
	ds_write_b16 v139, v105 offset:17424
	ds_write_b16 v139, v110 offset:17952
	ds_write_b16 v139, v111 offset:18480
	v_cvt_f16_f32_e32 v104, v112
	v_cvt_f16_f32_e32 v105, v113
	v_cvt_f16_f32_e32 v110, v114
	v_cvt_f16_f32_e32 v111, v115
	ds_write_b16 v139, v104 offset:16928
	ds_write_b16 v139, v105 offset:17456
	ds_write_b16 v139, v110 offset:17984
	ds_write_b16 v139, v111 offset:18512
	v_bitop3_b32 v110, v142, s22, 1 bitop3:0xc8
	v_or_b32_e32 v104, v135, v141
	v_lshlrev_b32_e32 v158, 7, v110
	v_lshlrev_b32_e32 v152, 3, v104
	v_or_b32_e32 v110, v158, v141
	v_lshl_add_u64 v[104:105], s[2:3], 0, v[152:153]
	v_lshlrev_b32_e32 v152, 3, v110
	v_lshl_add_u64 v[110:111], s[2:3], 0, v[152:153]
	s_waitcnt vmcnt(11)
	v_mov_b32_e32 v160, v218
	v_mov_b32_e32 v161, v219
	s_nop 0
	s_waitcnt vmcnt(10)
	v_mov_b32_e32 v104, v220
	v_mov_b32_e32 v105, v221
	v_mov_b32_e32 v110, v161
	v_mov_b32_e32 v111, v105
	v_pk_mul_f32 v[162:163], v[96:97], v[110:111]
	v_mov_b32_e32 v161, v104
	v_pk_fma_f32 v[104:105], v[100:101], v[160:161], v[162:163]
	v_pk_mul_f32 v[100:101], v[100:101], v[110:111]
	v_bitop3_b32 v110, v142, s22, 3 bitop3:0xc8
	v_pk_fma_f32 v[96:97], v[96:97], v[160:161], v[100:101] neg_lo:[0,0,1] neg_hi:[0,0,1]
	v_bitop3_b32 v100, v142, s22, 2 bitop3:0xc8
	v_lshlrev_b32_e32 v159, 7, v100
	v_or_b32_e32 v100, v159, v141
	v_lshlrev_b32_e32 v160, 7, v110
	v_lshlrev_b32_e32 v152, 3, v100
	v_or_b32_e32 v110, v160, v141
	v_lshl_add_u64 v[100:101], s[2:3], 0, v[152:153]
	v_lshlrev_b32_e32 v152, 3, v110
	v_lshl_add_u64 v[110:111], s[2:3], 0, v[152:153]
	s_waitcnt vmcnt(9)
	v_mov_b32_e32 v162, v222
	v_mov_b32_e32 v163, v223
	s_nop 0
	s_waitcnt vmcnt(8)
; #define FOR_R _Pragma("unroll") for (int r = 0; r < 4; ++r)
; #define FOR_AI _Pragma("unroll") for (int ai = 0; ai < 2; ++ai)
; #define FOR_BJ _Pragma("unroll") for (int bj = 0; bj < 2; ++bj)
; #define FOR_M4 _Pragma("unroll") for (int m = 0; m < 4; ++m)
; template <bool ISK>
; __device__ void job_qk_g(const P& p, int l, int g, int ct2, int rt, HALF* sm) {
;     ...
;   const float2* rope = (const float2*)(ws + OFF_ROPE);
;   FOR_AI FOR_BJ {
;     FOR_M4 {
;       const int row0 = ai * 128 + wr * 64 + m * 16 + fq * 4;
;       const int lc = bj * 128 + wc * 32 + fr;
;       const int j = (bj * 4 + wc) * 16 + fr;
;       f4 o1, o2;
;       FOR_R {
;         const int sp = (rt * 256 + row0 + r) & (S - 1);
;         const float2 cs = rope[sp * 128 + j];
;         const float a = acc[ai][bj][m][0][r], b = acc[ai][bj][m][1][r];
;         o1[r] = a * cs.x - b * cs.y;
;         o2[r] = a * cs.y + b * cs.x;
;       }
;       acc[ai][bj][m][0] = o1;
;       acc[ai][bj][m][1] = o2;
;       stage2_rm(sm, row0, lc, to_h4(o1));
;       stage2_rm(sm, row0, lc + 16, to_h4(o2));
;       __builtin_amdgcn_sched_barrier(0);
;     }
;   }
	v_mov_b32_e32 v100, v224
	v_mov_b32_e32 v101, v225
	v_mov_b32_e32 v110, v163
	v_mov_b32_e32 v111, v101
	v_pk_mul_f32 v[164:165], v[98:99], v[110:111]
	v_mov_b32_e32 v163, v100
	v_pk_fma_f32 v[100:101], v[102:103], v[162:163], v[164:165]
	v_pk_mul_f32 v[102:103], v[102:103], v[110:111]
	s_nop 0
	v_pk_fma_f32 v[98:99], v[98:99], v[162:163], v[102:103] neg_lo:[0,0,1] neg_hi:[0,0,1]
	v_cvt_f16_f32_e32 v102, v96
	v_cvt_f16_f32_e32 v103, v97
	v_cvt_f16_f32_e32 v110, v98
	v_cvt_f16_f32_e32 v111, v99
	ds_write_b16 v139, v102 offset:25344
	ds_write_b16 v139, v103 offset:25872
	ds_write_b16 v139, v110 offset:26400
	ds_write_b16 v139, v111 offset:26928
	v_cvt_f16_f32_e32 v102, v104
	v_cvt_f16_f32_e32 v103, v105
	v_cvt_f16_f32_e32 v110, v100
	v_cvt_f16_f32_e32 v111, v101
	ds_write_b16 v139, v102 offset:25376
	ds_write_b16 v139, v103 offset:25904
	ds_write_b16 v139, v110 offset:26432
	ds_write_b16 v139, v111 offset:26960
	v_or_b32_e32 v142, 64, v141
	v_or_b32_e32 v102, v138, v142
	v_lshlrev_b32_e32 v152, 3, v102
	v_or_b32_e32 v110, v140, v142
	v_lshl_add_u64 v[102:103], s[2:3], 0, v[152:153]
	v_lshlrev_b32_e32 v152, 3, v110
	v_lshl_add_u64 v[110:111], s[2:3], 0, v[152:153]
	v_add_u32_e32 v227, 0x8200, v226
	global_load_dwordx2 v[210:211], v227, s[2:3]
	global_load_dwordx2 v[212:213], v227, s[2:3] offset:1024
	global_load_dwordx2 v[214:215], v227, s[2:3] offset:2048
	global_load_dwordx2 v[216:217], v227, s[2:3] offset:3072
	v_add_u32_e32 v227, 0xc200, v226
	global_load_dwordx2 v[218:219], v227, s[2:3]
	global_load_dwordx2 v[220:221], v227, s[2:3] offset:1024
	global_load_dwordx2 v[222:223], v227, s[2:3] offset:2048
	global_load_dwordx2 v[224:225], v227, s[2:3] offset:3072
	s_waitcnt vmcnt(15)
	v_mov_b32_e32 v162, v194
	v_mov_b32_e32 v163, v195
	s_nop 0
	s_waitcnt vmcnt(14)
	v_mov_b32_e32 v102, v196
	v_mov_b32_e32 v103, v197
	v_mov_b32_e32 v110, v163
	v_mov_b32_e32 v111, v103
	v_pk_mul_f32 v[164:165], v[88:89], v[110:111]
	v_mov_b32_e32 v163, v102
	v_pk_fma_f32 v[102:103], v[92:93], v[162:163], v[164:165]
	v_pk_mul_f32 v[92:93], v[92:93], v[110:111]
	v_or_b32_e32 v110, v144, v142
	v_pk_fma_f32 v[92:93], v[88:89], v[162:163], v[92:93] neg_lo:[0,0,1] neg_hi:[0,0,1]
	v_or_b32_e32 v88, v143, v142
	v_lshlrev_b32_e32 v152, 3, v88
	v_lshl_add_u64 v[88:89], s[2:3], 0, v[152:153]
	v_lshlrev_b32_e32 v152, 3, v110
	v_lshl_add_u64 v[110:111], s[2:3], 0, v[152:153]
	s_waitcnt vmcnt(13)
	v_mov_b32_e32 v88, v198
	v_mov_b32_e32 v89, v199
	s_nop 0
	s_waitcnt vmcnt(12)
	v_mov_b32_e32 v110, v200
	v_mov_b32_e32 v111, v201
	v_mov_b32_e32 v162, v89
	v_mov_b32_e32 v163, v111
	v_pk_mul_f32 v[164:165], v[90:91], v[162:163]
	v_mov_b32_e32 v89, v110
	v_pk_fma_f32 v[110:111], v[94:95], v[88:89], v[164:165]
	v_pk_mul_f32 v[94:95], v[94:95], v[162:163]
	s_nop 0
	v_pk_fma_f32 v[94:95], v[90:91], v[88:89], v[94:95] neg_lo:[0,0,1] neg_hi:[0,0,1]
	v_cvt_f16_f32_e32 v88, v92
	v_cvt_f16_f32_e32 v89, v93
	v_cvt_f16_f32_e32 v90, v94
	v_cvt_f16_f32_e32 v91, v95
	ds_write_b16 v139, v88 offset:256
	ds_write_b16 v139, v89 offset:784
	ds_write_b16 v139, v90 offset:1312
	ds_write_b16 v139, v91 offset:1840
	v_cvt_f16_f32_e32 v88, v102
	v_cvt_f16_f32_e32 v89, v103
	v_cvt_f16_f32_e32 v90, v110
	v_cvt_f16_f32_e32 v91, v111
	ds_write_b16 v139, v88 offset:288
	ds_write_b16 v139, v89 offset:816
	ds_write_b16 v139, v90 offset:1344
	ds_write_b16 v139, v91 offset:1872
	v_or_b32_e32 v88, v145, v142
	v_lshlrev_b32_e32 v152, 3, v88
	v_or_b32_e32 v90, v146, v142
	v_lshl_add_u64 v[88:89], s[2:3], 0, v[152:153]
	v_lshlrev_b32_e32 v152, 3, v90
	v_lshl_add_u64 v[90:91], s[2:3], 0, v[152:153]
	s_waitcnt vmcnt(11)
	v_mov_b32_e32 v144, v202
	v_mov_b32_e32 v145, v203
	s_nop 0
	s_waitcnt vmcnt(10)
	v_mov_b32_e32 v88, v204
	v_mov_b32_e32 v89, v205
	v_mov_b32_e32 v90, v145
	v_mov_b32_e32 v91, v89
	v_pk_mul_f32 v[162:163], v[80:81], v[90:91]
	v_mov_b32_e32 v145, v88
	v_pk_fma_f32 v[88:89], v[84:85], v[144:145], v[162:163]
	v_pk_mul_f32 v[84:85], v[84:85], v[90:91]
	v_or_b32_e32 v90, v148, v142
	v_pk_fma_f32 v[84:85], v[80:81], v[144:145], v[84:85] neg_lo:[0,0,1] neg_hi:[0,0,1]
	v_or_b32_e32 v80, v147, v142
	v_lshlrev_b32_e32 v152, 3, v80
	v_lshl_add_u64 v[80:81], s[2:3], 0, v[152:153]
	v_lshlrev_b32_e32 v152, 3, v90
	v_lshl_add_u64 v[90:91], s[2:3], 0, v[152:153]
	s_waitcnt vmcnt(9)
	v_mov_b32_e32 v80, v206
	v_mov_b32_e32 v81, v207
	s_nop 0
	s_waitcnt vmcnt(8)
	v_mov_b32_e32 v90, v208
	v_mov_b32_e32 v91, v209
	v_mov_b32_e32 v144, v81
	v_mov_b32_e32 v145, v91
	v_pk_mul_f32 v[146:147], v[82:83], v[144:145]
	v_mov_b32_e32 v81, v90
	v_pk_fma_f32 v[90:91], v[86:87], v[80:81], v[146:147]
	v_pk_mul_f32 v[86:87], v[86:87], v[144:145]
	s_nop 0
	v_pk_fma_f32 v[86:87], v[82:83], v[80:81], v[86:87] neg_lo:[0,0,1] neg_hi:[0,0,1]
	v_cvt_f16_f32_e32 v80, v84
	v_cvt_f16_f32_e32 v81, v85
	v_cvt_f16_f32_e32 v82, v86
	v_cvt_f16_f32_e32 v83, v87
	ds_write_b16 v139, v80 offset:8704
	ds_write_b16 v139, v81 offset:9232
	ds_write_b16 v139, v82 offset:9760
	ds_write_b16 v139, v83 offset:10288
	v_cvt_f16_f32_e32 v80, v88
	v_cvt_f16_f32_e32 v81, v89
	v_cvt_f16_f32_e32 v82, v90
	v_cvt_f16_f32_e32 v83, v91
	ds_write_b16 v139, v80 offset:8736
	ds_write_b16 v139, v81 offset:9264
	ds_write_b16 v139, v82 offset:9792
	ds_write_b16 v139, v83 offset:10320
	v_or_b32_e32 v80, v149, v142
	v_lshlrev_b32_e32 v152, 3, v80
	v_or_b32_e32 v82, v150, v142
	v_lshl_add_u64 v[80:81], s[2:3], 0, v[152:153]
	v_lshlrev_b32_e32 v152, 3, v82
	v_lshl_add_u64 v[82:83], s[2:3], 0, v[152:153]
	v_add_u32_e32 v227, 0x20000, v226
	global_load_dwordx2 v[194:195], v227, s[2:3]
	global_load_dwordx2 v[196:197], v227, s[2:3] offset:1024
	global_load_dwordx2 v[198:199], v227, s[2:3] offset:2048
	global_load_dwordx2 v[200:201], v227, s[2:3] offset:3072
	v_add_u32_e32 v227, 0x24000, v226
	global_load_dwordx2 v[202:203], v227, s[2:3]
	global_load_dwordx2 v[204:205], v227, s[2:3] offset:1024
	global_load_dwordx2 v[206:207], v227, s[2:3] offset:2048
	global_load_dwordx2 v[208:209], v227, s[2:3] offset:3072
	s_waitcnt vmcnt(15)
; #define FOR_R _Pragma("unroll") for (int r = 0; r < 4; ++r)
; #define FOR_AI _Pragma("unroll") for (int ai = 0; ai < 2; ++ai)
; #define FOR_BJ _Pragma("unroll") for (int bj = 0; bj < 2; ++bj)
; #define FOR_M4 _Pragma("unroll") for (int m = 0; m < 4; ++m)
; template <bool ISK>
; __device__ void job_qk_g(const P& p, int l, int g, int ct2, int rt, HALF* sm) {
;     ...
;   const float2* rope = (const float2*)(ws + OFF_ROPE);
;   FOR_AI FOR_BJ {
;     FOR_M4 {
;       const int row0 = ai * 128 + wr * 64 + m * 16 + fq * 4;
;       const int lc = bj * 128 + wc * 32 + fr;
;       const int j = (bj * 4 + wc) * 16 + fr;
;       f4 o1, o2;
;       FOR_R {
;         const int sp = (rt * 256 + row0 + r) & (S - 1);
;         const float2 cs = rope[sp * 128 + j];
;         const float a = acc[ai][bj][m][0][r], b = acc[ai][bj][m][1][r];
;         o1[r] = a * cs.x - b * cs.y;
;         o2[r] = a * cs.y + b * cs.x;
;       }
;       acc[ai][bj][m][0] = o1;
;       acc[ai][bj][m][1] = o2;
;       stage2_rm(sm, row0, lc, to_h4(o1));
;       stage2_rm(sm, row0, lc + 16, to_h4(o2));
;       __builtin_amdgcn_sched_barrier(0);
;     }
;   }
	v_mov_b32_e32 v144, v210
	v_mov_b32_e32 v145, v211
	s_nop 0
	s_waitcnt vmcnt(14)
	v_mov_b32_e32 v80, v212
	v_mov_b32_e32 v81, v213
	v_mov_b32_e32 v82, v145
	v_mov_b32_e32 v83, v81
	v_pk_mul_f32 v[146:147], v[72:73], v[82:83]
	v_mov_b32_e32 v145, v80
	v_pk_fma_f32 v[80:81], v[76:77], v[144:145], v[146:147]
	v_pk_mul_f32 v[76:77], v[76:77], v[82:83]
	v_or_b32_e32 v82, v157, v142
	v_pk_fma_f32 v[76:77], v[72:73], v[144:145], v[76:77] neg_lo:[0,0,1] neg_hi:[0,0,1]
	v_or_b32_e32 v72, v151, v142
	v_lshlrev_b32_e32 v152, 3, v72
	v_lshl_add_u64 v[72:73], s[2:3], 0, v[152:153]
	v_lshlrev_b32_e32 v152, 3, v82
	v_lshl_add_u64 v[82:83], s[2:3], 0, v[152:153]
	s_waitcnt vmcnt(13)
	v_mov_b32_e32 v72, v214
	v_mov_b32_e32 v73, v215
	s_nop 0
	s_waitcnt vmcnt(12)
	v_mov_b32_e32 v82, v216
	v_mov_b32_e32 v83, v217
	v_mov_b32_e32 v144, v73
	v_mov_b32_e32 v145, v83
	v_pk_mul_f32 v[146:147], v[74:75], v[144:145]
	v_mov_b32_e32 v73, v82
	v_pk_fma_f32 v[82:83], v[78:79], v[72:73], v[146:147]
	v_pk_mul_f32 v[78:79], v[78:79], v[144:145]
	s_nop 0
	v_pk_fma_f32 v[78:79], v[74:75], v[72:73], v[78:79] neg_lo:[0,0,1] neg_hi:[0,0,1]
	v_cvt_f16_f32_e32 v72, v76
	v_cvt_f16_f32_e32 v73, v77
	v_cvt_f16_f32_e32 v74, v78
	v_cvt_f16_f32_e32 v75, v79
	ds_write_b16 v139, v72 offset:17152
	ds_write_b16 v139, v73 offset:17680
	ds_write_b16 v139, v74 offset:18208
	ds_write_b16 v139, v75 offset:18736
	v_cvt_f16_f32_e32 v72, v80
	v_cvt_f16_f32_e32 v73, v81
	v_cvt_f16_f32_e32 v74, v82
	v_cvt_f16_f32_e32 v75, v83
	ds_write_b16 v139, v72 offset:17184
	ds_write_b16 v139, v73 offset:17712
	ds_write_b16 v139, v74 offset:18240
	ds_write_b16 v139, v75 offset:18768
	v_or_b32_e32 v72, v135, v142
	v_lshlrev_b32_e32 v152, 3, v72
	v_or_b32_e32 v74, v158, v142
	v_lshl_add_u64 v[72:73], s[2:3], 0, v[152:153]
	v_lshlrev_b32_e32 v152, 3, v74
	v_lshl_add_u64 v[74:75], s[2:3], 0, v[152:153]
	s_waitcnt vmcnt(11)
	v_mov_b32_e32 v144, v218
	v_mov_b32_e32 v145, v219
	s_nop 0
	s_waitcnt vmcnt(10)
	v_mov_b32_e32 v72, v220
	v_mov_b32_e32 v73, v221
	v_mov_b32_e32 v74, v145
	v_mov_b32_e32 v75, v73
	v_pk_mul_f32 v[146:147], v[64:65], v[74:75]
	v_mov_b32_e32 v145, v72
	v_pk_fma_f32 v[72:73], v[68:69], v[144:145], v[146:147]
	v_pk_mul_f32 v[68:69], v[68:69], v[74:75]
	v_or_b32_e32 v74, v160, v142
	v_pk_fma_f32 v[68:69], v[64:65], v[144:145], v[68:69] neg_lo:[0,0,1] neg_hi:[0,0,1]
	v_or_b32_e32 v64, v159, v142
	v_lshlrev_b32_e32 v152, 3, v64
	v_lshl_add_u64 v[64:65], s[2:3], 0, v[152:153]
	v_lshlrev_b32_e32 v152, 3, v74
	v_lshl_add_u64 v[74:75], s[2:3], 0, v[152:153]
	s_waitcnt vmcnt(9)
	v_mov_b32_e32 v64, v222
	v_mov_b32_e32 v65, v223
	s_nop 0
	s_waitcnt vmcnt(8)
	v_mov_b32_e32 v74, v224
	v_mov_b32_e32 v75, v225
	v_mov_b32_e32 v144, v65
	v_mov_b32_e32 v145, v75
	v_pk_mul_f32 v[146:147], v[66:67], v[144:145]
	v_mov_b32_e32 v65, v74
	v_pk_fma_f32 v[74:75], v[70:71], v[64:65], v[146:147]
	v_pk_mul_f32 v[70:71], v[70:71], v[144:145]
	s_nop 0
	v_pk_fma_f32 v[70:71], v[66:67], v[64:65], v[70:71] neg_lo:[0,0,1] neg_hi:[0,0,1]
	v_cvt_f16_f32_e32 v64, v68
	v_cvt_f16_f32_e32 v65, v69
	v_cvt_f16_f32_e32 v66, v70
	v_cvt_f16_f32_e32 v67, v71
	ds_write_b16 v139, v64 offset:25600
	ds_write_b16 v139, v65 offset:26128
	ds_write_b16 v139, v66 offset:26656
	ds_write_b16 v139, v67 offset:27184
	v_cvt_f16_f32_e32 v64, v72
	v_cvt_f16_f32_e32 v65, v73
	v_cvt_f16_f32_e32 v66, v74
	v_cvt_f16_f32_e32 v67, v75
	ds_write_b16 v139, v64 offset:25632
	ds_write_b16 v139, v65 offset:26160
	ds_write_b16 v139, v66 offset:26688
	ds_write_b16 v139, v67 offset:27216
	v_add_u32_e32 v135, 0xb0, v133
	v_add_u32_e32 v138, 0x80, v133
	v_add_u32_e32 v164, s21, v135
	v_and_b32_e32 v64, s22, v164
	v_add_u32_e32 v140, s21, v138
	v_lshlrev_b32_e32 v144, 7, v64
	v_and_b32_e32 v64, s22, v140
	v_lshlrev_b32_e32 v145, 7, v64
	v_bitop3_b32 v66, v140, s22, 1 bitop3:0xc8
	v_or_b32_e32 v64, v145, v141
	v_lshlrev_b32_e32 v146, 7, v66
	v_lshlrev_b32_e32 v152, 3, v64
	v_or_b32_e32 v66, v146, v141
	v_lshl_add_u64 v[64:65], s[2:3], 0, v[152:153]
	v_lshlrev_b32_e32 v152, 3, v66
	v_lshl_add_u64 v[66:67], s[2:3], 0, v[152:153]
	v_add_u32_e32 v227, 0x28000, v226
	global_load_dwordx2 v[210:211], v227, s[2:3]
	global_load_dwordx2 v[212:213], v227, s[2:3] offset:1024
	global_load_dwordx2 v[214:215], v227, s[2:3] offset:2048
	global_load_dwordx2 v[216:217], v227, s[2:3] offset:3072
	v_add_u32_e32 v227, 0x2c000, v226
	global_load_dwordx2 v[218:219], v227, s[2:3]
	global_load_dwordx2 v[220:221], v227, s[2:3] offset:1024
	global_load_dwordx2 v[222:223], v227, s[2:3] offset:2048
	global_load_dwordx2 v[224:225], v227, s[2:3] offset:3072
	s_waitcnt vmcnt(15)
	v_mov_b32_e32 v148, v194
	v_mov_b32_e32 v149, v195
	s_nop 0
	s_waitcnt vmcnt(14)
	v_mov_b32_e32 v64, v196
	v_mov_b32_e32 v65, v197
	v_add_u32_e32 v143, 0x10800, v139
	v_mov_b32_e32 v66, v149
	v_mov_b32_e32 v67, v65
	v_pk_mul_f32 v[150:151], v[56:57], v[66:67]
	v_mov_b32_e32 v149, v64
	v_pk_fma_f32 v[64:65], v[60:61], v[148:149], v[150:151]
	v_pk_mul_f32 v[60:61], v[60:61], v[66:67]
	v_bitop3_b32 v66, v140, s22, 3 bitop3:0xc8
	v_pk_fma_f32 v[56:57], v[56:57], v[148:149], v[60:61] neg_lo:[0,0,1] neg_hi:[0,0,1]
	v_bitop3_b32 v60, v140, s22, 2 bitop3:0xc8
	v_lshlrev_b32_e32 v147, 7, v60
	v_or_b32_e32 v60, v147, v141
	v_lshlrev_b32_e32 v148, 7, v66
	v_lshlrev_b32_e32 v152, 3, v60
	v_or_b32_e32 v66, v148, v141
	v_lshl_add_u64 v[60:61], s[2:3], 0, v[152:153]
	v_lshlrev_b32_e32 v152, 3, v66
	v_lshl_add_u64 v[66:67], s[2:3], 0, v[152:153]
	s_waitcnt vmcnt(13)
	v_mov_b32_e32 v150, v198
	v_mov_b32_e32 v151, v199
	s_nop 0
	s_waitcnt vmcnt(12)
; #define FOR_R _Pragma("unroll") for (int r = 0; r < 4; ++r)
; #define FOR_AI _Pragma("unroll") for (int ai = 0; ai < 2; ++ai)
; #define FOR_BJ _Pragma("unroll") for (int bj = 0; bj < 2; ++bj)
; #define FOR_M4 _Pragma("unroll") for (int m = 0; m < 4; ++m)
; template <bool ISK>
; __device__ void job_qk_g(const P& p, int l, int g, int ct2, int rt, HALF* sm) {
;     ...
;   const float2* rope = (const float2*)(ws + OFF_ROPE);
;   FOR_AI FOR_BJ {
;     FOR_M4 {
;       const int row0 = ai * 128 + wr * 64 + m * 16 + fq * 4;
;       const int lc = bj * 128 + wc * 32 + fr;
;       const int j = (bj * 4 + wc) * 16 + fr;
;       f4 o1, o2;
;       FOR_R {
;         const int sp = (rt * 256 + row0 + r) & (S - 1);
;         const float2 cs = rope[sp * 128 + j];
;         const float a = acc[ai][bj][m][0][r], b = acc[ai][bj][m][1][r];
;         o1[r] = a * cs.x - b * cs.y;
;         o2[r] = a * cs.y + b * cs.x;
;       }
;       acc[ai][bj][m][0] = o1;
;       acc[ai][bj][m][1] = o2;
;       stage2_rm(sm, row0, lc, to_h4(o1));
;       stage2_rm(sm, row0, lc + 16, to_h4(o2));
;       __builtin_amdgcn_sched_barrier(0);
;     }
;   }
	v_mov_b32_e32 v60, v200
	v_mov_b32_e32 v61, v201
	v_mov_b32_e32 v66, v151
	v_mov_b32_e32 v67, v61
	v_pk_mul_f32 v[158:159], v[58:59], v[66:67]
	v_mov_b32_e32 v151, v60
	v_pk_fma_f32 v[60:61], v[62:63], v[150:151], v[158:159]
	v_pk_mul_f32 v[62:63], v[62:63], v[66:67]
	s_nop 0
	v_pk_fma_f32 v[62:63], v[58:59], v[150:151], v[62:63] neg_lo:[0,0,1] neg_hi:[0,0,1]
	v_cvt_f16_f32_e32 v58, v56
	v_cvt_f16_f32_e32 v59, v57
	v_cvt_f16_f32_e32 v66, v62
	v_cvt_f16_f32_e32 v67, v63
	ds_write_b16 v143, v58
	ds_write_b16 v143, v59 offset:528
	ds_write_b16 v143, v66 offset:1056
	ds_write_b16 v143, v67 offset:1584
	v_cvt_f16_f32_e32 v58, v64
	v_cvt_f16_f32_e32 v59, v65
	v_cvt_f16_f32_e32 v66, v60
	v_cvt_f16_f32_e32 v67, v61
	ds_write_b16 v143, v58 offset:32
	ds_write_b16 v143, v59 offset:560
	ds_write_b16 v143, v66 offset:1088
	ds_write_b16 v143, v67 offset:1616
	v_add_u32_e32 v140, 0x90, v133
	v_add_u32_e32 v139, s21, v140
	v_and_b32_e32 v58, s22, v139
	v_lshlrev_b32_e32 v149, 7, v58
	v_bitop3_b32 v66, v139, s22, 1 bitop3:0xc8
	v_or_b32_e32 v58, v149, v141
	v_lshlrev_b32_e32 v150, 7, v66
	v_lshlrev_b32_e32 v152, 3, v58
	v_or_b32_e32 v66, v150, v141
	v_lshl_add_u64 v[58:59], s[2:3], 0, v[152:153]
	v_lshlrev_b32_e32 v152, 3, v66
	v_lshl_add_u64 v[66:67], s[2:3], 0, v[152:153]
	s_waitcnt vmcnt(11)
	v_mov_b32_e32 v158, v202
	v_mov_b32_e32 v159, v203
	s_nop 0
	s_waitcnt vmcnt(10)
	v_mov_b32_e32 v58, v204
	v_mov_b32_e32 v59, v205
	v_mov_b32_e32 v66, v159
	v_mov_b32_e32 v67, v59
	v_pk_mul_f32 v[160:161], v[48:49], v[66:67]
	v_mov_b32_e32 v159, v58
	v_pk_fma_f32 v[58:59], v[52:53], v[158:159], v[160:161]
	v_pk_mul_f32 v[52:53], v[52:53], v[66:67]
	v_bitop3_b32 v66, v139, s22, 3 bitop3:0xc8
	v_pk_fma_f32 v[52:53], v[48:49], v[158:159], v[52:53] neg_lo:[0,0,1] neg_hi:[0,0,1]
	v_bitop3_b32 v48, v139, s22, 2 bitop3:0xc8
	v_lshlrev_b32_e32 v151, 7, v48
	v_or_b32_e32 v48, v151, v141
	v_lshlrev_b32_e32 v157, 7, v66
	v_lshlrev_b32_e32 v152, 3, v48
	v_or_b32_e32 v66, v157, v141
	v_lshl_add_u64 v[48:49], s[2:3], 0, v[152:153]
	v_lshlrev_b32_e32 v152, 3, v66
	v_lshl_add_u64 v[66:67], s[2:3], 0, v[152:153]
	s_waitcnt vmcnt(9)
	v_mov_b32_e32 v48, v206
	v_mov_b32_e32 v49, v207
	s_nop 0
	s_waitcnt vmcnt(8)
	v_mov_b32_e32 v66, v208
	v_mov_b32_e32 v67, v209
	v_mov_b32_e32 v158, v49
	v_mov_b32_e32 v159, v67
	v_pk_mul_f32 v[160:161], v[50:51], v[158:159]
	v_mov_b32_e32 v49, v66
	v_pk_fma_f32 v[66:67], v[54:55], v[48:49], v[160:161]
	v_pk_mul_f32 v[54:55], v[54:55], v[158:159]
	s_nop 0
	v_pk_fma_f32 v[54:55], v[50:51], v[48:49], v[54:55] neg_lo:[0,0,1] neg_hi:[0,0,1]
	v_cvt_f16_f32_e32 v48, v52
	v_cvt_f16_f32_e32 v49, v53
	v_cvt_f16_f32_e32 v50, v54
	v_cvt_f16_f32_e32 v51, v55
	ds_write_b16 v143, v48 offset:8448
	ds_write_b16 v143, v49 offset:8976
	ds_write_b16 v143, v50 offset:9504
	ds_write_b16 v143, v51 offset:10032
	v_cvt_f16_f32_e32 v48, v58
	v_cvt_f16_f32_e32 v49, v59
	v_cvt_f16_f32_e32 v50, v66
	v_cvt_f16_f32_e32 v51, v67
	ds_write_b16 v143, v48 offset:8480
	ds_write_b16 v143, v49 offset:9008
	ds_write_b16 v143, v50 offset:9536
	ds_write_b16 v143, v51 offset:10064
	v_add_u32_e32 v139, 0xa0, v133
	v_add_u32_e32 v165, s21, v139
	v_and_b32_e32 v48, s22, v165
	v_lshlrev_b32_e32 v158, 7, v48
	v_bitop3_b32 v50, v165, s22, 1 bitop3:0xc8
	v_or_b32_e32 v48, v158, v141
	v_lshlrev_b32_e32 v159, 7, v50
	v_lshlrev_b32_e32 v152, 3, v48
	v_or_b32_e32 v50, v159, v141
	v_lshl_add_u64 v[48:49], s[2:3], 0, v[152:153]
	v_lshlrev_b32_e32 v152, 3, v50
	v_lshl_add_u64 v[50:51], s[2:3], 0, v[152:153]
	v_add_u32_e32 v227, 0x20200, v226
	global_load_dwordx2 v[194:195], v227, s[2:3]
	global_load_dwordx2 v[196:197], v227, s[2:3] offset:1024
	global_load_dwordx2 v[198:199], v227, s[2:3] offset:2048
	global_load_dwordx2 v[200:201], v227, s[2:3] offset:3072
	v_add_u32_e32 v227, 0x24200, v226
	global_load_dwordx2 v[202:203], v227, s[2:3]
	global_load_dwordx2 v[204:205], v227, s[2:3] offset:1024
	global_load_dwordx2 v[206:207], v227, s[2:3] offset:2048
	global_load_dwordx2 v[208:209], v227, s[2:3] offset:3072
	s_waitcnt vmcnt(15)
	v_mov_b32_e32 v160, v210
	v_mov_b32_e32 v161, v211
	s_nop 0
	s_waitcnt vmcnt(14)
	v_mov_b32_e32 v48, v212
	v_mov_b32_e32 v49, v213
	v_mov_b32_e32 v50, v161
	v_mov_b32_e32 v51, v49
	v_pk_mul_f32 v[162:163], v[40:41], v[50:51]
	v_mov_b32_e32 v161, v48
	v_pk_fma_f32 v[48:49], v[44:45], v[160:161], v[162:163]
	v_pk_mul_f32 v[44:45], v[44:45], v[50:51]
	v_bitop3_b32 v50, v165, s22, 3 bitop3:0xc8
	v_pk_fma_f32 v[44:45], v[40:41], v[160:161], v[44:45] neg_lo:[0,0,1] neg_hi:[0,0,1]
	v_bitop3_b32 v40, v165, s22, 2 bitop3:0xc8
	v_lshlrev_b32_e32 v160, 7, v40
	v_or_b32_e32 v40, v160, v141
	v_lshlrev_b32_e32 v161, 7, v50
	v_lshlrev_b32_e32 v152, 3, v40
	v_or_b32_e32 v50, v161, v141
	v_lshl_add_u64 v[40:41], s[2:3], 0, v[152:153]
	v_lshlrev_b32_e32 v152, 3, v50
	v_lshl_add_u64 v[50:51], s[2:3], 0, v[152:153]
	s_waitcnt vmcnt(13)
	v_mov_b32_e32 v40, v214
	v_mov_b32_e32 v41, v215
	s_nop 0
	s_waitcnt vmcnt(12)
	v_mov_b32_e32 v50, v216
	v_mov_b32_e32 v51, v217
	v_mov_b32_e32 v162, v41
	v_mov_b32_e32 v163, v51
	v_pk_mul_f32 v[166:167], v[42:43], v[162:163]
	v_mov_b32_e32 v41, v50
	v_pk_fma_f32 v[50:51], v[46:47], v[40:41], v[166:167]
	v_pk_mul_f32 v[46:47], v[46:47], v[162:163]
	s_nop 0
	v_pk_fma_f32 v[42:43], v[42:43], v[40:41], v[46:47] neg_lo:[0,0,1] neg_hi:[0,0,1]
	v_cvt_f16_f32_e32 v40, v44
	v_cvt_f16_f32_e32 v41, v45
	v_cvt_f16_f32_e32 v46, v42
	v_cvt_f16_f32_e32 v47, v43
	ds_write_b16 v143, v40 offset:16896
	ds_write_b16 v143, v41 offset:17424
	ds_write_b16 v143, v46 offset:17952
	ds_write_b16 v143, v47 offset:18480
	v_cvt_f16_f32_e32 v40, v48
	v_cvt_f16_f32_e32 v41, v49
	v_cvt_f16_f32_e32 v46, v50
	v_cvt_f16_f32_e32 v47, v51
	ds_write_b16 v143, v40 offset:16928
	ds_write_b16 v143, v41 offset:17456
	ds_write_b16 v143, v46 offset:17984
	ds_write_b16 v143, v47 offset:18512
	v_bitop3_b32 v46, v164, s22, 1 bitop3:0xc8
	v_or_b32_e32 v40, v144, v141
	v_lshlrev_b32_e32 v162, 7, v46
	v_lshlrev_b32_e32 v152, 3, v40
	v_or_b32_e32 v46, v162, v141
	v_lshl_add_u64 v[40:41], s[2:3], 0, v[152:153]
	v_lshlrev_b32_e32 v152, 3, v46
	v_lshl_add_u64 v[46:47], s[2:3], 0, v[152:153]
	s_waitcnt vmcnt(11)
; #define FOR_R _Pragma("unroll") for (int r = 0; r < 4; ++r)
; #define FOR_AI _Pragma("unroll") for (int ai = 0; ai < 2; ++ai)
; #define FOR_BJ _Pragma("unroll") for (int bj = 0; bj < 2; ++bj)
; #define FOR_M4 _Pragma("unroll") for (int m = 0; m < 4; ++m)
; template <bool ISK>
; __device__ void job_qk_g(const P& p, int l, int g, int ct2, int rt, HALF* sm) {
;     ...
;   const float2* rope = (const float2*)(ws + OFF_ROPE);
;   FOR_AI FOR_BJ {
;     FOR_M4 {
;       const int row0 = ai * 128 + wr * 64 + m * 16 + fq * 4;
;       const int lc = bj * 128 + wc * 32 + fr;
;       const int j = (bj * 4 + wc) * 16 + fr;
;       f4 o1, o2;
;       FOR_R {
;         const int sp = (rt * 256 + row0 + r) & (S - 1);
;         const float2 cs = rope[sp * 128 + j];
;         const float a = acc[ai][bj][m][0][r], b = acc[ai][bj][m][1][r];
;         o1[r] = a * cs.x - b * cs.y;
;         o2[r] = a * cs.y + b * cs.x;
;       }
;       acc[ai][bj][m][0] = o1;
;       acc[ai][bj][m][1] = o2;
;       stage2_rm(sm, row0, lc, to_h4(o1));
;       stage2_rm(sm, row0, lc + 16, to_h4(o2));
;       __builtin_amdgcn_sched_barrier(0);
;     }
;   }
	v_mov_b32_e32 v166, v218
	v_mov_b32_e32 v167, v219
	s_nop 0
	s_waitcnt vmcnt(10)
	v_mov_b32_e32 v40, v220
	v_mov_b32_e32 v41, v221
	v_mov_b32_e32 v46, v167
	v_mov_b32_e32 v47, v41
	v_pk_mul_f32 v[168:169], v[32:33], v[46:47]
	v_mov_b32_e32 v167, v40
	v_pk_fma_f32 v[40:41], v[36:37], v[166:167], v[168:169]
	v_pk_mul_f32 v[36:37], v[36:37], v[46:47]
	v_bitop3_b32 v46, v164, s22, 3 bitop3:0xc8
	v_pk_fma_f32 v[32:33], v[32:33], v[166:167], v[36:37] neg_lo:[0,0,1] neg_hi:[0,0,1]
	v_bitop3_b32 v36, v164, s22, 2 bitop3:0xc8
	v_lshlrev_b32_e32 v163, 7, v36
	v_or_b32_e32 v36, v163, v141
	v_lshlrev_b32_e32 v164, 7, v46
	v_lshlrev_b32_e32 v152, 3, v36
	v_or_b32_e32 v46, v164, v141
	v_lshl_add_u64 v[36:37], s[2:3], 0, v[152:153]
	v_lshlrev_b32_e32 v152, 3, v46
	v_lshl_add_u64 v[46:47], s[2:3], 0, v[152:153]
	s_waitcnt vmcnt(9)
	v_mov_b32_e32 v166, v222
	v_mov_b32_e32 v167, v223
	s_nop 0
	s_waitcnt vmcnt(8)
	v_mov_b32_e32 v36, v224
	v_mov_b32_e32 v37, v225
	v_mov_b32_e32 v46, v167
	v_mov_b32_e32 v47, v37
	v_pk_mul_f32 v[168:169], v[34:35], v[46:47]
	v_mov_b32_e32 v167, v36
	v_pk_fma_f32 v[36:37], v[38:39], v[166:167], v[168:169]
	v_pk_mul_f32 v[38:39], v[38:39], v[46:47]
	s_nop 0
	v_pk_fma_f32 v[34:35], v[34:35], v[166:167], v[38:39] neg_lo:[0,0,1] neg_hi:[0,0,1]
	v_cvt_f16_f32_e32 v38, v32
	v_cvt_f16_f32_e32 v39, v33
	v_cvt_f16_f32_e32 v46, v34
	v_cvt_f16_f32_e32 v47, v35
	ds_write_b16 v143, v38 offset:25344
	ds_write_b16 v143, v39 offset:25872
	ds_write_b16 v143, v46 offset:26400
	ds_write_b16 v143, v47 offset:26928
	v_cvt_f16_f32_e32 v38, v40
	v_cvt_f16_f32_e32 v39, v41
	v_cvt_f16_f32_e32 v46, v36
	v_cvt_f16_f32_e32 v47, v37
	ds_write_b16 v143, v38 offset:25376
	ds_write_b16 v143, v39 offset:25904
	ds_write_b16 v143, v46 offset:26432
	ds_write_b16 v143, v47 offset:26960
	v_or_b32_e32 v38, v145, v142
	v_lshlrev_b32_e32 v152, 3, v38
	v_or_b32_e32 v46, v146, v142
	v_lshl_add_u64 v[38:39], s[2:3], 0, v[152:153]
	v_lshlrev_b32_e32 v152, 3, v46
	v_lshl_add_u64 v[46:47], s[2:3], 0, v[152:153]
	v_add_u32_e32 v227, 0x28200, v226
	global_load_dwordx2 v[210:211], v227, s[2:3]
	global_load_dwordx2 v[212:213], v227, s[2:3] offset:1024
	global_load_dwordx2 v[214:215], v227, s[2:3] offset:2048
	global_load_dwordx2 v[216:217], v227, s[2:3] offset:3072
	v_add_u32_e32 v227, 0x2c200, v226
	global_load_dwordx2 v[218:219], v227, s[2:3]
	global_load_dwordx2 v[220:221], v227, s[2:3] offset:1024
	global_load_dwordx2 v[222:223], v227, s[2:3] offset:2048
	global_load_dwordx2 v[224:225], v227, s[2:3] offset:3072
	s_waitcnt vmcnt(15)
	v_mov_b32_e32 v166, v194
	v_mov_b32_e32 v167, v195
	s_nop 0
	s_waitcnt vmcnt(14)
	v_mov_b32_e32 v38, v196
	v_mov_b32_e32 v39, v197
	v_mov_b32_e32 v46, v167
	v_mov_b32_e32 v47, v39
	v_pk_mul_f32 v[168:169], v[24:25], v[46:47]
	v_mov_b32_e32 v167, v38
	v_pk_fma_f32 v[38:39], v[28:29], v[166:167], v[168:169]
	v_pk_mul_f32 v[28:29], v[28:29], v[46:47]
	v_or_b32_e32 v46, v148, v142
	v_pk_fma_f32 v[28:29], v[24:25], v[166:167], v[28:29] neg_lo:[0,0,1] neg_hi:[0,0,1]
	v_or_b32_e32 v24, v147, v142
	v_lshlrev_b32_e32 v152, 3, v24
	v_lshl_add_u64 v[24:25], s[2:3], 0, v[152:153]
	v_lshlrev_b32_e32 v152, 3, v46
	v_lshl_add_u64 v[46:47], s[2:3], 0, v[152:153]
	s_waitcnt vmcnt(13)
	v_mov_b32_e32 v24, v198
	v_mov_b32_e32 v25, v199
	s_nop 0
	s_waitcnt vmcnt(12)
	v_mov_b32_e32 v46, v200
	v_mov_b32_e32 v47, v201
	v_mov_b32_e32 v146, v25
	v_mov_b32_e32 v147, v47
	v_pk_mul_f32 v[166:167], v[26:27], v[146:147]
	v_mov_b32_e32 v25, v46
	v_pk_fma_f32 v[46:47], v[30:31], v[24:25], v[166:167]
	v_pk_mul_f32 v[30:31], v[30:31], v[146:147]
	s_nop 0
	v_pk_fma_f32 v[30:31], v[26:27], v[24:25], v[30:31] neg_lo:[0,0,1] neg_hi:[0,0,1]
	v_cvt_f16_f32_e32 v24, v28
	v_cvt_f16_f32_e32 v25, v29
	v_cvt_f16_f32_e32 v26, v30
	v_cvt_f16_f32_e32 v27, v31
	ds_write_b16 v143, v24 offset:256
	ds_write_b16 v143, v25 offset:784
	ds_write_b16 v143, v26 offset:1312
	ds_write_b16 v143, v27 offset:1840
	v_cvt_f16_f32_e32 v24, v38
	v_cvt_f16_f32_e32 v25, v39
	v_cvt_f16_f32_e32 v26, v46
	v_cvt_f16_f32_e32 v27, v47
	ds_write_b16 v143, v24 offset:288
	ds_write_b16 v143, v25 offset:816
	ds_write_b16 v143, v26 offset:1344
	ds_write_b16 v143, v27 offset:1872
	v_or_b32_e32 v24, v149, v142
	v_lshlrev_b32_e32 v152, 3, v24
	v_or_b32_e32 v26, v150, v142
	v_lshl_add_u64 v[24:25], s[2:3], 0, v[152:153]
	v_lshlrev_b32_e32 v152, 3, v26
	v_lshl_add_u64 v[26:27], s[2:3], 0, v[152:153]
	s_waitcnt vmcnt(11)
	v_mov_b32_e32 v146, v202
	v_mov_b32_e32 v147, v203
	s_nop 0
	s_waitcnt vmcnt(10)
	v_mov_b32_e32 v24, v204
	v_mov_b32_e32 v25, v205
	v_mov_b32_e32 v26, v147
	v_mov_b32_e32 v27, v25
	v_pk_mul_f32 v[148:149], v[16:17], v[26:27]
	v_mov_b32_e32 v147, v24
	v_pk_fma_f32 v[24:25], v[20:21], v[146:147], v[148:149]
	v_pk_mul_f32 v[20:21], v[20:21], v[26:27]
	v_or_b32_e32 v26, v157, v142
	v_pk_fma_f32 v[20:21], v[16:17], v[146:147], v[20:21] neg_lo:[0,0,1] neg_hi:[0,0,1]
	v_or_b32_e32 v16, v151, v142
	v_lshlrev_b32_e32 v152, 3, v16
	v_lshl_add_u64 v[16:17], s[2:3], 0, v[152:153]
	v_lshlrev_b32_e32 v152, 3, v26
	v_lshl_add_u64 v[26:27], s[2:3], 0, v[152:153]
	s_waitcnt vmcnt(9)
	v_mov_b32_e32 v16, v206
	v_mov_b32_e32 v17, v207
	s_nop 0
	s_waitcnt vmcnt(8)
; DEV int opaque_tid512() { int t = threadIdx.x; asm volatile("" : "+v"(t)); return t; }
; #define FOR_R _Pragma("unroll") for (int r = 0; r < 4; ++r)
; #define FOR_AI _Pragma("unroll") for (int ai = 0; ai < 2; ++ai)
; #define FOR_BJ _Pragma("unroll") for (int bj = 0; bj < 2; ++bj)
; #define FOR_M4 _Pragma("unroll") for (int m = 0; m < 4; ++m)
; template <int CPR, class F>
; DEV void flush2(HALF* S, int NR, F fn) {
; #pragma unroll 4
;   for (int id = opaque_tid512(); id < NR * CPR; id += 512) {
;     const int row = id / CPR, ch = id % CPR;
;     const u4 v = *(const u4*)(S + row * SST2 + ch * 8);
;     __builtin_nontemporal_store(v, (u4*)(fn(row, ch)));
;   }
; template <bool ISK>
; __device__ void job_qk_g(const P& p, int l, int g, int ct2, int rt, HALF* sm) {
;     ...
;   const float2* rope = (const float2*)(ws + OFF_ROPE);
;   FOR_AI FOR_BJ {
;     FOR_M4 {
;       const int row0 = ai * 128 + wr * 64 + m * 16 + fq * 4;
;       const int lc = bj * 128 + wc * 32 + fr;
;       const int j = (bj * 4 + wc) * 16 + fr;
;       f4 o1, o2;
;       FOR_R {
;         const int sp = (rt * 256 + row0 + r) & (S - 1);
;         const float2 cs = rope[sp * 128 + j];
;         const float a = acc[ai][bj][m][0][r], b = acc[ai][bj][m][1][r];
;         o1[r] = a * cs.x - b * cs.y;
;         o2[r] = a * cs.y + b * cs.x;
;       }
;       acc[ai][bj][m][0] = o1;
;       acc[ai][bj][m][1] = o2;
;       stage2_rm(sm, row0, lc, to_h4(o1));
;       stage2_rm(sm, row0, lc + 16, to_h4(o2));
;       __builtin_amdgcn_sched_barrier(0);
;     }
;   }
;   __syncthreads();
;   HALF* dst = (HALF*)(ws + (ISK ? G_K : G_Q));
;   flush2<32>(sm, 256, [&](int row, int ch) { return dst + (size_t)(rt * 256 + row) * 1024 + hh * 256 + ch * 8; });
	v_mov_b32_e32 v26, v208
	v_mov_b32_e32 v27, v209
	v_mov_b32_e32 v146, v17
	v_mov_b32_e32 v147, v27
	v_pk_mul_f32 v[148:149], v[18:19], v[146:147]
	v_mov_b32_e32 v17, v26
	v_pk_fma_f32 v[26:27], v[22:23], v[16:17], v[148:149]
	v_pk_mul_f32 v[22:23], v[22:23], v[146:147]
	s_nop 0
	v_pk_fma_f32 v[22:23], v[18:19], v[16:17], v[22:23] neg_lo:[0,0,1] neg_hi:[0,0,1]
	v_cvt_f16_f32_e32 v16, v20
	v_cvt_f16_f32_e32 v17, v21
	v_cvt_f16_f32_e32 v18, v22
	v_cvt_f16_f32_e32 v19, v23
	ds_write_b16 v143, v16 offset:8704
	ds_write_b16 v143, v17 offset:9232
	ds_write_b16 v143, v18 offset:9760
	ds_write_b16 v143, v19 offset:10288
	v_cvt_f16_f32_e32 v16, v24
	v_cvt_f16_f32_e32 v17, v25
	v_cvt_f16_f32_e32 v18, v26
	v_cvt_f16_f32_e32 v19, v27
	ds_write_b16 v143, v16 offset:8736
	ds_write_b16 v143, v17 offset:9264
	ds_write_b16 v143, v18 offset:9792
	ds_write_b16 v143, v19 offset:10320
	v_or_b32_e32 v16, v158, v142
	v_lshlrev_b32_e32 v152, 3, v16
	v_or_b32_e32 v18, v159, v142
	v_lshl_add_u64 v[16:17], s[2:3], 0, v[152:153]
	v_lshlrev_b32_e32 v152, 3, v18
	v_lshl_add_u64 v[18:19], s[2:3], 0, v[152:153]
	s_waitcnt vmcnt(7)
	v_mov_b32_e32 v146, v210
	v_mov_b32_e32 v147, v211
	s_nop 0
	s_waitcnt vmcnt(6)
	v_mov_b32_e32 v16, v212
	v_mov_b32_e32 v17, v213
	v_mov_b32_e32 v18, v147
	v_mov_b32_e32 v19, v17
	v_pk_mul_f32 v[148:149], v[8:9], v[18:19]
	v_mov_b32_e32 v147, v16
	v_pk_fma_f32 v[16:17], v[12:13], v[146:147], v[148:149]
	v_pk_mul_f32 v[12:13], v[12:13], v[18:19]
	v_or_b32_e32 v18, v161, v142
	v_pk_fma_f32 v[12:13], v[8:9], v[146:147], v[12:13] neg_lo:[0,0,1] neg_hi:[0,0,1]
	v_or_b32_e32 v8, v160, v142
	v_lshlrev_b32_e32 v152, 3, v8
	v_lshl_add_u64 v[8:9], s[2:3], 0, v[152:153]
	v_lshlrev_b32_e32 v152, 3, v18
	v_lshl_add_u64 v[18:19], s[2:3], 0, v[152:153]
	s_waitcnt vmcnt(5)
	v_mov_b32_e32 v8, v214
	v_mov_b32_e32 v9, v215
	s_nop 0
	s_waitcnt vmcnt(4)
	v_mov_b32_e32 v18, v216
	v_mov_b32_e32 v19, v217
	v_mov_b32_e32 v146, v9
	v_mov_b32_e32 v147, v19
	v_pk_mul_f32 v[148:149], v[10:11], v[146:147]
	v_mov_b32_e32 v9, v18
	v_pk_fma_f32 v[18:19], v[14:15], v[8:9], v[148:149]
	v_pk_mul_f32 v[14:15], v[14:15], v[146:147]
	s_nop 0
	v_pk_fma_f32 v[10:11], v[10:11], v[8:9], v[14:15] neg_lo:[0,0,1] neg_hi:[0,0,1]
	v_cvt_f16_f32_e32 v8, v12
	v_cvt_f16_f32_e32 v9, v13
	v_cvt_f16_f32_e32 v14, v10
	v_cvt_f16_f32_e32 v15, v11
	ds_write_b16 v143, v8 offset:17152
	ds_write_b16 v143, v9 offset:17680
	ds_write_b16 v143, v14 offset:18208
	ds_write_b16 v143, v15 offset:18736
	v_cvt_f16_f32_e32 v8, v16
	v_cvt_f16_f32_e32 v9, v17
	v_cvt_f16_f32_e32 v14, v18
	v_cvt_f16_f32_e32 v15, v19
	ds_write_b16 v143, v8 offset:17184
	ds_write_b16 v143, v9 offset:17712
	ds_write_b16 v143, v14 offset:18240
	ds_write_b16 v143, v15 offset:18768
	v_or_b32_e32 v8, v144, v142
	v_lshlrev_b32_e32 v152, 3, v8
	v_or_b32_e32 v14, v162, v142
	v_lshl_add_u64 v[8:9], s[2:3], 0, v[152:153]
	v_lshlrev_b32_e32 v152, 3, v14
	v_lshl_add_u64 v[14:15], s[2:3], 0, v[152:153]
	s_waitcnt vmcnt(3)
	v_mov_b32_e32 v144, v218
	v_mov_b32_e32 v145, v219
	s_nop 0
	s_waitcnt vmcnt(2)
	v_mov_b32_e32 v8, v220
	v_mov_b32_e32 v9, v221
	v_mov_b32_e32 v14, v145
	v_mov_b32_e32 v15, v9
	v_pk_mul_f32 v[146:147], v[0:1], v[14:15]
	v_mov_b32_e32 v145, v8
	v_pk_fma_f32 v[8:9], v[4:5], v[144:145], v[146:147]
	v_pk_mul_f32 v[4:5], v[4:5], v[14:15]
	v_or_b32_e32 v14, v164, v142
	v_pk_fma_f32 v[0:1], v[0:1], v[144:145], v[4:5] neg_lo:[0,0,1] neg_hi:[0,0,1]
	v_or_b32_e32 v4, v163, v142
	v_lshlrev_b32_e32 v152, 3, v4
	v_lshl_add_u64 v[4:5], s[2:3], 0, v[152:153]
	v_lshlrev_b32_e32 v152, 3, v14
	v_lshl_add_u64 v[14:15], s[2:3], 0, v[152:153]
	s_waitcnt vmcnt(1)
	v_mov_b32_e32 v144, v222
	v_mov_b32_e32 v145, v223
	s_nop 0
	s_waitcnt vmcnt(0)
	v_mov_b32_e32 v4, v224
	v_mov_b32_e32 v5, v225
	v_mov_b32_e32 v14, v145
	v_mov_b32_e32 v15, v5
	v_pk_mul_f32 v[146:147], v[2:3], v[14:15]
	v_mov_b32_e32 v145, v4
	v_pk_fma_f32 v[4:5], v[6:7], v[144:145], v[146:147]
	v_pk_mul_f32 v[6:7], v[6:7], v[14:15]
	s_nop 0
	v_pk_fma_f32 v[2:3], v[2:3], v[144:145], v[6:7] neg_lo:[0,0,1] neg_hi:[0,0,1]
	v_cvt_f16_f32_e32 v6, v0
	v_cvt_f16_f32_e32 v7, v1
	v_cvt_f16_f32_e32 v14, v2
	v_cvt_f16_f32_e32 v15, v3
	ds_write_b16 v143, v6 offset:25600
	ds_write_b16 v143, v7 offset:26128
	ds_write_b16 v143, v14 offset:26656
	ds_write_b16 v143, v15 offset:27184
	v_cvt_f16_f32_e32 v6, v8
	v_cvt_f16_f32_e32 v7, v9
	v_cvt_f16_f32_e32 v14, v4
	v_cvt_f16_f32_e32 v15, v5
	ds_write_b16 v143, v6 offset:25632
	ds_write_b16 v143, v7 offset:26160
	ds_write_b16 v143, v14 offset:26688
	ds_write_b16 v143, v15 offset:27216
	v_mov_b32_e32 v7, v155
	s_movk_i32 s2, 0x1fff
	s_waitcnt lgkmcnt(0)
	s_barrier
	s_nop 0
	v_cmp_lt_i32_e32 vcc, s2, v7
	s_and_saveexec_b64 s[2:3], vcc
	s_xor_b64 s[2:3], exec, s[2:3]
	s_lshl_b32 s6, s44, 8
	s_or_saveexec_b64 s[2:3], s[2:3]
	v_mov_b32_e32 v6, s6
	s_xor_b64 exec, exec, s[2:3]
	s_cbranch_execz .LBB0_223
	s_lshl_b32 s6, s44, 9
	v_max_i32_e32 v6, 0x1e00, v7
	s_add_u32 s6, s0, s6
	v_sub_u32_e32 v6, v6, v7
	s_addc_u32 s7, s1, 0
	v_add_u32_e32 v6, 0x1ff, v6
	s_add_u32 s6, s6, 0x1aeb0000
	v_and_b32_e32 v14, 0x600, v6
	s_movk_i32 s12, 0x600
	s_addc_u32 s7, s7, 0
	v_cmp_ne_u32_e32 vcc, s12, v14
	s_and_saveexec_b64 s[12:13], vcc
	s_cbranch_execz .LBB0_219
	v_lshrrev_b32_e32 v14, 9, v6
	v_add_u32_e32 v14, 1, v14
	v_and_b32_e32 v141, 3, v14
	v_lshl_add_u32 v14, v7, 4, 0
	v_lshlrev_b32_e32 v15, 3, v7
	v_sub_u32_e32 v141, 0, v141
	s_mov_b64 s[14:15], 0

; DEV float logsig(float x) { return -log1pf(expf(-x)); }
; __device__ void job_scores_g(const P& p, int l, int job, HALF* sm) {
;     ...
;   __syncthreads();
;   const float lgf = logsig(p.decay[l * 8 + h]);
;   const float lgb = logsig(p.decay[l * 8 + 4 + h]);
.LBB0_382:
	s_or_b64 exec, exec, s[0:1]
	v_readlane_b32 s68, v254, 14
	v_readlane_b32 s0, v255, 54
	v_readlane_b32 s69, v254, 15
	v_readlane_b32 s70, v254, 16
	v_readlane_b32 s71, v254, 17
	v_readlane_b32 s72, v254, 18
	v_readlane_b32 s73, v254, 19
	v_readlane_b32 s74, v254, 20
	v_readlane_b32 s75, v254, 21
	v_readlane_b32 s76, v254, 22
	v_readlane_b32 s77, v254, 23
	v_readlane_b32 s78, v254, 24
	v_readlane_b32 s79, v254, 25
	s_or_b32 s44, s6, s0
	v_readlane_b32 s80, v254, 26
	v_readlane_b32 s81, v254, 27
	v_readlane_b32 s82, v254, 28
	v_readlane_b32 s83, v254, 29
	s_mov_b64 s[68:69], s[72:73]
	s_lshl_b64 s[0:1], s[44:45], 2
	s_mov_b64 s[70:71], s[74:75]
	s_add_u32 s0, s70, s0
	s_addc_u32 s1, s71, s1
	s_waitcnt vmcnt(0)
	s_barrier
	global_load_dword v128, v153, s[0:1]
	s_mov_b32 s7, 0x3f2aaaab
	s_mov_b32 s12, 0x3f317218
	s_mov_b32 s6, 0x7f800000
	s_mov_b32 s11, 0x33800000
	v_and_b32_e32 v131, 15, v130
	s_mov_b64 s[72:73], s[76:77]
	s_mov_b64 s[74:75], s[78:79]
	s_mov_b64 s[76:77], s[80:81]
	s_mov_b64 s[78:79], s[82:83]
	s_waitcnt vmcnt(0)
	v_mul_f32_e32 v129, 0xbfb8aa3b, v128
	v_fma_f32 v132, v128, s31, -v129
	v_rndne_f32_e32 v133, v129
	v_fmac_f32_e32 v132, 0xb2a5705f, v128
	v_sub_f32_e32 v129, v129, v133
	v_add_f32_e32 v129, v129, v132
	v_exp_f32_e32 v129, v129
	v_cvt_i32_f32_e32 v132, v133
	v_cmp_nlt_f32_e32 vcc, s34, v128
	v_ldexp_f32 v129, v129, v132
	s_nop 0
	v_cndmask_b32_e32 v129, 0, v129, vcc
	v_cmp_ngt_f32_e32 vcc, s35, v128
	s_nop 1
	v_cndmask_b32_e32 v146, v181, v129, vcc
	v_add_f32_e32 v132, 1.0, v146
	v_add_f32_e32 v128, -1.0, v132
	v_sub_f32_e32 v129, v128, v132
	v_add_f32_e32 v129, 1.0, v129
	v_sub_f32_e32 v128, v146, v128
	v_add_f32_e32 v133, v128, v129
	v_frexp_mant_f32_e32 v128, v132
	v_cmp_gt_f32_e32 vcc, s7, v128
	v_cvt_f64_f32_e32 v[128:129], v132
	v_frexp_exp_i32_f64_e32 v128, v[128:129]
	v_subbrev_co_u32_e32 v138, vcc, 0, v128, vcc
	v_sub_u32_e32 v128, 0, v138
	v_ldexp_f32 v129, v132, v128
	v_add_f32_e32 v132, -1.0, v129
	v_add_f32_e32 v134, 1.0, v129
	v_ldexp_f32 v128, v133, v128
	v_add_f32_e32 v133, 1.0, v132
	v_add_f32_e32 v135, -1.0, v134
	v_sub_f32_e32 v133, v129, v133
	v_sub_f32_e32 v129, v129, v135
	v_add_f32_e32 v133, v128, v133
	v_add_f32_e32 v128, v128, v129
	v_add_f32_e32 v139, v134, v128
	v_rcp_f32_e32 v141, v139
	v_sub_f32_e32 v129, v134, v139
	v_add_f32_e32 v140, v128, v129
	v_add_f32_e32 v129, v132, v133
	v_mul_f32_e32 v143, v129, v141
	v_sub_f32_e32 v128, v132, v129
	v_mul_f32_e32 v132, v139, v143
	v_fma_f32 v134, v143, v139, -v132
	v_fmac_f32_e32 v134, v143, v140
	v_add_f32_e32 v142, v133, v128
	v_add_f32_e32 v128, v132, v134
	v_sub_f32_e32 v133, v129, v128
	v_pk_add_f32 v[136:137], v[128:129], v[132:133] neg_lo:[0,1] neg_hi:[0,1]
	v_mov_b32_e32 v135, v128
	v_pk_add_f32 v[128:129], v[136:137], v[134:135] neg_lo:[0,1] neg_hi:[0,1]
	v_cmp_neq_f32_e32 vcc, s6, v146
	v_add_f32_e32 v129, v142, v129
	v_add_f32_e32 v128, v128, v129
	v_add_f32_e32 v129, v133, v128
	v_mul_f32_e32 v142, v141, v129
	v_mul_f32_e32 v132, v139, v142
	v_fma_f32 v134, v142, v139, -v132
	v_fmac_f32_e32 v134, v142, v140
	v_sub_f32_e32 v133, v133, v129
	v_add_f32_e32 v139, v128, v133
	v_add_f32_e32 v128, v132, v134
	v_sub_f32_e32 v133, v129, v128
	v_pk_add_f32 v[136:137], v[128:129], v[132:133] neg_lo:[0,1] neg_hi:[0,1]
	v_mov_b32_e32 v135, v128
	v_pk_add_f32 v[128:129], v[136:137], v[134:135] neg_lo:[0,1] neg_hi:[0,1]
	s_nop 0
	v_add_f32_e32 v129, v139, v129
	v_add_f32_e32 v128, v128, v129
	v_add_f32_e32 v129, v143, v142
	v_add_f32_e32 v128, v133, v128
	v_sub_f32_e32 v132, v129, v143
	v_mul_f32_e32 v128, v141, v128
	v_sub_f32_e32 v132, v142, v132
	v_add_f32_e32 v132, v132, v128
	v_add_f32_e32 v134, v129, v132
	v_mul_f32_e32 v135, v134, v134
	v_fmamk_f32 v128, v135, 0x3e9b6dac, v154
	v_fmaak_f32 v157, v135, v128, 0x3f2aaada
	v_cvt_f32_i32_e32 v128, v138
	v_sub_f32_e32 v129, v134, v129
	v_sub_f32_e32 v129, v132, v129
	v_ldexp_f32 v136, v129, 1
	v_mul_f32_e32 v129, v134, v135
	v_ldexp_f32 v133, v134, 1
	v_pk_mul_f32 v[134:135], v[128:129], v[156:157]
	s_nop 0
	v_fma_f32 v132, v128, s12, -v134
	v_fmac_f32_e32 v132, 0xb102e308, v128
	v_pk_add_f32 v[128:129], v[134:135], v[132:133]
	s_nop 0
	v_sub_f32_e32 v133, v129, v133
	v_sub_f32_e32 v133, v135, v133
	v_add_f32_e32 v137, v136, v133
	v_mov_b32_e32 v136, v134
	v_pk_add_f32 v[134:135], v[128:129], v[134:135] neg_lo:[0,1] neg_hi:[0,1]
	v_pk_add_f32 v[138:139], v[128:129], v[136:137]
	v_mov_b32_e32 v133, v128
	v_mov_b32_e32 v135, v139
	v_pk_add_f32 v[140:141], v[132:133], v[134:135] neg_lo:[0,1] neg_hi:[0,1]
	v_pk_add_f32 v[132:133], v[132:133], v[134:135]
	v_mov_b32_e32 v144, v129
	v_pk_add_f32 v[134:135], v[132:133], v[128:129] op_sel:[1,0] op_sel_hi:[0,1] neg_lo:[0,1] neg_hi:[0,1]
	v_pk_add_f32 v[142:143], v[138:139], v[134:135] op_sel_hi:[1,0] neg_lo:[0,1] neg_hi:[0,1]
	v_mov_b32_e32 v138, v139
	v_mov_b32_e32 v139, v133
	v_mov_b32_e32 v145, v134
	v_pk_add_f32 v[134:135], v[138:139], v[144:145] neg_lo:[0,1] neg_hi:[0,1]
	v_mov_b32_e32 v136, v137
	v_mov_b32_e32 v137, v128
	v_pk_add_f32 v[128:129], v[136:137], v[134:135] neg_lo:[0,1] neg_hi:[0,1]
	v_mov_b32_e32 v142, v140
	v_pk_add_f32 v[134:135], v[142:143], v[128:129]
	v_mov_b32_e32 v141, v133
	v_pk_add_f32 v[136:137], v[134:135], v[134:135] op_sel:[0,1] op_sel_hi:[1,0]
	s_nop 0
	v_pk_add_f32 v[132:133], v[132:133], v[136:137] op_sel:[1,0] op_sel_hi:[0,1]
	v_mov_b32_e32 v135, v132
	v_pk_add_f32 v[138:139], v[134:135], v[140:141] neg_lo:[0,1] neg_hi:[0,1]
	v_mov_b32_e32 v129, v136
	v_sub_f32_e32 v133, v134, v138
	v_pk_add_f32 v[128:129], v[128:129], v[138:139] neg_lo:[0,1] neg_hi:[0,1]
	v_sub_f32_e32 v133, v140, v133
	v_add_f32_e32 v128, v128, v133
	v_add_f32_e32 v128, v128, v129
	global_load_dword v129, v153, s[0:1] offset:16
	v_add_f32_e32 v128, v132, v128
	v_cndmask_b32_e32 v128, v181, v128, vcc
	v_cmp_lt_f32_e64 vcc, |v146|, s11
	s_movk_i32 s0, 0xffc0
	s_waitcnt vmcnt(0)
; DEV float logsig(float x) { return -log1pf(expf(-x)); }
; #define FOR_R _Pragma("unroll") for (int r = 0; r < 4; ++r)
; #define FOR_AI _Pragma("unroll") for (int ai = 0; ai < 2; ++ai)
; #define FOR_BJ _Pragma("unroll") for (int bj = 0; bj < 2; ++bj)
; #define FOR_M4 _Pragma("unroll") for (int m = 0; m < 4; ++m)
; #define FOR_NN _Pragma("unroll") for (int n = 0; n < 2; ++n)
; __device__ void job_scores_g(const P& p, int l, int job, HALF* sm) {
;     ...
;   const float lgf = logsig(p.decay[l * 8 + h]);
;   const float lgb = logsig(p.decay[l * 8 + 4 + h]);
;   FOR_AI FOR_BJ {
;     FOR_M4 FOR_NN {
;       const int j0 = ai * 128 + wr * 64 + m * 16 + fq * 4;
;       const int i = bj * 128 + wc * 32 + n * 16 + fr;
;       f4 o;
;       FOR_R {
;         const int j = j0 + r;
;         const float d = (j <= i) ? expf(lgf * (float)(i - j)) : expf(lgb * (float)(j - i));
;         o[r] = acc[ai][bj][m][n][r] * d;
;       }
;       stage2_T(sm, i, j0, to_h4(o));
;     }
	v_mul_f32_e32 v132, 0xbfb8aa3b, v129
	v_fma_f32 v133, v129, s31, -v132
	v_rndne_f32_e32 v134, v132
	v_fmac_f32_e32 v133, 0xb2a5705f, v129
	v_sub_f32_e32 v132, v132, v134
	v_add_f32_e32 v132, v132, v133
	v_exp_f32_e32 v132, v132
	v_cvt_i32_f32_e32 v133, v134
	v_cndmask_b32_e32 v128, v128, v146, vcc
	v_cmp_nlt_f32_e32 vcc, s34, v129
	v_ldexp_f32 v132, v132, v133
	s_nop 0
	v_cndmask_b32_e32 v132, 0, v132, vcc
	v_cmp_ngt_f32_e32 vcc, s35, v129
	s_nop 1
	v_cndmask_b32_e32 v129, v181, v132, vcc
	v_add_f32_e32 v134, 1.0, v129
	v_add_f32_e32 v132, -1.0, v134
	v_sub_f32_e32 v133, v132, v134
	v_add_f32_e32 v133, 1.0, v133
	v_sub_f32_e32 v132, v129, v132
	v_add_f32_e32 v135, v132, v133
	v_frexp_mant_f32_e32 v132, v134
	v_cmp_gt_f32_e32 vcc, s7, v132
	v_cvt_f64_f32_e32 v[132:133], v134
	v_frexp_exp_i32_f64_e32 v132, v[132:133]
	v_subbrev_co_u32_e32 v140, vcc, 0, v132, vcc
	v_sub_u32_e32 v132, 0, v140
	v_ldexp_f32 v133, v134, v132
	v_add_f32_e32 v134, -1.0, v133
	v_add_f32_e32 v136, 1.0, v133
	v_ldexp_f32 v132, v135, v132
	v_add_f32_e32 v135, 1.0, v134
	v_add_f32_e32 v137, -1.0, v136
	v_sub_f32_e32 v135, v133, v135
	v_sub_f32_e32 v133, v133, v137
	v_add_f32_e32 v135, v132, v135
	v_add_f32_e32 v132, v132, v133
	v_add_f32_e32 v141, v136, v132
	v_rcp_f32_e32 v143, v141
	v_sub_f32_e32 v133, v136, v141
	v_add_f32_e32 v142, v132, v133
	v_add_f32_e32 v133, v134, v135
	v_mul_f32_e32 v145, v133, v143
	v_sub_f32_e32 v132, v134, v133
	v_mul_f32_e32 v134, v141, v145
	v_fma_f32 v136, v145, v141, -v134
	v_fmac_f32_e32 v136, v145, v142
	v_add_f32_e32 v144, v135, v132
	v_add_f32_e32 v132, v134, v136
	v_sub_f32_e32 v135, v133, v132
	v_pk_add_f32 v[138:139], v[132:133], v[134:135] neg_lo:[0,1] neg_hi:[0,1]
	v_mov_b32_e32 v137, v132
	v_pk_add_f32 v[132:133], v[138:139], v[136:137] neg_lo:[0,1] neg_hi:[0,1]
	v_cmp_neq_f32_e32 vcc, s6, v129
	v_add_f32_e32 v133, v144, v133
	v_add_f32_e32 v132, v132, v133
	v_add_f32_e32 v133, v135, v132
	v_mul_f32_e32 v144, v143, v133
	v_mul_f32_e32 v134, v141, v144
	v_fma_f32 v136, v144, v141, -v134
	v_fmac_f32_e32 v136, v144, v142
	v_sub_f32_e32 v135, v135, v133
	v_add_f32_e32 v141, v132, v135
	v_add_f32_e32 v132, v134, v136
	v_sub_f32_e32 v135, v133, v132
	v_pk_add_f32 v[138:139], v[132:133], v[134:135] neg_lo:[0,1] neg_hi:[0,1]
	v_mov_b32_e32 v137, v132
	v_pk_add_f32 v[132:133], v[138:139], v[136:137] neg_lo:[0,1] neg_hi:[0,1]
	s_nop 0
	v_add_f32_e32 v133, v141, v133
	v_add_f32_e32 v132, v132, v133
	v_add_f32_e32 v133, v145, v144
	v_add_f32_e32 v132, v135, v132
	v_sub_f32_e32 v134, v133, v145
	v_mul_f32_e32 v132, v143, v132
	v_sub_f32_e32 v134, v144, v134
	v_add_f32_e32 v134, v134, v132
	v_add_f32_e32 v136, v133, v134
	v_mul_f32_e32 v137, v136, v136
	v_fmamk_f32 v132, v137, 0x3e9b6dac, v154
	v_fmaak_f32 v157, v137, v132, 0x3f2aaada
	v_cvt_f32_i32_e32 v132, v140
	v_sub_f32_e32 v133, v136, v133
	v_sub_f32_e32 v133, v134, v133
	v_ldexp_f32 v138, v133, 1
	v_mul_f32_e32 v133, v136, v137
	v_ldexp_f32 v135, v136, 1
	v_pk_mul_f32 v[136:137], v[132:133], v[156:157]
	s_nop 0
	v_fma_f32 v134, v132, s12, -v136
	v_fmac_f32_e32 v134, 0xb102e308, v132
	v_pk_add_f32 v[132:133], v[136:137], v[134:135]
	s_nop 0
	v_sub_f32_e32 v135, v133, v135
	v_sub_f32_e32 v135, v137, v135
	v_add_f32_e32 v139, v138, v135
	v_mov_b32_e32 v138, v136
	v_pk_add_f32 v[136:137], v[132:133], v[136:137] neg_lo:[0,1] neg_hi:[0,1]
	v_pk_add_f32 v[140:141], v[132:133], v[138:139]
	v_mov_b32_e32 v135, v132
	v_mov_b32_e32 v137, v141
	v_pk_add_f32 v[142:143], v[134:135], v[136:137] neg_lo:[0,1] neg_hi:[0,1]
	v_pk_add_f32 v[134:135], v[134:135], v[136:137]
	v_mov_b32_e32 v146, v133
	v_pk_add_f32 v[136:137], v[134:135], v[132:133] op_sel:[1,0] op_sel_hi:[0,1] neg_lo:[0,1] neg_hi:[0,1]
	v_pk_add_f32 v[144:145], v[140:141], v[136:137] op_sel_hi:[1,0] neg_lo:[0,1] neg_hi:[0,1]
	v_mov_b32_e32 v140, v141
	v_mov_b32_e32 v141, v135
	v_mov_b32_e32 v147, v136
	v_pk_add_f32 v[136:137], v[140:141], v[146:147] neg_lo:[0,1] neg_hi:[0,1]
	v_mov_b32_e32 v138, v139
	v_mov_b32_e32 v139, v132
	v_pk_add_f32 v[132:133], v[138:139], v[136:137] neg_lo:[0,1] neg_hi:[0,1]
	v_mov_b32_e32 v144, v142
	v_pk_add_f32 v[136:137], v[144:145], v[132:133]
	v_mov_b32_e32 v143, v135
	v_pk_add_f32 v[138:139], v[136:137], v[136:137] op_sel:[0,1] op_sel_hi:[1,0]
	s_nop 0
	v_pk_add_f32 v[134:135], v[134:135], v[138:139] op_sel:[1,0] op_sel_hi:[0,1]
	v_mov_b32_e32 v137, v134
	v_pk_add_f32 v[140:141], v[136:137], v[142:143] neg_lo:[0,1] neg_hi:[0,1]
	v_mov_b32_e32 v133, v138
	v_sub_f32_e32 v135, v136, v140
	v_pk_add_f32 v[132:133], v[132:133], v[140:141] neg_lo:[0,1] neg_hi:[0,1]
	v_sub_f32_e32 v135, v142, v135
	v_add_f32_e32 v132, v132, v135
	v_add_f32_e32 v132, v132, v133
	v_add_f32_e32 v132, v134, v132
	v_cndmask_b32_e32 v132, v181, v132, vcc
	v_cmp_lt_f32_e64 vcc, |v129|, s11
	v_lshrrev_b32_e32 v133, 2, v130
	v_and_b32_e32 v133, 12, v133
	v_cndmask_b32_e32 v129, v132, v129, vcc
	v_ashrrev_i32_e32 v132, 2, v130
	v_lshrrev_b32_e32 v133, 2, v130
	v_and_b32_e32 v133, 12, v133
	s_movk_i32 s0, 0xffc0
	v_and_or_b32 v133, v132, s0, v133
	v_lshrrev_b32_e32 v134, 1, v130
	v_and_b32_e32 v135, 15, v130
	s_movk_i32 s0, 0x60
	v_and_or_b32 v134, v134, s0, v135
	v_sub_u32_e32 v132, v134, v133
	v_cvt_f32_i32_e32 v132, v132
	v_lshlrev_b32_e32 v135, 1, v133
	v_mad_u32_u24 v150, v134, s64, v135
	v_add_u32_e32 v151, 0x10800, v150
	v_mov_b32_e32 v136, 0
	v_mov_b32_e32 v137, -1.0
	v_mov_b32_e32 v138, -2.0
	v_mov_b32_e32 v139, 0xc0400000
	v_xor_b32_e32 v140, 0x80000000, v128
	v_mov_b32_e32 v142, v129
	v_mov_b32_e32 v144, 0x3fb8aa3b
	v_mov_b32_e32 v146, 0x32a5705f
	v_add_f32_e32 v134, 0x00000000, v132
	v_pk_add_f32 v[206:207], v[134:135], v[136:137] op_sel_hi:[0,1]
; #define FOR_R _Pragma("unroll") for (int r = 0; r < 4; ++r)
; #define FOR_AI _Pragma("unroll") for (int ai = 0; ai < 2; ++ai)
; #define FOR_BJ _Pragma("unroll") for (int bj = 0; bj < 2; ++bj)
; #define FOR_M4 _Pragma("unroll") for (int m = 0; m < 4; ++m)
; #define FOR_NN _Pragma("unroll") for (int n = 0; n < 2; ++n)
; __device__ void job_scores_g(const P& p, int l, int job, HALF* sm) {
;     ...
;   FOR_AI FOR_BJ {
;     FOR_M4 FOR_NN {
;       const int j0 = ai * 128 + wr * 64 + m * 16 + fq * 4;
;       const int i = bj * 128 + wc * 32 + n * 16 + fr;
;       f4 o;
;       FOR_R {
;         const int j = j0 + r;
;         const float d = (j <= i) ? expf(lgf * (float)(i - j)) : expf(lgb * (float)(j - i));
;         o[r] = acc[ai][bj][m][n][r] * d;
;       }
;       stage2_T(sm, i, j0, to_h4(o));
;     }
	v_pk_add_f32 v[208:209], v[134:135], v[138:139] op_sel_hi:[0,1]
	v_pk_mul_f32 v[186:187], v[206:207], v[140:141] op_sel_hi:[1,0]
	v_pk_mul_f32 v[188:189], v[208:209], v[140:141] op_sel_hi:[1,0]
	v_pk_mul_f32 v[190:191], v[206:207], v[142:143] op_sel_hi:[1,0]
	v_pk_mul_f32 v[192:193], v[208:209], v[142:143] op_sel_hi:[1,0]
	v_min_f32_e32 v186, v186, v190
	v_min_f32_e32 v187, v187, v191
	v_min_f32_e32 v188, v188, v192
	v_min_f32_e32 v189, v189, v193
	v_pk_mul_f32 v[194:195], v[186:187], v[144:145] op_sel_hi:[1,0]
	v_pk_mul_f32 v[196:197], v[188:189], v[144:145] op_sel_hi:[1,0]
	v_rndne_f32_e32 v198, v194
	v_rndne_f32_e32 v199, v195
	v_rndne_f32_e32 v200, v196
	v_rndne_f32_e32 v201, v197
	v_pk_fma_f32 v[202:203], v[186:187], v[144:145], v[194:195] op_sel_hi:[1,0,1] neg_lo:[0,0,1] neg_hi:[0,0,1]
	v_pk_fma_f32 v[204:205], v[188:189], v[144:145], v[196:197] op_sel_hi:[1,0,1] neg_lo:[0,0,1] neg_hi:[0,0,1]
	v_pk_add_f32 v[194:195], v[194:195], v[198:199] neg_lo:[0,1] neg_hi:[0,1]
	v_pk_add_f32 v[196:197], v[196:197], v[200:201] neg_lo:[0,1] neg_hi:[0,1]
	v_pk_fma_f32 v[202:203], v[186:187], v[146:147], v[202:203] op_sel_hi:[1,0,1]
	v_pk_fma_f32 v[204:205], v[188:189], v[146:147], v[204:205] op_sel_hi:[1,0,1]
	v_pk_add_f32 v[194:195], v[194:195], v[202:203]
	v_pk_add_f32 v[196:197], v[196:197], v[204:205]
	v_exp_f32_e32 v194, v194
	v_exp_f32_e32 v195, v195
	v_exp_f32_e32 v196, v196
	v_exp_f32_e32 v197, v197
	v_cvt_i32_f32_e32 v198, v198
	v_cvt_i32_f32_e32 v199, v199
	v_cvt_i32_f32_e32 v200, v200
	v_cvt_i32_f32_e32 v201, v201
	v_ldexp_f32 v194, v194, v198
	v_ldexp_f32 v195, v195, v199
	v_ldexp_f32 v196, v196, v200
	v_ldexp_f32 v197, v197, v201
	v_pk_mul_f32 v[194:195], v[124:125], v[194:195]
	v_pk_mul_f32 v[196:197], v[126:127], v[196:197]
	v_cvt_pk_f16_f32 v148, v194, v195
	v_cvt_pk_f16_f32 v149, v196, v197
	ds_write_b64 v150, v[148:149]
	v_add_f32_e32 v134, 0x41800000, v132
	v_pk_add_f32 v[206:207], v[134:135], v[136:137] op_sel_hi:[0,1]
	v_pk_add_f32 v[208:209], v[134:135], v[138:139] op_sel_hi:[0,1]
	v_pk_mul_f32 v[186:187], v[206:207], v[140:141] op_sel_hi:[1,0]
	v_pk_mul_f32 v[188:189], v[208:209], v[140:141] op_sel_hi:[1,0]
	v_pk_mul_f32 v[190:191], v[206:207], v[142:143] op_sel_hi:[1,0]
	v_pk_mul_f32 v[192:193], v[208:209], v[142:143] op_sel_hi:[1,0]
	v_min_f32_e32 v186, v186, v190
	v_min_f32_e32 v187, v187, v191
	v_min_f32_e32 v188, v188, v192
	v_min_f32_e32 v189, v189, v193
	v_pk_mul_f32 v[194:195], v[186:187], v[144:145] op_sel_hi:[1,0]
	v_pk_mul_f32 v[196:197], v[188:189], v[144:145] op_sel_hi:[1,0]
	v_rndne_f32_e32 v198, v194
	v_rndne_f32_e32 v199, v195
	v_rndne_f32_e32 v200, v196
	v_rndne_f32_e32 v201, v197
	v_pk_fma_f32 v[202:203], v[186:187], v[144:145], v[194:195] op_sel_hi:[1,0,1] neg_lo:[0,0,1] neg_hi:[0,0,1]
	v_pk_fma_f32 v[204:205], v[188:189], v[144:145], v[196:197] op_sel_hi:[1,0,1] neg_lo:[0,0,1] neg_hi:[0,0,1]
	v_pk_add_f32 v[194:195], v[194:195], v[198:199] neg_lo:[0,1] neg_hi:[0,1]
	v_pk_add_f32 v[196:197], v[196:197], v[200:201] neg_lo:[0,1] neg_hi:[0,1]
	v_pk_fma_f32 v[202:203], v[186:187], v[146:147], v[202:203] op_sel_hi:[1,0,1]
	v_pk_fma_f32 v[204:205], v[188:189], v[146:147], v[204:205] op_sel_hi:[1,0,1]
	v_pk_add_f32 v[194:195], v[194:195], v[202:203]
	v_pk_add_f32 v[196:197], v[196:197], v[204:205]
	v_exp_f32_e32 v194, v194
	v_exp_f32_e32 v195, v195
	v_exp_f32_e32 v196, v196
	v_exp_f32_e32 v197, v197
	v_cvt_i32_f32_e32 v198, v198
	v_cvt_i32_f32_e32 v199, v199
	v_cvt_i32_f32_e32 v200, v200
	v_cvt_i32_f32_e32 v201, v201
	v_ldexp_f32 v194, v194, v198
	v_ldexp_f32 v195, v195, v199
	v_ldexp_f32 v196, v196, v200
	v_ldexp_f32 v197, v197, v201
	v_pk_mul_f32 v[194:195], v[120:121], v[194:195]
	v_pk_mul_f32 v[196:197], v[122:123], v[196:197]
	v_cvt_pk_f16_f32 v148, v194, v195
	v_cvt_pk_f16_f32 v149, v196, v197
	ds_write_b64 v150, v[148:149] offset:8448
	v_add_f32_e32 v134, 0xc1800000, v132
	v_pk_add_f32 v[206:207], v[134:135], v[136:137] op_sel_hi:[0,1]
	v_pk_add_f32 v[208:209], v[134:135], v[138:139] op_sel_hi:[0,1]
	v_pk_mul_f32 v[186:187], v[206:207], v[140:141] op_sel_hi:[1,0]
	v_pk_mul_f32 v[188:189], v[208:209], v[140:141] op_sel_hi:[1,0]
	v_pk_mul_f32 v[190:191], v[206:207], v[142:143] op_sel_hi:[1,0]
	v_pk_mul_f32 v[192:193], v[208:209], v[142:143] op_sel_hi:[1,0]
	v_min_f32_e32 v186, v186, v190
	v_min_f32_e32 v187, v187, v191
	v_min_f32_e32 v188, v188, v192
	v_min_f32_e32 v189, v189, v193
	v_pk_mul_f32 v[194:195], v[186:187], v[144:145] op_sel_hi:[1,0]
	v_pk_mul_f32 v[196:197], v[188:189], v[144:145] op_sel_hi:[1,0]
	v_rndne_f32_e32 v198, v194
	v_rndne_f32_e32 v199, v195
	v_rndne_f32_e32 v200, v196
	v_rndne_f32_e32 v201, v197
	v_pk_fma_f32 v[202:203], v[186:187], v[144:145], v[194:195] op_sel_hi:[1,0,1] neg_lo:[0,0,1] neg_hi:[0,0,1]
	v_pk_fma_f32 v[204:205], v[188:189], v[144:145], v[196:197] op_sel_hi:[1,0,1] neg_lo:[0,0,1] neg_hi:[0,0,1]
	v_pk_add_f32 v[194:195], v[194:195], v[198:199] neg_lo:[0,1] neg_hi:[0,1]
	v_pk_add_f32 v[196:197], v[196:197], v[200:201] neg_lo:[0,1] neg_hi:[0,1]
	v_pk_fma_f32 v[202:203], v[186:187], v[146:147], v[202:203] op_sel_hi:[1,0,1]
	v_pk_fma_f32 v[204:205], v[188:189], v[146:147], v[204:205] op_sel_hi:[1,0,1]
	v_pk_add_f32 v[194:195], v[194:195], v[202:203]
	v_pk_add_f32 v[196:197], v[196:197], v[204:205]
	v_exp_f32_e32 v194, v194
	v_exp_f32_e32 v195, v195
	v_exp_f32_e32 v196, v196
	v_exp_f32_e32 v197, v197
	v_cvt_i32_f32_e32 v198, v198
	v_cvt_i32_f32_e32 v199, v199
	v_cvt_i32_f32_e32 v200, v200
	v_cvt_i32_f32_e32 v201, v201
	v_ldexp_f32 v194, v194, v198
	v_ldexp_f32 v195, v195, v199
	v_ldexp_f32 v196, v196, v200
	v_ldexp_f32 v197, v197, v201
	v_pk_mul_f32 v[194:195], v[116:117], v[194:195]
; #define FOR_R _Pragma("unroll") for (int r = 0; r < 4; ++r)
; #define FOR_AI _Pragma("unroll") for (int ai = 0; ai < 2; ++ai)
; #define FOR_BJ _Pragma("unroll") for (int bj = 0; bj < 2; ++bj)
; #define FOR_M4 _Pragma("unroll") for (int m = 0; m < 4; ++m)
; #define FOR_NN _Pragma("unroll") for (int n = 0; n < 2; ++n)
; __device__ void job_scores_g(const P& p, int l, int job, HALF* sm) {
;     ...
;   FOR_AI FOR_BJ {
;     FOR_M4 FOR_NN {
;       const int j0 = ai * 128 + wr * 64 + m * 16 + fq * 4;
;       const int i = bj * 128 + wc * 32 + n * 16 + fr;
;       f4 o;
;       FOR_R {
;         const int j = j0 + r;
;         const float d = (j <= i) ? expf(lgf * (float)(i - j)) : expf(lgb * (float)(j - i));
;         o[r] = acc[ai][bj][m][n][r] * d;
;       }
;       stage2_T(sm, i, j0, to_h4(o));
;     }
	v_pk_mul_f32 v[196:197], v[118:119], v[196:197]
	v_cvt_pk_f16_f32 v148, v194, v195
	v_cvt_pk_f16_f32 v149, v196, v197
	ds_write_b64 v150, v[148:149] offset:32
	v_add_f32_e32 v134, 0x00000000, v132
	v_pk_add_f32 v[206:207], v[134:135], v[136:137] op_sel_hi:[0,1]
	v_pk_add_f32 v[208:209], v[134:135], v[138:139] op_sel_hi:[0,1]
	v_pk_mul_f32 v[186:187], v[206:207], v[140:141] op_sel_hi:[1,0]
	v_pk_mul_f32 v[188:189], v[208:209], v[140:141] op_sel_hi:[1,0]
	v_pk_mul_f32 v[190:191], v[206:207], v[142:143] op_sel_hi:[1,0]
	v_pk_mul_f32 v[192:193], v[208:209], v[142:143] op_sel_hi:[1,0]
	v_min_f32_e32 v186, v186, v190
	v_min_f32_e32 v187, v187, v191
	v_min_f32_e32 v188, v188, v192
	v_min_f32_e32 v189, v189, v193
	v_pk_mul_f32 v[194:195], v[186:187], v[144:145] op_sel_hi:[1,0]
	v_pk_mul_f32 v[196:197], v[188:189], v[144:145] op_sel_hi:[1,0]
	v_rndne_f32_e32 v198, v194
	v_rndne_f32_e32 v199, v195
	v_rndne_f32_e32 v200, v196
	v_rndne_f32_e32 v201, v197
	v_pk_fma_f32 v[202:203], v[186:187], v[144:145], v[194:195] op_sel_hi:[1,0,1] neg_lo:[0,0,1] neg_hi:[0,0,1]
	v_pk_fma_f32 v[204:205], v[188:189], v[144:145], v[196:197] op_sel_hi:[1,0,1] neg_lo:[0,0,1] neg_hi:[0,0,1]
	v_pk_add_f32 v[194:195], v[194:195], v[198:199] neg_lo:[0,1] neg_hi:[0,1]
	v_pk_add_f32 v[196:197], v[196:197], v[200:201] neg_lo:[0,1] neg_hi:[0,1]
	v_pk_fma_f32 v[202:203], v[186:187], v[146:147], v[202:203] op_sel_hi:[1,0,1]
	v_pk_fma_f32 v[204:205], v[188:189], v[146:147], v[204:205] op_sel_hi:[1,0,1]
	v_pk_add_f32 v[194:195], v[194:195], v[202:203]
	v_pk_add_f32 v[196:197], v[196:197], v[204:205]
	v_exp_f32_e32 v194, v194
	v_exp_f32_e32 v195, v195
	v_exp_f32_e32 v196, v196
	v_exp_f32_e32 v197, v197
	v_cvt_i32_f32_e32 v198, v198
	v_cvt_i32_f32_e32 v199, v199
	v_cvt_i32_f32_e32 v200, v200
	v_cvt_i32_f32_e32 v201, v201
	v_ldexp_f32 v194, v194, v198
	v_ldexp_f32 v195, v195, v199
	v_ldexp_f32 v196, v196, v200
	v_ldexp_f32 v197, v197, v201
	v_pk_mul_f32 v[194:195], v[112:113], v[194:195]
	v_pk_mul_f32 v[196:197], v[114:115], v[196:197]
	v_cvt_pk_f16_f32 v148, v194, v195
	v_cvt_pk_f16_f32 v149, v196, v197
	ds_write_b64 v150, v[148:149] offset:8480
	v_add_f32_e32 v134, 0xc2000000, v132
	v_pk_add_f32 v[206:207], v[134:135], v[136:137] op_sel_hi:[0,1]
	v_pk_add_f32 v[208:209], v[134:135], v[138:139] op_sel_hi:[0,1]
	v_pk_mul_f32 v[186:187], v[206:207], v[140:141] op_sel_hi:[1,0]
	v_pk_mul_f32 v[188:189], v[208:209], v[140:141] op_sel_hi:[1,0]
	v_pk_mul_f32 v[190:191], v[206:207], v[142:143] op_sel_hi:[1,0]
	v_pk_mul_f32 v[192:193], v[208:209], v[142:143] op_sel_hi:[1,0]
	v_min_f32_e32 v186, v186, v190
	v_min_f32_e32 v187, v187, v191
	v_min_f32_e32 v188, v188, v192
	v_min_f32_e32 v189, v189, v193
	v_pk_mul_f32 v[194:195], v[186:187], v[144:145] op_sel_hi:[1,0]
	v_pk_mul_f32 v[196:197], v[188:189], v[144:145] op_sel_hi:[1,0]
	v_rndne_f32_e32 v198, v194
	v_rndne_f32_e32 v199, v195
	v_rndne_f32_e32 v200, v196
	v_rndne_f32_e32 v201, v197
	v_pk_fma_f32 v[202:203], v[186:187], v[144:145], v[194:195] op_sel_hi:[1,0,1] neg_lo:[0,0,1] neg_hi:[0,0,1]
	v_pk_fma_f32 v[204:205], v[188:189], v[144:145], v[196:197] op_sel_hi:[1,0,1] neg_lo:[0,0,1] neg_hi:[0,0,1]
	v_pk_add_f32 v[194:195], v[194:195], v[198:199] neg_lo:[0,1] neg_hi:[0,1]
	v_pk_add_f32 v[196:197], v[196:197], v[200:201] neg_lo:[0,1] neg_hi:[0,1]
	v_pk_fma_f32 v[202:203], v[186:187], v[146:147], v[202:203] op_sel_hi:[1,0,1]
	v_pk_fma_f32 v[204:205], v[188:189], v[146:147], v[204:205] op_sel_hi:[1,0,1]
	v_pk_add_f32 v[194:195], v[194:195], v[202:203]
	v_pk_add_f32 v[196:197], v[196:197], v[204:205]
	v_exp_f32_e32 v194, v194
	v_exp_f32_e32 v195, v195
	v_exp_f32_e32 v196, v196
	v_exp_f32_e32 v197, v197
	v_cvt_i32_f32_e32 v198, v198
	v_cvt_i32_f32_e32 v199, v199
	v_cvt_i32_f32_e32 v200, v200
	v_cvt_i32_f32_e32 v201, v201
	v_ldexp_f32 v194, v194, v198
	v_ldexp_f32 v195, v195, v199
	v_ldexp_f32 v196, v196, v200
	v_ldexp_f32 v197, v197, v201
	v_pk_mul_f32 v[194:195], v[108:109], v[194:195]
	v_pk_mul_f32 v[196:197], v[110:111], v[196:197]
	v_cvt_pk_f16_f32 v148, v194, v195
	v_cvt_pk_f16_f32 v149, v196, v197
	ds_write_b64 v150, v[148:149] offset:64
	v_add_f32_e32 v134, 0xc1800000, v132
	v_pk_add_f32 v[206:207], v[134:135], v[136:137] op_sel_hi:[0,1]
	v_pk_add_f32 v[208:209], v[134:135], v[138:139] op_sel_hi:[0,1]
	v_pk_mul_f32 v[186:187], v[206:207], v[140:141] op_sel_hi:[1,0]
	v_pk_mul_f32 v[188:189], v[208:209], v[140:141] op_sel_hi:[1,0]
	v_pk_mul_f32 v[190:191], v[206:207], v[142:143] op_sel_hi:[1,0]
	v_pk_mul_f32 v[192:193], v[208:209], v[142:143] op_sel_hi:[1,0]
	v_min_f32_e32 v186, v186, v190
	v_min_f32_e32 v187, v187, v191
	v_min_f32_e32 v188, v188, v192
	v_min_f32_e32 v189, v189, v193
	v_pk_mul_f32 v[194:195], v[186:187], v[144:145] op_sel_hi:[1,0]
	v_pk_mul_f32 v[196:197], v[188:189], v[144:145] op_sel_hi:[1,0]
	v_rndne_f32_e32 v198, v194
	v_rndne_f32_e32 v199, v195
	v_rndne_f32_e32 v200, v196
	v_rndne_f32_e32 v201, v197
	v_pk_fma_f32 v[202:203], v[186:187], v[144:145], v[194:195] op_sel_hi:[1,0,1] neg_lo:[0,0,1] neg_hi:[0,0,1]
	v_pk_fma_f32 v[204:205], v[188:189], v[144:145], v[196:197] op_sel_hi:[1,0,1] neg_lo:[0,0,1] neg_hi:[0,0,1]
	v_pk_add_f32 v[194:195], v[194:195], v[198:199] neg_lo:[0,1] neg_hi:[0,1]
	v_pk_add_f32 v[196:197], v[196:197], v[200:201] neg_lo:[0,1] neg_hi:[0,1]
	v_pk_fma_f32 v[202:203], v[186:187], v[146:147], v[202:203] op_sel_hi:[1,0,1]
	v_pk_fma_f32 v[204:205], v[188:189], v[146:147], v[204:205] op_sel_hi:[1,0,1]
	v_pk_add_f32 v[194:195], v[194:195], v[202:203]
	v_pk_add_f32 v[196:197], v[196:197], v[204:205]
	v_exp_f32_e32 v194, v194
	v_exp_f32_e32 v195, v195
	v_exp_f32_e32 v196, v196
	v_exp_f32_e32 v197, v197
; #define FOR_R _Pragma("unroll") for (int r = 0; r < 4; ++r)
; #define FOR_AI _Pragma("unroll") for (int ai = 0; ai < 2; ++ai)
; #define FOR_BJ _Pragma("unroll") for (int bj = 0; bj < 2; ++bj)
; #define FOR_M4 _Pragma("unroll") for (int m = 0; m < 4; ++m)
; #define FOR_NN _Pragma("unroll") for (int n = 0; n < 2; ++n)
; __device__ void job_scores_g(const P& p, int l, int job, HALF* sm) {
;     ...
;   FOR_AI FOR_BJ {
;     FOR_M4 FOR_NN {
;       const int j0 = ai * 128 + wr * 64 + m * 16 + fq * 4;
;       const int i = bj * 128 + wc * 32 + n * 16 + fr;
;       f4 o;
;       FOR_R {
;         const int j = j0 + r;
;         const float d = (j <= i) ? expf(lgf * (float)(i - j)) : expf(lgb * (float)(j - i));
;         o[r] = acc[ai][bj][m][n][r] * d;
;       }
;       stage2_T(sm, i, j0, to_h4(o));
;     }
	v_cvt_i32_f32_e32 v198, v198
	v_cvt_i32_f32_e32 v199, v199
	v_cvt_i32_f32_e32 v200, v200
	v_cvt_i32_f32_e32 v201, v201
	v_ldexp_f32 v194, v194, v198
	v_ldexp_f32 v195, v195, v199
	v_ldexp_f32 v196, v196, v200
	v_ldexp_f32 v197, v197, v201
	v_pk_mul_f32 v[194:195], v[104:105], v[194:195]
	v_pk_mul_f32 v[196:197], v[106:107], v[196:197]
	v_cvt_pk_f16_f32 v148, v194, v195
	v_cvt_pk_f16_f32 v149, v196, v197
	ds_write_b64 v150, v[148:149] offset:8512
	v_add_f32_e32 v134, 0xc2400000, v132
	v_pk_add_f32 v[206:207], v[134:135], v[136:137] op_sel_hi:[0,1]
	v_pk_add_f32 v[208:209], v[134:135], v[138:139] op_sel_hi:[0,1]
	v_pk_mul_f32 v[186:187], v[206:207], v[140:141] op_sel_hi:[1,0]
	v_pk_mul_f32 v[188:189], v[208:209], v[140:141] op_sel_hi:[1,0]
	v_pk_mul_f32 v[190:191], v[206:207], v[142:143] op_sel_hi:[1,0]
	v_pk_mul_f32 v[192:193], v[208:209], v[142:143] op_sel_hi:[1,0]
	v_min_f32_e32 v186, v186, v190
	v_min_f32_e32 v187, v187, v191
	v_min_f32_e32 v188, v188, v192
	v_min_f32_e32 v189, v189, v193
	v_pk_mul_f32 v[194:195], v[186:187], v[144:145] op_sel_hi:[1,0]
	v_pk_mul_f32 v[196:197], v[188:189], v[144:145] op_sel_hi:[1,0]
	v_rndne_f32_e32 v198, v194
	v_rndne_f32_e32 v199, v195
	v_rndne_f32_e32 v200, v196
	v_rndne_f32_e32 v201, v197
	v_pk_fma_f32 v[202:203], v[186:187], v[144:145], v[194:195] op_sel_hi:[1,0,1] neg_lo:[0,0,1] neg_hi:[0,0,1]
	v_pk_fma_f32 v[204:205], v[188:189], v[144:145], v[196:197] op_sel_hi:[1,0,1] neg_lo:[0,0,1] neg_hi:[0,0,1]
	v_pk_add_f32 v[194:195], v[194:195], v[198:199] neg_lo:[0,1] neg_hi:[0,1]
	v_pk_add_f32 v[196:197], v[196:197], v[200:201] neg_lo:[0,1] neg_hi:[0,1]
	v_pk_fma_f32 v[202:203], v[186:187], v[146:147], v[202:203] op_sel_hi:[1,0,1]
	v_pk_fma_f32 v[204:205], v[188:189], v[146:147], v[204:205] op_sel_hi:[1,0,1]
	v_pk_add_f32 v[194:195], v[194:195], v[202:203]
	v_pk_add_f32 v[196:197], v[196:197], v[204:205]
	v_exp_f32_e32 v194, v194
	v_exp_f32_e32 v195, v195
	v_exp_f32_e32 v196, v196
	v_exp_f32_e32 v197, v197
	v_cvt_i32_f32_e32 v198, v198
	v_cvt_i32_f32_e32 v199, v199
	v_cvt_i32_f32_e32 v200, v200
	v_cvt_i32_f32_e32 v201, v201
	v_ldexp_f32 v194, v194, v198
	v_ldexp_f32 v195, v195, v199
	v_ldexp_f32 v196, v196, v200
	v_ldexp_f32 v197, v197, v201
	v_pk_mul_f32 v[194:195], v[100:101], v[194:195]
	v_pk_mul_f32 v[196:197], v[102:103], v[196:197]
	v_cvt_pk_f16_f32 v148, v194, v195
	v_cvt_pk_f16_f32 v149, v196, v197
	ds_write_b64 v150, v[148:149] offset:96
	v_add_f32_e32 v134, 0xc2000000, v132
	v_pk_add_f32 v[206:207], v[134:135], v[136:137] op_sel_hi:[0,1]
	v_pk_add_f32 v[208:209], v[134:135], v[138:139] op_sel_hi:[0,1]
	v_pk_mul_f32 v[186:187], v[206:207], v[140:141] op_sel_hi:[1,0]
	v_pk_mul_f32 v[188:189], v[208:209], v[140:141] op_sel_hi:[1,0]
	v_pk_mul_f32 v[190:191], v[206:207], v[142:143] op_sel_hi:[1,0]
	v_pk_mul_f32 v[192:193], v[208:209], v[142:143] op_sel_hi:[1,0]
	v_min_f32_e32 v186, v186, v190
	v_min_f32_e32 v187, v187, v191
	v_min_f32_e32 v188, v188, v192
	v_min_f32_e32 v189, v189, v193
	v_pk_mul_f32 v[194:195], v[186:187], v[144:145] op_sel_hi:[1,0]
	v_pk_mul_f32 v[196:197], v[188:189], v[144:145] op_sel_hi:[1,0]
	v_rndne_f32_e32 v198, v194
	v_rndne_f32_e32 v199, v195
	v_rndne_f32_e32 v200, v196
	v_rndne_f32_e32 v201, v197
	v_pk_fma_f32 v[202:203], v[186:187], v[144:145], v[194:195] op_sel_hi:[1,0,1] neg_lo:[0,0,1] neg_hi:[0,0,1]
	v_pk_fma_f32 v[204:205], v[188:189], v[144:145], v[196:197] op_sel_hi:[1,0,1] neg_lo:[0,0,1] neg_hi:[0,0,1]
	v_pk_add_f32 v[194:195], v[194:195], v[198:199] neg_lo:[0,1] neg_hi:[0,1]
	v_pk_add_f32 v[196:197], v[196:197], v[200:201] neg_lo:[0,1] neg_hi:[0,1]
	v_pk_fma_f32 v[202:203], v[186:187], v[146:147], v[202:203] op_sel_hi:[1,0,1]
	v_pk_fma_f32 v[204:205], v[188:189], v[146:147], v[204:205] op_sel_hi:[1,0,1]
	v_pk_add_f32 v[194:195], v[194:195], v[202:203]
	v_pk_add_f32 v[196:197], v[196:197], v[204:205]
	v_exp_f32_e32 v194, v194
	v_exp_f32_e32 v195, v195
	v_exp_f32_e32 v196, v196
	v_exp_f32_e32 v197, v197
	v_cvt_i32_f32_e32 v198, v198
	v_cvt_i32_f32_e32 v199, v199
	v_cvt_i32_f32_e32 v200, v200
	v_cvt_i32_f32_e32 v201, v201
	v_ldexp_f32 v194, v194, v198
	v_ldexp_f32 v195, v195, v199
	v_ldexp_f32 v196, v196, v200
	v_ldexp_f32 v197, v197, v201
	v_pk_mul_f32 v[194:195], v[96:97], v[194:195]
	v_pk_mul_f32 v[196:197], v[98:99], v[196:197]
	v_cvt_pk_f16_f32 v148, v194, v195
	v_cvt_pk_f16_f32 v149, v196, v197
	ds_write_b64 v150, v[148:149] offset:8544
	v_add_f32_e32 v134, 0x43000000, v132
	v_pk_add_f32 v[206:207], v[134:135], v[136:137] op_sel_hi:[0,1]
	v_pk_add_f32 v[208:209], v[134:135], v[138:139] op_sel_hi:[0,1]
	v_pk_mul_f32 v[186:187], v[206:207], v[140:141] op_sel_hi:[1,0]
	v_pk_mul_f32 v[188:189], v[208:209], v[140:141] op_sel_hi:[1,0]
	v_pk_mul_f32 v[190:191], v[206:207], v[142:143] op_sel_hi:[1,0]
	v_pk_mul_f32 v[192:193], v[208:209], v[142:143] op_sel_hi:[1,0]
	v_min_f32_e32 v186, v186, v190
	v_min_f32_e32 v187, v187, v191
	v_min_f32_e32 v188, v188, v192
	v_min_f32_e32 v189, v189, v193
	v_pk_mul_f32 v[194:195], v[186:187], v[144:145] op_sel_hi:[1,0]
	v_pk_mul_f32 v[196:197], v[188:189], v[144:145] op_sel_hi:[1,0]
	v_rndne_f32_e32 v198, v194
	v_rndne_f32_e32 v199, v195
	v_rndne_f32_e32 v200, v196
	v_rndne_f32_e32 v201, v197
	v_pk_fma_f32 v[202:203], v[186:187], v[144:145], v[194:195] op_sel_hi:[1,0,1] neg_lo:[0,0,1] neg_hi:[0,0,1]
	v_pk_fma_f32 v[204:205], v[188:189], v[144:145], v[196:197] op_sel_hi:[1,0,1] neg_lo:[0,0,1] neg_hi:[0,0,1]
	v_pk_add_f32 v[194:195], v[194:195], v[198:199] neg_lo:[0,1] neg_hi:[0,1]
	v_pk_add_f32 v[196:197], v[196:197], v[200:201] neg_lo:[0,1] neg_hi:[0,1]
	v_pk_fma_f32 v[202:203], v[186:187], v[146:147], v[202:203] op_sel_hi:[1,0,1]
; #define FOR_R _Pragma("unroll") for (int r = 0; r < 4; ++r)
; #define FOR_AI _Pragma("unroll") for (int ai = 0; ai < 2; ++ai)
; #define FOR_BJ _Pragma("unroll") for (int bj = 0; bj < 2; ++bj)
; #define FOR_M4 _Pragma("unroll") for (int m = 0; m < 4; ++m)
; #define FOR_NN _Pragma("unroll") for (int n = 0; n < 2; ++n)
; __device__ void job_scores_g(const P& p, int l, int job, HALF* sm) {
;     ...
;   FOR_AI FOR_BJ {
;     FOR_M4 FOR_NN {
;       const int j0 = ai * 128 + wr * 64 + m * 16 + fq * 4;
;       const int i = bj * 128 + wc * 32 + n * 16 + fr;
;       f4 o;
;       FOR_R {
;         const int j = j0 + r;
;         const float d = (j <= i) ? expf(lgf * (float)(i - j)) : expf(lgb * (float)(j - i));
;         o[r] = acc[ai][bj][m][n][r] * d;
;       }
;       stage2_T(sm, i, j0, to_h4(o));
;     }
	v_pk_fma_f32 v[204:205], v[188:189], v[146:147], v[204:205] op_sel_hi:[1,0,1]
	v_pk_add_f32 v[194:195], v[194:195], v[202:203]
	v_pk_add_f32 v[196:197], v[196:197], v[204:205]
	v_exp_f32_e32 v194, v194
	v_exp_f32_e32 v195, v195
	v_exp_f32_e32 v196, v196
	v_exp_f32_e32 v197, v197
	v_cvt_i32_f32_e32 v198, v198
	v_cvt_i32_f32_e32 v199, v199
	v_cvt_i32_f32_e32 v200, v200
	v_cvt_i32_f32_e32 v201, v201
	v_ldexp_f32 v194, v194, v198
	v_ldexp_f32 v195, v195, v199
	v_ldexp_f32 v196, v196, v200
	v_ldexp_f32 v197, v197, v201
	v_pk_mul_f32 v[194:195], v[92:93], v[194:195]
	v_pk_mul_f32 v[196:197], v[94:95], v[196:197]
	v_cvt_pk_f16_f32 v148, v194, v195
	v_cvt_pk_f16_f32 v149, v196, v197
	ds_write_b64 v151, v[148:149]
	v_add_f32_e32 v134, 0x43100000, v132
	v_pk_add_f32 v[206:207], v[134:135], v[136:137] op_sel_hi:[0,1]
	v_pk_add_f32 v[208:209], v[134:135], v[138:139] op_sel_hi:[0,1]
	v_pk_mul_f32 v[186:187], v[206:207], v[140:141] op_sel_hi:[1,0]
	v_pk_mul_f32 v[188:189], v[208:209], v[140:141] op_sel_hi:[1,0]
	v_pk_mul_f32 v[190:191], v[206:207], v[142:143] op_sel_hi:[1,0]
	v_pk_mul_f32 v[192:193], v[208:209], v[142:143] op_sel_hi:[1,0]
	v_min_f32_e32 v186, v186, v190
	v_min_f32_e32 v187, v187, v191
	v_min_f32_e32 v188, v188, v192
	v_min_f32_e32 v189, v189, v193
	v_pk_mul_f32 v[194:195], v[186:187], v[144:145] op_sel_hi:[1,0]
	v_pk_mul_f32 v[196:197], v[188:189], v[144:145] op_sel_hi:[1,0]
	v_rndne_f32_e32 v198, v194
	v_rndne_f32_e32 v199, v195
	v_rndne_f32_e32 v200, v196
	v_rndne_f32_e32 v201, v197
	v_pk_fma_f32 v[202:203], v[186:187], v[144:145], v[194:195] op_sel_hi:[1,0,1] neg_lo:[0,0,1] neg_hi:[0,0,1]
	v_pk_fma_f32 v[204:205], v[188:189], v[144:145], v[196:197] op_sel_hi:[1,0,1] neg_lo:[0,0,1] neg_hi:[0,0,1]
	v_pk_add_f32 v[194:195], v[194:195], v[198:199] neg_lo:[0,1] neg_hi:[0,1]
	v_pk_add_f32 v[196:197], v[196:197], v[200:201] neg_lo:[0,1] neg_hi:[0,1]
	v_pk_fma_f32 v[202:203], v[186:187], v[146:147], v[202:203] op_sel_hi:[1,0,1]
	v_pk_fma_f32 v[204:205], v[188:189], v[146:147], v[204:205] op_sel_hi:[1,0,1]
	v_pk_add_f32 v[194:195], v[194:195], v[202:203]
	v_pk_add_f32 v[196:197], v[196:197], v[204:205]
	v_exp_f32_e32 v194, v194
	v_exp_f32_e32 v195, v195
	v_exp_f32_e32 v196, v196
	v_exp_f32_e32 v197, v197
	v_cvt_i32_f32_e32 v198, v198
	v_cvt_i32_f32_e32 v199, v199
	v_cvt_i32_f32_e32 v200, v200
	v_cvt_i32_f32_e32 v201, v201
	v_ldexp_f32 v194, v194, v198
	v_ldexp_f32 v195, v195, v199
	v_ldexp_f32 v196, v196, v200
	v_ldexp_f32 v197, v197, v201
	v_pk_mul_f32 v[194:195], v[88:89], v[194:195]
	v_pk_mul_f32 v[196:197], v[90:91], v[196:197]
	v_cvt_pk_f16_f32 v148, v194, v195
	v_cvt_pk_f16_f32 v149, v196, v197
	ds_write_b64 v151, v[148:149] offset:8448
	v_add_f32_e32 v134, 0x42e00000, v132
	v_pk_add_f32 v[206:207], v[134:135], v[136:137] op_sel_hi:[0,1]
	v_pk_add_f32 v[208:209], v[134:135], v[138:139] op_sel_hi:[0,1]
	v_pk_mul_f32 v[186:187], v[206:207], v[140:141] op_sel_hi:[1,0]
	v_pk_mul_f32 v[188:189], v[208:209], v[140:141] op_sel_hi:[1,0]
	v_pk_mul_f32 v[190:191], v[206:207], v[142:143] op_sel_hi:[1,0]
	v_pk_mul_f32 v[192:193], v[208:209], v[142:143] op_sel_hi:[1,0]
	v_min_f32_e32 v186, v186, v190
	v_min_f32_e32 v187, v187, v191
	v_min_f32_e32 v188, v188, v192
	v_min_f32_e32 v189, v189, v193
	v_pk_mul_f32 v[194:195], v[186:187], v[144:145] op_sel_hi:[1,0]
	v_pk_mul_f32 v[196:197], v[188:189], v[144:145] op_sel_hi:[1,0]
	v_rndne_f32_e32 v198, v194
	v_rndne_f32_e32 v199, v195
	v_rndne_f32_e32 v200, v196
	v_rndne_f32_e32 v201, v197
	v_pk_fma_f32 v[202:203], v[186:187], v[144:145], v[194:195] op_sel_hi:[1,0,1] neg_lo:[0,0,1] neg_hi:[0,0,1]
	v_pk_fma_f32 v[204:205], v[188:189], v[144:145], v[196:197] op_sel_hi:[1,0,1] neg_lo:[0,0,1] neg_hi:[0,0,1]
	v_pk_add_f32 v[194:195], v[194:195], v[198:199] neg_lo:[0,1] neg_hi:[0,1]
	v_pk_add_f32 v[196:197], v[196:197], v[200:201] neg_lo:[0,1] neg_hi:[0,1]
	v_pk_fma_f32 v[202:203], v[186:187], v[146:147], v[202:203] op_sel_hi:[1,0,1]
	v_pk_fma_f32 v[204:205], v[188:189], v[146:147], v[204:205] op_sel_hi:[1,0,1]
	v_pk_add_f32 v[194:195], v[194:195], v[202:203]
	v_pk_add_f32 v[196:197], v[196:197], v[204:205]
	v_exp_f32_e32 v194, v194
	v_exp_f32_e32 v195, v195
	v_exp_f32_e32 v196, v196
	v_exp_f32_e32 v197, v197
	v_cvt_i32_f32_e32 v198, v198
	v_cvt_i32_f32_e32 v199, v199
	v_cvt_i32_f32_e32 v200, v200
	v_cvt_i32_f32_e32 v201, v201
	v_ldexp_f32 v194, v194, v198
	v_ldexp_f32 v195, v195, v199
	v_ldexp_f32 v196, v196, v200
	v_ldexp_f32 v197, v197, v201
	v_pk_mul_f32 v[194:195], v[84:85], v[194:195]
	v_pk_mul_f32 v[196:197], v[86:87], v[196:197]
	v_cvt_pk_f16_f32 v148, v194, v195
	v_cvt_pk_f16_f32 v149, v196, v197
	ds_write_b64 v151, v[148:149] offset:32
	v_add_f32_e32 v134, 0x43000000, v132
	v_pk_add_f32 v[206:207], v[134:135], v[136:137] op_sel_hi:[0,1]
	v_pk_add_f32 v[208:209], v[134:135], v[138:139] op_sel_hi:[0,1]
	v_pk_mul_f32 v[186:187], v[206:207], v[140:141] op_sel_hi:[1,0]
	v_pk_mul_f32 v[188:189], v[208:209], v[140:141] op_sel_hi:[1,0]
	v_pk_mul_f32 v[190:191], v[206:207], v[142:143] op_sel_hi:[1,0]
	v_pk_mul_f32 v[192:193], v[208:209], v[142:143] op_sel_hi:[1,0]
	v_min_f32_e32 v186, v186, v190
	v_min_f32_e32 v187, v187, v191
	v_min_f32_e32 v188, v188, v192
	v_min_f32_e32 v189, v189, v193
	v_pk_mul_f32 v[194:195], v[186:187], v[144:145] op_sel_hi:[1,0]
	v_pk_mul_f32 v[196:197], v[188:189], v[144:145] op_sel_hi:[1,0]
	v_rndne_f32_e32 v198, v194
	v_rndne_f32_e32 v199, v195
	v_rndne_f32_e32 v200, v196
	v_rndne_f32_e32 v201, v197
	v_pk_fma_f32 v[202:203], v[186:187], v[144:145], v[194:195] op_sel_hi:[1,0,1] neg_lo:[0,0,1] neg_hi:[0,0,1]
	v_pk_fma_f32 v[204:205], v[188:189], v[144:145], v[196:197] op_sel_hi:[1,0,1] neg_lo:[0,0,1] neg_hi:[0,0,1]
; #define FOR_R _Pragma("unroll") for (int r = 0; r < 4; ++r)
; #define FOR_AI _Pragma("unroll") for (int ai = 0; ai < 2; ++ai)
; #define FOR_BJ _Pragma("unroll") for (int bj = 0; bj < 2; ++bj)
; #define FOR_M4 _Pragma("unroll") for (int m = 0; m < 4; ++m)
; #define FOR_NN _Pragma("unroll") for (int n = 0; n < 2; ++n)
; __device__ void job_scores_g(const P& p, int l, int job, HALF* sm) {
;     ...
;   FOR_AI FOR_BJ {
;     FOR_M4 FOR_NN {
;       const int j0 = ai * 128 + wr * 64 + m * 16 + fq * 4;
;       const int i = bj * 128 + wc * 32 + n * 16 + fr;
;       f4 o;
;       FOR_R {
;         const int j = j0 + r;
;         const float d = (j <= i) ? expf(lgf * (float)(i - j)) : expf(lgb * (float)(j - i));
;         o[r] = acc[ai][bj][m][n][r] * d;
;       }
;       stage2_T(sm, i, j0, to_h4(o));
;     }
	v_pk_add_f32 v[194:195], v[194:195], v[198:199] neg_lo:[0,1] neg_hi:[0,1]
	v_pk_add_f32 v[196:197], v[196:197], v[200:201] neg_lo:[0,1] neg_hi:[0,1]
	v_pk_fma_f32 v[202:203], v[186:187], v[146:147], v[202:203] op_sel_hi:[1,0,1]
	v_pk_fma_f32 v[204:205], v[188:189], v[146:147], v[204:205] op_sel_hi:[1,0,1]
	v_pk_add_f32 v[194:195], v[194:195], v[202:203]
	v_pk_add_f32 v[196:197], v[196:197], v[204:205]
	v_exp_f32_e32 v194, v194
	v_exp_f32_e32 v195, v195
	v_exp_f32_e32 v196, v196
	v_exp_f32_e32 v197, v197
	v_cvt_i32_f32_e32 v198, v198
	v_cvt_i32_f32_e32 v199, v199
	v_cvt_i32_f32_e32 v200, v200
	v_cvt_i32_f32_e32 v201, v201
	v_ldexp_f32 v194, v194, v198
	v_ldexp_f32 v195, v195, v199
	v_ldexp_f32 v196, v196, v200
	v_ldexp_f32 v197, v197, v201
	v_pk_mul_f32 v[194:195], v[80:81], v[194:195]
	v_pk_mul_f32 v[196:197], v[82:83], v[196:197]
	v_cvt_pk_f16_f32 v148, v194, v195
	v_cvt_pk_f16_f32 v149, v196, v197
	ds_write_b64 v151, v[148:149] offset:8480
	v_add_f32_e32 v134, 0x42c00000, v132
	v_pk_add_f32 v[206:207], v[134:135], v[136:137] op_sel_hi:[0,1]
	v_pk_add_f32 v[208:209], v[134:135], v[138:139] op_sel_hi:[0,1]
	v_pk_mul_f32 v[186:187], v[206:207], v[140:141] op_sel_hi:[1,0]
	v_pk_mul_f32 v[188:189], v[208:209], v[140:141] op_sel_hi:[1,0]
	v_pk_mul_f32 v[190:191], v[206:207], v[142:143] op_sel_hi:[1,0]
	v_pk_mul_f32 v[192:193], v[208:209], v[142:143] op_sel_hi:[1,0]
	v_min_f32_e32 v186, v186, v190
	v_min_f32_e32 v187, v187, v191
	v_min_f32_e32 v188, v188, v192
	v_min_f32_e32 v189, v189, v193
	v_pk_mul_f32 v[194:195], v[186:187], v[144:145] op_sel_hi:[1,0]
	v_pk_mul_f32 v[196:197], v[188:189], v[144:145] op_sel_hi:[1,0]
	v_rndne_f32_e32 v198, v194
	v_rndne_f32_e32 v199, v195
	v_rndne_f32_e32 v200, v196
	v_rndne_f32_e32 v201, v197
	v_pk_fma_f32 v[202:203], v[186:187], v[144:145], v[194:195] op_sel_hi:[1,0,1] neg_lo:[0,0,1] neg_hi:[0,0,1]
	v_pk_fma_f32 v[204:205], v[188:189], v[144:145], v[196:197] op_sel_hi:[1,0,1] neg_lo:[0,0,1] neg_hi:[0,0,1]
	v_pk_add_f32 v[194:195], v[194:195], v[198:199] neg_lo:[0,1] neg_hi:[0,1]
	v_pk_add_f32 v[196:197], v[196:197], v[200:201] neg_lo:[0,1] neg_hi:[0,1]
	v_pk_fma_f32 v[202:203], v[186:187], v[146:147], v[202:203] op_sel_hi:[1,0,1]
	v_pk_fma_f32 v[204:205], v[188:189], v[146:147], v[204:205] op_sel_hi:[1,0,1]
	v_pk_add_f32 v[194:195], v[194:195], v[202:203]
	v_pk_add_f32 v[196:197], v[196:197], v[204:205]
	v_exp_f32_e32 v194, v194
	v_exp_f32_e32 v195, v195
	v_exp_f32_e32 v196, v196
	v_exp_f32_e32 v197, v197
	v_cvt_i32_f32_e32 v198, v198
	v_cvt_i32_f32_e32 v199, v199
	v_cvt_i32_f32_e32 v200, v200
	v_cvt_i32_f32_e32 v201, v201
	v_ldexp_f32 v194, v194, v198
	v_ldexp_f32 v195, v195, v199
	v_ldexp_f32 v196, v196, v200
	v_ldexp_f32 v197, v197, v201
	v_pk_mul_f32 v[194:195], v[76:77], v[194:195]
	v_pk_mul_f32 v[196:197], v[78:79], v[196:197]
	v_cvt_pk_f16_f32 v148, v194, v195
	v_cvt_pk_f16_f32 v149, v196, v197
	ds_write_b64 v151, v[148:149] offset:64
	v_add_f32_e32 v134, 0x42e00000, v132
	v_pk_add_f32 v[206:207], v[134:135], v[136:137] op_sel_hi:[0,1]
	v_pk_add_f32 v[208:209], v[134:135], v[138:139] op_sel_hi:[0,1]
	v_pk_mul_f32 v[186:187], v[206:207], v[140:141] op_sel_hi:[1,0]
	v_pk_mul_f32 v[188:189], v[208:209], v[140:141] op_sel_hi:[1,0]
	v_pk_mul_f32 v[190:191], v[206:207], v[142:143] op_sel_hi:[1,0]
	v_pk_mul_f32 v[192:193], v[208:209], v[142:143] op_sel_hi:[1,0]
	v_min_f32_e32 v186, v186, v190
	v_min_f32_e32 v187, v187, v191
	v_min_f32_e32 v188, v188, v192
	v_min_f32_e32 v189, v189, v193
	v_pk_mul_f32 v[194:195], v[186:187], v[144:145] op_sel_hi:[1,0]
	v_pk_mul_f32 v[196:197], v[188:189], v[144:145] op_sel_hi:[1,0]
	v_rndne_f32_e32 v198, v194
	v_rndne_f32_e32 v199, v195
	v_rndne_f32_e32 v200, v196
	v_rndne_f32_e32 v201, v197
	v_pk_fma_f32 v[202:203], v[186:187], v[144:145], v[194:195] op_sel_hi:[1,0,1] neg_lo:[0,0,1] neg_hi:[0,0,1]
	v_pk_fma_f32 v[204:205], v[188:189], v[144:145], v[196:197] op_sel_hi:[1,0,1] neg_lo:[0,0,1] neg_hi:[0,0,1]
	v_pk_add_f32 v[194:195], v[194:195], v[198:199] neg_lo:[0,1] neg_hi:[0,1]
	v_pk_add_f32 v[196:197], v[196:197], v[200:201] neg_lo:[0,1] neg_hi:[0,1]
	v_pk_fma_f32 v[202:203], v[186:187], v[146:147], v[202:203] op_sel_hi:[1,0,1]
	v_pk_fma_f32 v[204:205], v[188:189], v[146:147], v[204:205] op_sel_hi:[1,0,1]
	v_pk_add_f32 v[194:195], v[194:195], v[202:203]
	v_pk_add_f32 v[196:197], v[196:197], v[204:205]
	v_exp_f32_e32 v194, v194
	v_exp_f32_e32 v195, v195
	v_exp_f32_e32 v196, v196
	v_exp_f32_e32 v197, v197
	v_cvt_i32_f32_e32 v198, v198
	v_cvt_i32_f32_e32 v199, v199
	v_cvt_i32_f32_e32 v200, v200
	v_cvt_i32_f32_e32 v201, v201
	v_ldexp_f32 v194, v194, v198
	v_ldexp_f32 v195, v195, v199
	v_ldexp_f32 v196, v196, v200
	v_ldexp_f32 v197, v197, v201
	v_pk_mul_f32 v[194:195], v[72:73], v[194:195]
	v_pk_mul_f32 v[196:197], v[74:75], v[196:197]
	v_cvt_pk_f16_f32 v148, v194, v195
	v_cvt_pk_f16_f32 v149, v196, v197
	ds_write_b64 v151, v[148:149] offset:8512
	v_add_f32_e32 v134, 0x42a00000, v132
	v_pk_add_f32 v[206:207], v[134:135], v[136:137] op_sel_hi:[0,1]
	v_pk_add_f32 v[208:209], v[134:135], v[138:139] op_sel_hi:[0,1]
	v_pk_mul_f32 v[186:187], v[206:207], v[140:141] op_sel_hi:[1,0]
	v_pk_mul_f32 v[188:189], v[208:209], v[140:141] op_sel_hi:[1,0]
	v_pk_mul_f32 v[190:191], v[206:207], v[142:143] op_sel_hi:[1,0]
	v_pk_mul_f32 v[192:193], v[208:209], v[142:143] op_sel_hi:[1,0]
	v_min_f32_e32 v186, v186, v190
	v_min_f32_e32 v187, v187, v191
	v_min_f32_e32 v188, v188, v192
	v_min_f32_e32 v189, v189, v193
	v_pk_mul_f32 v[194:195], v[186:187], v[144:145] op_sel_hi:[1,0]
	v_pk_mul_f32 v[196:197], v[188:189], v[144:145] op_sel_hi:[1,0]
	v_rndne_f32_e32 v198, v194
	v_rndne_f32_e32 v199, v195
; #define FOR_R _Pragma("unroll") for (int r = 0; r < 4; ++r)
; #define FOR_AI _Pragma("unroll") for (int ai = 0; ai < 2; ++ai)
; #define FOR_BJ _Pragma("unroll") for (int bj = 0; bj < 2; ++bj)
; #define FOR_M4 _Pragma("unroll") for (int m = 0; m < 4; ++m)
; #define FOR_NN _Pragma("unroll") for (int n = 0; n < 2; ++n)
; __device__ void job_scores_g(const P& p, int l, int job, HALF* sm) {
;     ...
;   FOR_AI FOR_BJ {
;     FOR_M4 FOR_NN {
;       const int j0 = ai * 128 + wr * 64 + m * 16 + fq * 4;
;       const int i = bj * 128 + wc * 32 + n * 16 + fr;
;       f4 o;
;       FOR_R {
;         const int j = j0 + r;
;         const float d = (j <= i) ? expf(lgf * (float)(i - j)) : expf(lgb * (float)(j - i));
;         o[r] = acc[ai][bj][m][n][r] * d;
;       }
;       stage2_T(sm, i, j0, to_h4(o));
;     }
	v_rndne_f32_e32 v200, v196
	v_rndne_f32_e32 v201, v197
	v_pk_fma_f32 v[202:203], v[186:187], v[144:145], v[194:195] op_sel_hi:[1,0,1] neg_lo:[0,0,1] neg_hi:[0,0,1]
	v_pk_fma_f32 v[204:205], v[188:189], v[144:145], v[196:197] op_sel_hi:[1,0,1] neg_lo:[0,0,1] neg_hi:[0,0,1]
	v_pk_add_f32 v[194:195], v[194:195], v[198:199] neg_lo:[0,1] neg_hi:[0,1]
	v_pk_add_f32 v[196:197], v[196:197], v[200:201] neg_lo:[0,1] neg_hi:[0,1]
	v_pk_fma_f32 v[202:203], v[186:187], v[146:147], v[202:203] op_sel_hi:[1,0,1]
	v_pk_fma_f32 v[204:205], v[188:189], v[146:147], v[204:205] op_sel_hi:[1,0,1]
	v_pk_add_f32 v[194:195], v[194:195], v[202:203]
	v_pk_add_f32 v[196:197], v[196:197], v[204:205]
	v_exp_f32_e32 v194, v194
	v_exp_f32_e32 v195, v195
	v_exp_f32_e32 v196, v196
	v_exp_f32_e32 v197, v197
	v_cvt_i32_f32_e32 v198, v198
	v_cvt_i32_f32_e32 v199, v199
	v_cvt_i32_f32_e32 v200, v200
	v_cvt_i32_f32_e32 v201, v201
	v_ldexp_f32 v194, v194, v198
	v_ldexp_f32 v195, v195, v199
	v_ldexp_f32 v196, v196, v200
	v_ldexp_f32 v197, v197, v201
	v_pk_mul_f32 v[194:195], v[68:69], v[194:195]
	v_pk_mul_f32 v[196:197], v[70:71], v[196:197]
	v_cvt_pk_f16_f32 v148, v194, v195
	v_cvt_pk_f16_f32 v149, v196, v197
	ds_write_b64 v151, v[148:149] offset:96
	v_add_f32_e32 v134, 0x42c00000, v132
	v_pk_add_f32 v[206:207], v[134:135], v[136:137] op_sel_hi:[0,1]
	v_pk_add_f32 v[208:209], v[134:135], v[138:139] op_sel_hi:[0,1]
	v_pk_mul_f32 v[186:187], v[206:207], v[140:141] op_sel_hi:[1,0]
	v_pk_mul_f32 v[188:189], v[208:209], v[140:141] op_sel_hi:[1,0]
	v_pk_mul_f32 v[190:191], v[206:207], v[142:143] op_sel_hi:[1,0]
	v_pk_mul_f32 v[192:193], v[208:209], v[142:143] op_sel_hi:[1,0]
	v_min_f32_e32 v186, v186, v190
	v_min_f32_e32 v187, v187, v191
	v_min_f32_e32 v188, v188, v192
	v_min_f32_e32 v189, v189, v193
	v_pk_mul_f32 v[194:195], v[186:187], v[144:145] op_sel_hi:[1,0]
	v_pk_mul_f32 v[196:197], v[188:189], v[144:145] op_sel_hi:[1,0]
	v_rndne_f32_e32 v198, v194
	v_rndne_f32_e32 v199, v195
	v_rndne_f32_e32 v200, v196
	v_rndne_f32_e32 v201, v197
	v_pk_fma_f32 v[202:203], v[186:187], v[144:145], v[194:195] op_sel_hi:[1,0,1] neg_lo:[0,0,1] neg_hi:[0,0,1]
	v_pk_fma_f32 v[204:205], v[188:189], v[144:145], v[196:197] op_sel_hi:[1,0,1] neg_lo:[0,0,1] neg_hi:[0,0,1]
	v_pk_add_f32 v[194:195], v[194:195], v[198:199] neg_lo:[0,1] neg_hi:[0,1]
	v_pk_add_f32 v[196:197], v[196:197], v[200:201] neg_lo:[0,1] neg_hi:[0,1]
	v_pk_fma_f32 v[202:203], v[186:187], v[146:147], v[202:203] op_sel_hi:[1,0,1]
	v_pk_fma_f32 v[204:205], v[188:189], v[146:147], v[204:205] op_sel_hi:[1,0,1]
	v_pk_add_f32 v[194:195], v[194:195], v[202:203]
	v_pk_add_f32 v[196:197], v[196:197], v[204:205]
	v_exp_f32_e32 v194, v194
	v_exp_f32_e32 v195, v195
	v_exp_f32_e32 v196, v196
	v_exp_f32_e32 v197, v197
	v_cvt_i32_f32_e32 v198, v198
	v_cvt_i32_f32_e32 v199, v199
	v_cvt_i32_f32_e32 v200, v200
	v_cvt_i32_f32_e32 v201, v201
	v_ldexp_f32 v194, v194, v198
	v_ldexp_f32 v195, v195, v199
	v_ldexp_f32 v196, v196, v200
	v_ldexp_f32 v197, v197, v201
	v_pk_mul_f32 v[194:195], v[64:65], v[194:195]
	v_pk_mul_f32 v[196:197], v[66:67], v[196:197]
	v_cvt_pk_f16_f32 v148, v194, v195
	v_cvt_pk_f16_f32 v149, v196, v197
	ds_write_b64 v151, v[148:149] offset:8544
	v_add_f32_e32 v134, 0xc3000000, v132
	v_pk_add_f32 v[206:207], v[134:135], v[136:137] op_sel_hi:[0,1]
	v_pk_add_f32 v[208:209], v[134:135], v[138:139] op_sel_hi:[0,1]
	v_pk_mul_f32 v[186:187], v[206:207], v[140:141] op_sel_hi:[1,0]
	v_pk_mul_f32 v[188:189], v[208:209], v[140:141] op_sel_hi:[1,0]
	v_pk_mul_f32 v[190:191], v[206:207], v[142:143] op_sel_hi:[1,0]
	v_pk_mul_f32 v[192:193], v[208:209], v[142:143] op_sel_hi:[1,0]
	v_min_f32_e32 v186, v186, v190
	v_min_f32_e32 v187, v187, v191
	v_min_f32_e32 v188, v188, v192
	v_min_f32_e32 v189, v189, v193
	v_pk_mul_f32 v[194:195], v[186:187], v[144:145] op_sel_hi:[1,0]
	v_pk_mul_f32 v[196:197], v[188:189], v[144:145] op_sel_hi:[1,0]
	v_rndne_f32_e32 v198, v194
	v_rndne_f32_e32 v199, v195
	v_rndne_f32_e32 v200, v196
	v_rndne_f32_e32 v201, v197
	v_pk_fma_f32 v[202:203], v[186:187], v[144:145], v[194:195] op_sel_hi:[1,0,1] neg_lo:[0,0,1] neg_hi:[0,0,1]
	v_pk_fma_f32 v[204:205], v[188:189], v[144:145], v[196:197] op_sel_hi:[1,0,1] neg_lo:[0,0,1] neg_hi:[0,0,1]
	v_pk_add_f32 v[194:195], v[194:195], v[198:199] neg_lo:[0,1] neg_hi:[0,1]
	v_pk_add_f32 v[196:197], v[196:197], v[200:201] neg_lo:[0,1] neg_hi:[0,1]
	v_pk_fma_f32 v[202:203], v[186:187], v[146:147], v[202:203] op_sel_hi:[1,0,1]
	v_pk_fma_f32 v[204:205], v[188:189], v[146:147], v[204:205] op_sel_hi:[1,0,1]
	v_pk_add_f32 v[194:195], v[194:195], v[202:203]
	v_pk_add_f32 v[196:197], v[196:197], v[204:205]
	v_exp_f32_e32 v194, v194
	v_exp_f32_e32 v195, v195
	v_exp_f32_e32 v196, v196
	v_exp_f32_e32 v197, v197
	v_cvt_i32_f32_e32 v198, v198
	v_cvt_i32_f32_e32 v199, v199
	v_cvt_i32_f32_e32 v200, v200
	v_cvt_i32_f32_e32 v201, v201
	v_ldexp_f32 v194, v194, v198
	v_ldexp_f32 v195, v195, v199
	v_ldexp_f32 v196, v196, v200
	v_ldexp_f32 v197, v197, v201
	v_pk_mul_f32 v[194:195], v[60:61], v[194:195]
	v_pk_mul_f32 v[196:197], v[62:63], v[196:197]
	v_cvt_pk_f16_f32 v148, v194, v195
	v_cvt_pk_f16_f32 v149, v196, v197
	ds_write_b64 v150, v[148:149] offset:256
	v_add_f32_e32 v134, 0xc2e00000, v132
	v_pk_add_f32 v[206:207], v[134:135], v[136:137] op_sel_hi:[0,1]
	v_pk_add_f32 v[208:209], v[134:135], v[138:139] op_sel_hi:[0,1]
	v_pk_mul_f32 v[186:187], v[206:207], v[140:141] op_sel_hi:[1,0]
	v_pk_mul_f32 v[188:189], v[208:209], v[140:141] op_sel_hi:[1,0]
	v_pk_mul_f32 v[190:191], v[206:207], v[142:143] op_sel_hi:[1,0]
	v_pk_mul_f32 v[192:193], v[208:209], v[142:143] op_sel_hi:[1,0]
	v_min_f32_e32 v186, v186, v190
; #define FOR_R _Pragma("unroll") for (int r = 0; r < 4; ++r)
; #define FOR_AI _Pragma("unroll") for (int ai = 0; ai < 2; ++ai)
; #define FOR_BJ _Pragma("unroll") for (int bj = 0; bj < 2; ++bj)
; #define FOR_M4 _Pragma("unroll") for (int m = 0; m < 4; ++m)
; #define FOR_NN _Pragma("unroll") for (int n = 0; n < 2; ++n)
; __device__ void job_scores_g(const P& p, int l, int job, HALF* sm) {
;     ...
;   FOR_AI FOR_BJ {
;     FOR_M4 FOR_NN {
;       const int j0 = ai * 128 + wr * 64 + m * 16 + fq * 4;
;       const int i = bj * 128 + wc * 32 + n * 16 + fr;
;       f4 o;
;       FOR_R {
;         const int j = j0 + r;
;         const float d = (j <= i) ? expf(lgf * (float)(i - j)) : expf(lgb * (float)(j - i));
;         o[r] = acc[ai][bj][m][n][r] * d;
;       }
;       stage2_T(sm, i, j0, to_h4(o));
;     }
;     __builtin_amdgcn_sched_barrier(0);
;   }
	v_min_f32_e32 v187, v187, v191
	v_min_f32_e32 v188, v188, v192
	v_min_f32_e32 v189, v189, v193
	v_pk_mul_f32 v[194:195], v[186:187], v[144:145] op_sel_hi:[1,0]
	v_pk_mul_f32 v[196:197], v[188:189], v[144:145] op_sel_hi:[1,0]
	v_rndne_f32_e32 v198, v194
	v_rndne_f32_e32 v199, v195
	v_rndne_f32_e32 v200, v196
	v_rndne_f32_e32 v201, v197
	v_pk_fma_f32 v[202:203], v[186:187], v[144:145], v[194:195] op_sel_hi:[1,0,1] neg_lo:[0,0,1] neg_hi:[0,0,1]
	v_pk_fma_f32 v[204:205], v[188:189], v[144:145], v[196:197] op_sel_hi:[1,0,1] neg_lo:[0,0,1] neg_hi:[0,0,1]
	v_pk_add_f32 v[194:195], v[194:195], v[198:199] neg_lo:[0,1] neg_hi:[0,1]
	v_pk_add_f32 v[196:197], v[196:197], v[200:201] neg_lo:[0,1] neg_hi:[0,1]
	v_pk_fma_f32 v[202:203], v[186:187], v[146:147], v[202:203] op_sel_hi:[1,0,1]
	v_pk_fma_f32 v[204:205], v[188:189], v[146:147], v[204:205] op_sel_hi:[1,0,1]
	v_pk_add_f32 v[194:195], v[194:195], v[202:203]
	v_pk_add_f32 v[196:197], v[196:197], v[204:205]
	v_exp_f32_e32 v194, v194
	v_exp_f32_e32 v195, v195
	v_exp_f32_e32 v196, v196
	v_exp_f32_e32 v197, v197
	v_cvt_i32_f32_e32 v198, v198
	v_cvt_i32_f32_e32 v199, v199
	v_cvt_i32_f32_e32 v200, v200
	v_cvt_i32_f32_e32 v201, v201
	v_ldexp_f32 v194, v194, v198
	v_ldexp_f32 v195, v195, v199
	v_ldexp_f32 v196, v196, v200
	v_ldexp_f32 v197, v197, v201
	v_pk_mul_f32 v[194:195], v[56:57], v[194:195]
	v_pk_mul_f32 v[196:197], v[58:59], v[196:197]
	v_cvt_pk_f16_f32 v148, v194, v195
	v_cvt_pk_f16_f32 v149, v196, v197
	ds_write_b64 v150, v[148:149] offset:8704
	v_add_f32_e32 v134, 0xc3100000, v132
	v_pk_add_f32 v[206:207], v[134:135], v[136:137] op_sel_hi:[0,1]
	v_pk_add_f32 v[208:209], v[134:135], v[138:139] op_sel_hi:[0,1]
	v_pk_mul_f32 v[186:187], v[206:207], v[140:141] op_sel_hi:[1,0]
	v_pk_mul_f32 v[188:189], v[208:209], v[140:141] op_sel_hi:[1,0]
	v_pk_mul_f32 v[190:191], v[206:207], v[142:143] op_sel_hi:[1,0]
	v_pk_mul_f32 v[192:193], v[208:209], v[142:143] op_sel_hi:[1,0]
	v_min_f32_e32 v186, v186, v190
	v_min_f32_e32 v187, v187, v191
	v_min_f32_e32 v188, v188, v192
	v_min_f32_e32 v189, v189, v193
	v_pk_mul_f32 v[194:195], v[186:187], v[144:145] op_sel_hi:[1,0]
	v_pk_mul_f32 v[196:197], v[188:189], v[144:145] op_sel_hi:[1,0]
	v_rndne_f32_e32 v198, v194
	v_rndne_f32_e32 v199, v195
	v_rndne_f32_e32 v200, v196
	v_rndne_f32_e32 v201, v197
	v_pk_fma_f32 v[202:203], v[186:187], v[144:145], v[194:195] op_sel_hi:[1,0,1] neg_lo:[0,0,1] neg_hi:[0,0,1]
	v_pk_fma_f32 v[204:205], v[188:189], v[144:145], v[196:197] op_sel_hi:[1,0,1] neg_lo:[0,0,1] neg_hi:[0,0,1]
	v_pk_add_f32 v[194:195], v[194:195], v[198:199] neg_lo:[0,1] neg_hi:[0,1]
	v_pk_add_f32 v[196:197], v[196:197], v[200:201] neg_lo:[0,1] neg_hi:[0,1]
	v_pk_fma_f32 v[202:203], v[186:187], v[146:147], v[202:203] op_sel_hi:[1,0,1]
	v_pk_fma_f32 v[204:205], v[188:189], v[146:147], v[204:205] op_sel_hi:[1,0,1]
	v_pk_add_f32 v[194:195], v[194:195], v[202:203]
	v_pk_add_f32 v[196:197], v[196:197], v[204:205]
	v_exp_f32_e32 v194, v194
	v_exp_f32_e32 v195, v195
	v_exp_f32_e32 v196, v196
	v_exp_f32_e32 v197, v197
	v_cvt_i32_f32_e32 v198, v198
	v_cvt_i32_f32_e32 v199, v199
	v_cvt_i32_f32_e32 v200, v200
	v_cvt_i32_f32_e32 v201, v201
	v_ldexp_f32 v194, v194, v198
	v_ldexp_f32 v195, v195, v199
	v_ldexp_f32 v196, v196, v200
	v_ldexp_f32 v197, v197, v201
	v_pk_mul_f32 v[194:195], v[52:53], v[194:195]
	v_pk_mul_f32 v[196:197], v[54:55], v[196:197]
	v_cvt_pk_f16_f32 v148, v194, v195
	v_cvt_pk_f16_f32 v149, v196, v197
	ds_write_b64 v150, v[148:149] offset:288
	v_add_f32_e32 v134, 0xc3000000, v132
	v_pk_add_f32 v[206:207], v[134:135], v[136:137] op_sel_hi:[0,1]
	v_pk_add_f32 v[208:209], v[134:135], v[138:139] op_sel_hi:[0,1]
	v_pk_mul_f32 v[186:187], v[206:207], v[140:141] op_sel_hi:[1,0]
	v_pk_mul_f32 v[188:189], v[208:209], v[140:141] op_sel_hi:[1,0]
	v_pk_mul_f32 v[190:191], v[206:207], v[142:143] op_sel_hi:[1,0]
	v_pk_mul_f32 v[192:193], v[208:209], v[142:143] op_sel_hi:[1,0]
	v_min_f32_e32 v186, v186, v190
	v_min_f32_e32 v187, v187, v191
	v_min_f32_e32 v188, v188, v192
	v_min_f32_e32 v189, v189, v193
	v_pk_mul_f32 v[194:195], v[186:187], v[144:145] op_sel_hi:[1,0]
	v_pk_mul_f32 v[196:197], v[188:189], v[144:145] op_sel_hi:[1,0]
	v_rndne_f32_e32 v198, v194
	v_rndne_f32_e32 v199, v195
	v_rndne_f32_e32 v200, v196
	v_rndne_f32_e32 v201, v197
	v_pk_fma_f32 v[202:203], v[186:187], v[144:145], v[194:195] op_sel_hi:[1,0,1] neg_lo:[0,0,1] neg_hi:[0,0,1]
	v_pk_fma_f32 v[204:205], v[188:189], v[144:145], v[196:197] op_sel_hi:[1,0,1] neg_lo:[0,0,1] neg_hi:[0,0,1]
	v_pk_add_f32 v[194:195], v[194:195], v[198:199] neg_lo:[0,1] neg_hi:[0,1]
	v_pk_add_f32 v[196:197], v[196:197], v[200:201] neg_lo:[0,1] neg_hi:[0,1]
	v_pk_fma_f32 v[202:203], v[186:187], v[146:147], v[202:203] op_sel_hi:[1,0,1]
	v_pk_fma_f32 v[204:205], v[188:189], v[146:147], v[204:205] op_sel_hi:[1,0,1]
	v_pk_add_f32 v[194:195], v[194:195], v[202:203]
	v_pk_add_f32 v[196:197], v[196:197], v[204:205]
	v_exp_f32_e32 v194, v194
	v_exp_f32_e32 v195, v195
	v_exp_f32_e32 v196, v196
	v_exp_f32_e32 v197, v197
	v_cvt_i32_f32_e32 v198, v198
	v_cvt_i32_f32_e32 v199, v199
	v_cvt_i32_f32_e32 v200, v200
	v_cvt_i32_f32_e32 v201, v201
	v_ldexp_f32 v194, v194, v198
	v_ldexp_f32 v195, v195, v199
	v_ldexp_f32 v196, v196, v200
	v_ldexp_f32 v197, v197, v201
	v_pk_mul_f32 v[194:195], v[48:49], v[194:195]
	v_pk_mul_f32 v[196:197], v[50:51], v[196:197]
	v_cvt_pk_f16_f32 v148, v194, v195
	v_cvt_pk_f16_f32 v149, v196, v197
	ds_write_b64 v150, v[148:149] offset:8736
	v_add_f32_e32 v134, 0xc3200000, v132
	v_pk_add_f32 v[206:207], v[134:135], v[136:137] op_sel_hi:[0,1]
	v_pk_add_f32 v[208:209], v[134:135], v[138:139] op_sel_hi:[0,1]
; #define FOR_R _Pragma("unroll") for (int r = 0; r < 4; ++r)
; #define FOR_AI _Pragma("unroll") for (int ai = 0; ai < 2; ++ai)
; #define FOR_BJ _Pragma("unroll") for (int bj = 0; bj < 2; ++bj)
; #define FOR_M4 _Pragma("unroll") for (int m = 0; m < 4; ++m)
; #define FOR_NN _Pragma("unroll") for (int n = 0; n < 2; ++n)
; __device__ void job_scores_g(const P& p, int l, int job, HALF* sm) {
;     ...
;   FOR_AI FOR_BJ {
;     FOR_M4 FOR_NN {
;       const int j0 = ai * 128 + wr * 64 + m * 16 + fq * 4;
;       const int i = bj * 128 + wc * 32 + n * 16 + fr;
;       f4 o;
;       FOR_R {
;         const int j = j0 + r;
;         const float d = (j <= i) ? expf(lgf * (float)(i - j)) : expf(lgb * (float)(j - i));
;         o[r] = acc[ai][bj][m][n][r] * d;
;       }
;       stage2_T(sm, i, j0, to_h4(o));
;     }
;     __builtin_amdgcn_sched_barrier(0);
;   }
	v_pk_mul_f32 v[186:187], v[206:207], v[140:141] op_sel_hi:[1,0]
	v_pk_mul_f32 v[188:189], v[208:209], v[140:141] op_sel_hi:[1,0]
	v_pk_mul_f32 v[190:191], v[206:207], v[142:143] op_sel_hi:[1,0]
	v_pk_mul_f32 v[192:193], v[208:209], v[142:143] op_sel_hi:[1,0]
	v_min_f32_e32 v186, v186, v190
	v_min_f32_e32 v187, v187, v191
	v_min_f32_e32 v188, v188, v192
	v_min_f32_e32 v189, v189, v193
	v_pk_mul_f32 v[194:195], v[186:187], v[144:145] op_sel_hi:[1,0]
	v_pk_mul_f32 v[196:197], v[188:189], v[144:145] op_sel_hi:[1,0]
	v_rndne_f32_e32 v198, v194
	v_rndne_f32_e32 v199, v195
	v_rndne_f32_e32 v200, v196
	v_rndne_f32_e32 v201, v197
	v_pk_fma_f32 v[202:203], v[186:187], v[144:145], v[194:195] op_sel_hi:[1,0,1] neg_lo:[0,0,1] neg_hi:[0,0,1]
	v_pk_fma_f32 v[204:205], v[188:189], v[144:145], v[196:197] op_sel_hi:[1,0,1] neg_lo:[0,0,1] neg_hi:[0,0,1]
	v_pk_add_f32 v[194:195], v[194:195], v[198:199] neg_lo:[0,1] neg_hi:[0,1]
	v_pk_add_f32 v[196:197], v[196:197], v[200:201] neg_lo:[0,1] neg_hi:[0,1]
	v_pk_fma_f32 v[202:203], v[186:187], v[146:147], v[202:203] op_sel_hi:[1,0,1]
	v_pk_fma_f32 v[204:205], v[188:189], v[146:147], v[204:205] op_sel_hi:[1,0,1]
	v_pk_add_f32 v[194:195], v[194:195], v[202:203]
	v_pk_add_f32 v[196:197], v[196:197], v[204:205]
	v_exp_f32_e32 v194, v194
	v_exp_f32_e32 v195, v195
	v_exp_f32_e32 v196, v196
	v_exp_f32_e32 v197, v197
	v_cvt_i32_f32_e32 v198, v198
	v_cvt_i32_f32_e32 v199, v199
	v_cvt_i32_f32_e32 v200, v200
	v_cvt_i32_f32_e32 v201, v201
	v_ldexp_f32 v194, v194, v198
	v_ldexp_f32 v195, v195, v199
	v_ldexp_f32 v196, v196, v200
	v_ldexp_f32 v197, v197, v201
	v_pk_mul_f32 v[194:195], v[44:45], v[194:195]
	v_pk_mul_f32 v[196:197], v[46:47], v[196:197]
	v_cvt_pk_f16_f32 v148, v194, v195
	v_cvt_pk_f16_f32 v149, v196, v197
	ds_write_b64 v150, v[148:149] offset:320
	v_add_f32_e32 v134, 0xc3100000, v132
	v_pk_add_f32 v[206:207], v[134:135], v[136:137] op_sel_hi:[0,1]
	v_pk_add_f32 v[208:209], v[134:135], v[138:139] op_sel_hi:[0,1]
	v_pk_mul_f32 v[186:187], v[206:207], v[140:141] op_sel_hi:[1,0]
	v_pk_mul_f32 v[188:189], v[208:209], v[140:141] op_sel_hi:[1,0]
	v_pk_mul_f32 v[190:191], v[206:207], v[142:143] op_sel_hi:[1,0]
	v_pk_mul_f32 v[192:193], v[208:209], v[142:143] op_sel_hi:[1,0]
	v_min_f32_e32 v186, v186, v190
	v_min_f32_e32 v187, v187, v191
	v_min_f32_e32 v188, v188, v192
	v_min_f32_e32 v189, v189, v193
	v_pk_mul_f32 v[194:195], v[186:187], v[144:145] op_sel_hi:[1,0]
	v_pk_mul_f32 v[196:197], v[188:189], v[144:145] op_sel_hi:[1,0]
	v_rndne_f32_e32 v198, v194
	v_rndne_f32_e32 v199, v195
	v_rndne_f32_e32 v200, v196
	v_rndne_f32_e32 v201, v197
	v_pk_fma_f32 v[202:203], v[186:187], v[144:145], v[194:195] op_sel_hi:[1,0,1] neg_lo:[0,0,1] neg_hi:[0,0,1]
	v_pk_fma_f32 v[204:205], v[188:189], v[144:145], v[196:197] op_sel_hi:[1,0,1] neg_lo:[0,0,1] neg_hi:[0,0,1]
	v_pk_add_f32 v[194:195], v[194:195], v[198:199] neg_lo:[0,1] neg_hi:[0,1]
	v_pk_add_f32 v[196:197], v[196:197], v[200:201] neg_lo:[0,1] neg_hi:[0,1]
	v_pk_fma_f32 v[202:203], v[186:187], v[146:147], v[202:203] op_sel_hi:[1,0,1]
	v_pk_fma_f32 v[204:205], v[188:189], v[146:147], v[204:205] op_sel_hi:[1,0,1]
	v_pk_add_f32 v[194:195], v[194:195], v[202:203]
	v_pk_add_f32 v[196:197], v[196:197], v[204:205]
	v_exp_f32_e32 v194, v194
	v_exp_f32_e32 v195, v195
	v_exp_f32_e32 v196, v196
	v_exp_f32_e32 v197, v197
	v_cvt_i32_f32_e32 v198, v198
	v_cvt_i32_f32_e32 v199, v199
	v_cvt_i32_f32_e32 v200, v200
	v_cvt_i32_f32_e32 v201, v201
	v_ldexp_f32 v194, v194, v198
	v_ldexp_f32 v195, v195, v199
	v_ldexp_f32 v196, v196, v200
	v_ldexp_f32 v197, v197, v201
	v_pk_mul_f32 v[194:195], v[40:41], v[194:195]
	v_pk_mul_f32 v[196:197], v[42:43], v[196:197]
	v_cvt_pk_f16_f32 v148, v194, v195
	v_cvt_pk_f16_f32 v149, v196, v197
	ds_write_b64 v150, v[148:149] offset:8768
	v_add_f32_e32 v134, 0xc3300000, v132
	v_pk_add_f32 v[206:207], v[134:135], v[136:137] op_sel_hi:[0,1]
	v_pk_add_f32 v[208:209], v[134:135], v[138:139] op_sel_hi:[0,1]
	v_pk_mul_f32 v[186:187], v[206:207], v[140:141] op_sel_hi:[1,0]
	v_pk_mul_f32 v[188:189], v[208:209], v[140:141] op_sel_hi:[1,0]
	v_pk_mul_f32 v[190:191], v[206:207], v[142:143] op_sel_hi:[1,0]
	v_pk_mul_f32 v[192:193], v[208:209], v[142:143] op_sel_hi:[1,0]
	v_min_f32_e32 v186, v186, v190
	v_min_f32_e32 v187, v187, v191
	v_min_f32_e32 v188, v188, v192
	v_min_f32_e32 v189, v189, v193
	v_pk_mul_f32 v[194:195], v[186:187], v[144:145] op_sel_hi:[1,0]
	v_pk_mul_f32 v[196:197], v[188:189], v[144:145] op_sel_hi:[1,0]
	v_rndne_f32_e32 v198, v194
	v_rndne_f32_e32 v199, v195
	v_rndne_f32_e32 v200, v196
	v_rndne_f32_e32 v201, v197
	v_pk_fma_f32 v[202:203], v[186:187], v[144:145], v[194:195] op_sel_hi:[1,0,1] neg_lo:[0,0,1] neg_hi:[0,0,1]
	v_pk_fma_f32 v[204:205], v[188:189], v[144:145], v[196:197] op_sel_hi:[1,0,1] neg_lo:[0,0,1] neg_hi:[0,0,1]
	v_pk_add_f32 v[194:195], v[194:195], v[198:199] neg_lo:[0,1] neg_hi:[0,1]
	v_pk_add_f32 v[196:197], v[196:197], v[200:201] neg_lo:[0,1] neg_hi:[0,1]
	v_pk_fma_f32 v[202:203], v[186:187], v[146:147], v[202:203] op_sel_hi:[1,0,1]
	v_pk_fma_f32 v[204:205], v[188:189], v[146:147], v[204:205] op_sel_hi:[1,0,1]
	v_pk_add_f32 v[194:195], v[194:195], v[202:203]
	v_pk_add_f32 v[196:197], v[196:197], v[204:205]
	v_exp_f32_e32 v194, v194
	v_exp_f32_e32 v195, v195
	v_exp_f32_e32 v196, v196
	v_exp_f32_e32 v197, v197
	v_cvt_i32_f32_e32 v198, v198
	v_cvt_i32_f32_e32 v199, v199
	v_cvt_i32_f32_e32 v200, v200
	v_cvt_i32_f32_e32 v201, v201
	v_ldexp_f32 v194, v194, v198
	v_ldexp_f32 v195, v195, v199
	v_ldexp_f32 v196, v196, v200
	v_ldexp_f32 v197, v197, v201
	v_pk_mul_f32 v[194:195], v[36:37], v[194:195]
	v_pk_mul_f32 v[196:197], v[38:39], v[196:197]
; #define FOR_R _Pragma("unroll") for (int r = 0; r < 4; ++r)
; #define FOR_AI _Pragma("unroll") for (int ai = 0; ai < 2; ++ai)
; #define FOR_BJ _Pragma("unroll") for (int bj = 0; bj < 2; ++bj)
; #define FOR_M4 _Pragma("unroll") for (int m = 0; m < 4; ++m)
; #define FOR_NN _Pragma("unroll") for (int n = 0; n < 2; ++n)
; __device__ void job_scores_g(const P& p, int l, int job, HALF* sm) {
;     ...
;   FOR_AI FOR_BJ {
;     FOR_M4 FOR_NN {
;       const int j0 = ai * 128 + wr * 64 + m * 16 + fq * 4;
;       const int i = bj * 128 + wc * 32 + n * 16 + fr;
;       f4 o;
;       FOR_R {
;         const int j = j0 + r;
;         const float d = (j <= i) ? expf(lgf * (float)(i - j)) : expf(lgb * (float)(j - i));
;         o[r] = acc[ai][bj][m][n][r] * d;
;       }
;       stage2_T(sm, i, j0, to_h4(o));
;     }
;     __builtin_amdgcn_sched_barrier(0);
;   }
	v_cvt_pk_f16_f32 v148, v194, v195
	v_cvt_pk_f16_f32 v149, v196, v197
	ds_write_b64 v150, v[148:149] offset:352
	v_add_f32_e32 v134, 0xc3200000, v132
	v_pk_add_f32 v[206:207], v[134:135], v[136:137] op_sel_hi:[0,1]
	v_pk_add_f32 v[208:209], v[134:135], v[138:139] op_sel_hi:[0,1]
	v_pk_mul_f32 v[186:187], v[206:207], v[140:141] op_sel_hi:[1,0]
	v_pk_mul_f32 v[188:189], v[208:209], v[140:141] op_sel_hi:[1,0]
	v_pk_mul_f32 v[190:191], v[206:207], v[142:143] op_sel_hi:[1,0]
	v_pk_mul_f32 v[192:193], v[208:209], v[142:143] op_sel_hi:[1,0]
	v_min_f32_e32 v186, v186, v190
	v_min_f32_e32 v187, v187, v191
	v_min_f32_e32 v188, v188, v192
	v_min_f32_e32 v189, v189, v193
	v_pk_mul_f32 v[194:195], v[186:187], v[144:145] op_sel_hi:[1,0]
	v_pk_mul_f32 v[196:197], v[188:189], v[144:145] op_sel_hi:[1,0]
	v_rndne_f32_e32 v198, v194
	v_rndne_f32_e32 v199, v195
	v_rndne_f32_e32 v200, v196
	v_rndne_f32_e32 v201, v197
	v_pk_fma_f32 v[202:203], v[186:187], v[144:145], v[194:195] op_sel_hi:[1,0,1] neg_lo:[0,0,1] neg_hi:[0,0,1]
	v_pk_fma_f32 v[204:205], v[188:189], v[144:145], v[196:197] op_sel_hi:[1,0,1] neg_lo:[0,0,1] neg_hi:[0,0,1]
	v_pk_add_f32 v[194:195], v[194:195], v[198:199] neg_lo:[0,1] neg_hi:[0,1]
	v_pk_add_f32 v[196:197], v[196:197], v[200:201] neg_lo:[0,1] neg_hi:[0,1]
	v_pk_fma_f32 v[202:203], v[186:187], v[146:147], v[202:203] op_sel_hi:[1,0,1]
	v_pk_fma_f32 v[204:205], v[188:189], v[146:147], v[204:205] op_sel_hi:[1,0,1]
	v_pk_add_f32 v[194:195], v[194:195], v[202:203]
	v_pk_add_f32 v[196:197], v[196:197], v[204:205]
	v_exp_f32_e32 v194, v194
	v_exp_f32_e32 v195, v195
	v_exp_f32_e32 v196, v196
	v_exp_f32_e32 v197, v197
	v_cvt_i32_f32_e32 v198, v198
	v_cvt_i32_f32_e32 v199, v199
	v_cvt_i32_f32_e32 v200, v200
	v_cvt_i32_f32_e32 v201, v201
	v_ldexp_f32 v194, v194, v198
	v_ldexp_f32 v195, v195, v199
	v_ldexp_f32 v196, v196, v200
	v_ldexp_f32 v197, v197, v201
	v_pk_mul_f32 v[194:195], v[32:33], v[194:195]
	v_pk_mul_f32 v[196:197], v[34:35], v[196:197]
	v_cvt_pk_f16_f32 v148, v194, v195
	v_cvt_pk_f16_f32 v149, v196, v197
	ds_write_b64 v150, v[148:149] offset:8800
	v_add_f32_e32 v134, 0x00000000, v132
	v_pk_add_f32 v[206:207], v[134:135], v[136:137] op_sel_hi:[0,1]
	v_pk_add_f32 v[208:209], v[134:135], v[138:139] op_sel_hi:[0,1]
	v_pk_mul_f32 v[186:187], v[206:207], v[140:141] op_sel_hi:[1,0]
	v_pk_mul_f32 v[188:189], v[208:209], v[140:141] op_sel_hi:[1,0]
	v_pk_mul_f32 v[190:191], v[206:207], v[142:143] op_sel_hi:[1,0]
	v_pk_mul_f32 v[192:193], v[208:209], v[142:143] op_sel_hi:[1,0]
	v_min_f32_e32 v186, v186, v190
	v_min_f32_e32 v187, v187, v191
	v_min_f32_e32 v188, v188, v192
	v_min_f32_e32 v189, v189, v193
	v_pk_mul_f32 v[194:195], v[186:187], v[144:145] op_sel_hi:[1,0]
	v_pk_mul_f32 v[196:197], v[188:189], v[144:145] op_sel_hi:[1,0]
	v_rndne_f32_e32 v198, v194
	v_rndne_f32_e32 v199, v195
	v_rndne_f32_e32 v200, v196
	v_rndne_f32_e32 v201, v197
	v_pk_fma_f32 v[202:203], v[186:187], v[144:145], v[194:195] op_sel_hi:[1,0,1] neg_lo:[0,0,1] neg_hi:[0,0,1]
	v_pk_fma_f32 v[204:205], v[188:189], v[144:145], v[196:197] op_sel_hi:[1,0,1] neg_lo:[0,0,1] neg_hi:[0,0,1]
	v_pk_add_f32 v[194:195], v[194:195], v[198:199] neg_lo:[0,1] neg_hi:[0,1]
	v_pk_add_f32 v[196:197], v[196:197], v[200:201] neg_lo:[0,1] neg_hi:[0,1]
	v_pk_fma_f32 v[202:203], v[186:187], v[146:147], v[202:203] op_sel_hi:[1,0,1]
	v_pk_fma_f32 v[204:205], v[188:189], v[146:147], v[204:205] op_sel_hi:[1,0,1]
	v_pk_add_f32 v[194:195], v[194:195], v[202:203]
	v_pk_add_f32 v[196:197], v[196:197], v[204:205]
	v_exp_f32_e32 v194, v194
	v_exp_f32_e32 v195, v195
	v_exp_f32_e32 v196, v196
	v_exp_f32_e32 v197, v197
	v_cvt_i32_f32_e32 v198, v198
	v_cvt_i32_f32_e32 v199, v199
	v_cvt_i32_f32_e32 v200, v200
	v_cvt_i32_f32_e32 v201, v201
	v_ldexp_f32 v194, v194, v198
	v_ldexp_f32 v195, v195, v199
	v_ldexp_f32 v196, v196, v200
	v_ldexp_f32 v197, v197, v201
	v_pk_mul_f32 v[194:195], v[28:29], v[194:195]
	v_pk_mul_f32 v[196:197], v[30:31], v[196:197]
	v_cvt_pk_f16_f32 v148, v194, v195
	v_cvt_pk_f16_f32 v149, v196, v197
	ds_write_b64 v151, v[148:149] offset:256
	v_add_f32_e32 v134, 0x41800000, v132
	v_pk_add_f32 v[206:207], v[134:135], v[136:137] op_sel_hi:[0,1]
	v_pk_add_f32 v[208:209], v[134:135], v[138:139] op_sel_hi:[0,1]
	v_pk_mul_f32 v[186:187], v[206:207], v[140:141] op_sel_hi:[1,0]
	v_pk_mul_f32 v[188:189], v[208:209], v[140:141] op_sel_hi:[1,0]
	v_pk_mul_f32 v[190:191], v[206:207], v[142:143] op_sel_hi:[1,0]
	v_pk_mul_f32 v[192:193], v[208:209], v[142:143] op_sel_hi:[1,0]
	v_min_f32_e32 v186, v186, v190
	v_min_f32_e32 v187, v187, v191
	v_min_f32_e32 v188, v188, v192
	v_min_f32_e32 v189, v189, v193
	v_pk_mul_f32 v[194:195], v[186:187], v[144:145] op_sel_hi:[1,0]
	v_pk_mul_f32 v[196:197], v[188:189], v[144:145] op_sel_hi:[1,0]
	v_rndne_f32_e32 v198, v194
	v_rndne_f32_e32 v199, v195
	v_rndne_f32_e32 v200, v196
	v_rndne_f32_e32 v201, v197
	v_pk_fma_f32 v[202:203], v[186:187], v[144:145], v[194:195] op_sel_hi:[1,0,1] neg_lo:[0,0,1] neg_hi:[0,0,1]
	v_pk_fma_f32 v[204:205], v[188:189], v[144:145], v[196:197] op_sel_hi:[1,0,1] neg_lo:[0,0,1] neg_hi:[0,0,1]
	v_pk_add_f32 v[194:195], v[194:195], v[198:199] neg_lo:[0,1] neg_hi:[0,1]
	v_pk_add_f32 v[196:197], v[196:197], v[200:201] neg_lo:[0,1] neg_hi:[0,1]
	v_pk_fma_f32 v[202:203], v[186:187], v[146:147], v[202:203] op_sel_hi:[1,0,1]
	v_pk_fma_f32 v[204:205], v[188:189], v[146:147], v[204:205] op_sel_hi:[1,0,1]
	v_pk_add_f32 v[194:195], v[194:195], v[202:203]
	v_pk_add_f32 v[196:197], v[196:197], v[204:205]
	v_exp_f32_e32 v194, v194
	v_exp_f32_e32 v195, v195
	v_exp_f32_e32 v196, v196
	v_exp_f32_e32 v197, v197
	v_cvt_i32_f32_e32 v198, v198
	v_cvt_i32_f32_e32 v199, v199
; #define FOR_R _Pragma("unroll") for (int r = 0; r < 4; ++r)
; #define FOR_AI _Pragma("unroll") for (int ai = 0; ai < 2; ++ai)
; #define FOR_BJ _Pragma("unroll") for (int bj = 0; bj < 2; ++bj)
; #define FOR_M4 _Pragma("unroll") for (int m = 0; m < 4; ++m)
; #define FOR_NN _Pragma("unroll") for (int n = 0; n < 2; ++n)
; __device__ void job_scores_g(const P& p, int l, int job, HALF* sm) {
;     ...
;   FOR_AI FOR_BJ {
;     FOR_M4 FOR_NN {
;       const int j0 = ai * 128 + wr * 64 + m * 16 + fq * 4;
;       const int i = bj * 128 + wc * 32 + n * 16 + fr;
;       f4 o;
;       FOR_R {
;         const int j = j0 + r;
;         const float d = (j <= i) ? expf(lgf * (float)(i - j)) : expf(lgb * (float)(j - i));
;         o[r] = acc[ai][bj][m][n][r] * d;
;       }
;       stage2_T(sm, i, j0, to_h4(o));
;     }
;     __builtin_amdgcn_sched_barrier(0);
;   }
	v_cvt_i32_f32_e32 v200, v200
	v_cvt_i32_f32_e32 v201, v201
	v_ldexp_f32 v194, v194, v198
	v_ldexp_f32 v195, v195, v199
	v_ldexp_f32 v196, v196, v200
	v_ldexp_f32 v197, v197, v201
	v_pk_mul_f32 v[194:195], v[24:25], v[194:195]
	v_pk_mul_f32 v[196:197], v[26:27], v[196:197]
	v_cvt_pk_f16_f32 v148, v194, v195
	v_cvt_pk_f16_f32 v149, v196, v197
	ds_write_b64 v151, v[148:149] offset:8704
	v_add_f32_e32 v134, 0xc1800000, v132
	v_pk_add_f32 v[206:207], v[134:135], v[136:137] op_sel_hi:[0,1]
	v_pk_add_f32 v[208:209], v[134:135], v[138:139] op_sel_hi:[0,1]
	v_pk_mul_f32 v[186:187], v[206:207], v[140:141] op_sel_hi:[1,0]
	v_pk_mul_f32 v[188:189], v[208:209], v[140:141] op_sel_hi:[1,0]
	v_pk_mul_f32 v[190:191], v[206:207], v[142:143] op_sel_hi:[1,0]
	v_pk_mul_f32 v[192:193], v[208:209], v[142:143] op_sel_hi:[1,0]
	v_min_f32_e32 v186, v186, v190
	v_min_f32_e32 v187, v187, v191
	v_min_f32_e32 v188, v188, v192
	v_min_f32_e32 v189, v189, v193
	v_pk_mul_f32 v[194:195], v[186:187], v[144:145] op_sel_hi:[1,0]
	v_pk_mul_f32 v[196:197], v[188:189], v[144:145] op_sel_hi:[1,0]
	v_rndne_f32_e32 v198, v194
	v_rndne_f32_e32 v199, v195
	v_rndne_f32_e32 v200, v196
	v_rndne_f32_e32 v201, v197
	v_pk_fma_f32 v[202:203], v[186:187], v[144:145], v[194:195] op_sel_hi:[1,0,1] neg_lo:[0,0,1] neg_hi:[0,0,1]
	v_pk_fma_f32 v[204:205], v[188:189], v[144:145], v[196:197] op_sel_hi:[1,0,1] neg_lo:[0,0,1] neg_hi:[0,0,1]
	v_pk_add_f32 v[194:195], v[194:195], v[198:199] neg_lo:[0,1] neg_hi:[0,1]
	v_pk_add_f32 v[196:197], v[196:197], v[200:201] neg_lo:[0,1] neg_hi:[0,1]
	v_pk_fma_f32 v[202:203], v[186:187], v[146:147], v[202:203] op_sel_hi:[1,0,1]
	v_pk_fma_f32 v[204:205], v[188:189], v[146:147], v[204:205] op_sel_hi:[1,0,1]
	v_pk_add_f32 v[194:195], v[194:195], v[202:203]
	v_pk_add_f32 v[196:197], v[196:197], v[204:205]
	v_exp_f32_e32 v194, v194
	v_exp_f32_e32 v195, v195
	v_exp_f32_e32 v196, v196
	v_exp_f32_e32 v197, v197
	v_cvt_i32_f32_e32 v198, v198
	v_cvt_i32_f32_e32 v199, v199
	v_cvt_i32_f32_e32 v200, v200
	v_cvt_i32_f32_e32 v201, v201
	v_ldexp_f32 v194, v194, v198
	v_ldexp_f32 v195, v195, v199
	v_ldexp_f32 v196, v196, v200
	v_ldexp_f32 v197, v197, v201
	v_pk_mul_f32 v[194:195], v[20:21], v[194:195]
	v_pk_mul_f32 v[196:197], v[22:23], v[196:197]
	v_cvt_pk_f16_f32 v148, v194, v195
	v_cvt_pk_f16_f32 v149, v196, v197
	ds_write_b64 v151, v[148:149] offset:288
	v_add_f32_e32 v134, 0x00000000, v132
	v_pk_add_f32 v[206:207], v[134:135], v[136:137] op_sel_hi:[0,1]
	v_pk_add_f32 v[208:209], v[134:135], v[138:139] op_sel_hi:[0,1]
	v_pk_mul_f32 v[186:187], v[206:207], v[140:141] op_sel_hi:[1,0]
	v_pk_mul_f32 v[188:189], v[208:209], v[140:141] op_sel_hi:[1,0]
	v_pk_mul_f32 v[190:191], v[206:207], v[142:143] op_sel_hi:[1,0]
	v_pk_mul_f32 v[192:193], v[208:209], v[142:143] op_sel_hi:[1,0]
	v_min_f32_e32 v186, v186, v190
	v_min_f32_e32 v187, v187, v191
	v_min_f32_e32 v188, v188, v192
	v_min_f32_e32 v189, v189, v193
	v_pk_mul_f32 v[194:195], v[186:187], v[144:145] op_sel_hi:[1,0]
	v_pk_mul_f32 v[196:197], v[188:189], v[144:145] op_sel_hi:[1,0]
	v_rndne_f32_e32 v198, v194
	v_rndne_f32_e32 v199, v195
	v_rndne_f32_e32 v200, v196
	v_rndne_f32_e32 v201, v197
	v_pk_fma_f32 v[202:203], v[186:187], v[144:145], v[194:195] op_sel_hi:[1,0,1] neg_lo:[0,0,1] neg_hi:[0,0,1]
	v_pk_fma_f32 v[204:205], v[188:189], v[144:145], v[196:197] op_sel_hi:[1,0,1] neg_lo:[0,0,1] neg_hi:[0,0,1]
	v_pk_add_f32 v[194:195], v[194:195], v[198:199] neg_lo:[0,1] neg_hi:[0,1]
	v_pk_add_f32 v[196:197], v[196:197], v[200:201] neg_lo:[0,1] neg_hi:[0,1]
	v_pk_fma_f32 v[202:203], v[186:187], v[146:147], v[202:203] op_sel_hi:[1,0,1]
	v_pk_fma_f32 v[204:205], v[188:189], v[146:147], v[204:205] op_sel_hi:[1,0,1]
	v_pk_add_f32 v[194:195], v[194:195], v[202:203]
	v_pk_add_f32 v[196:197], v[196:197], v[204:205]
	v_exp_f32_e32 v194, v194
	v_exp_f32_e32 v195, v195
	v_exp_f32_e32 v196, v196
	v_exp_f32_e32 v197, v197
	v_cvt_i32_f32_e32 v198, v198
	v_cvt_i32_f32_e32 v199, v199
	v_cvt_i32_f32_e32 v200, v200
	v_cvt_i32_f32_e32 v201, v201
	v_ldexp_f32 v194, v194, v198
	v_ldexp_f32 v195, v195, v199
	v_ldexp_f32 v196, v196, v200
	v_ldexp_f32 v197, v197, v201
	v_pk_mul_f32 v[194:195], v[16:17], v[194:195]
	v_pk_mul_f32 v[196:197], v[18:19], v[196:197]
	v_cvt_pk_f16_f32 v148, v194, v195
	v_cvt_pk_f16_f32 v149, v196, v197
	ds_write_b64 v151, v[148:149] offset:8736
	v_add_f32_e32 v134, 0xc2000000, v132
	v_pk_add_f32 v[206:207], v[134:135], v[136:137] op_sel_hi:[0,1]
	v_pk_add_f32 v[208:209], v[134:135], v[138:139] op_sel_hi:[0,1]
	v_pk_mul_f32 v[186:187], v[206:207], v[140:141] op_sel_hi:[1,0]
	v_pk_mul_f32 v[188:189], v[208:209], v[140:141] op_sel_hi:[1,0]
	v_pk_mul_f32 v[190:191], v[206:207], v[142:143] op_sel_hi:[1,0]
	v_pk_mul_f32 v[192:193], v[208:209], v[142:143] op_sel_hi:[1,0]
	v_min_f32_e32 v186, v186, v190
	v_min_f32_e32 v187, v187, v191
	v_min_f32_e32 v188, v188, v192
	v_min_f32_e32 v189, v189, v193
	v_pk_mul_f32 v[194:195], v[186:187], v[144:145] op_sel_hi:[1,0]
	v_pk_mul_f32 v[196:197], v[188:189], v[144:145] op_sel_hi:[1,0]
	v_rndne_f32_e32 v198, v194
	v_rndne_f32_e32 v199, v195
	v_rndne_f32_e32 v200, v196
	v_rndne_f32_e32 v201, v197
	v_pk_fma_f32 v[202:203], v[186:187], v[144:145], v[194:195] op_sel_hi:[1,0,1] neg_lo:[0,0,1] neg_hi:[0,0,1]
	v_pk_fma_f32 v[204:205], v[188:189], v[144:145], v[196:197] op_sel_hi:[1,0,1] neg_lo:[0,0,1] neg_hi:[0,0,1]
	v_pk_add_f32 v[194:195], v[194:195], v[198:199] neg_lo:[0,1] neg_hi:[0,1]
	v_pk_add_f32 v[196:197], v[196:197], v[200:201] neg_lo:[0,1] neg_hi:[0,1]
	v_pk_fma_f32 v[202:203], v[186:187], v[146:147], v[202:203] op_sel_hi:[1,0,1]
	v_pk_fma_f32 v[204:205], v[188:189], v[146:147], v[204:205] op_sel_hi:[1,0,1]
; #define FOR_R _Pragma("unroll") for (int r = 0; r < 4; ++r)
; #define FOR_AI _Pragma("unroll") for (int ai = 0; ai < 2; ++ai)
; #define FOR_BJ _Pragma("unroll") for (int bj = 0; bj < 2; ++bj)
; #define FOR_M4 _Pragma("unroll") for (int m = 0; m < 4; ++m)
; #define FOR_NN _Pragma("unroll") for (int n = 0; n < 2; ++n)
; __device__ void job_scores_g(const P& p, int l, int job, HALF* sm) {
;     ...
;   FOR_AI FOR_BJ {
;     FOR_M4 FOR_NN {
;       const int j0 = ai * 128 + wr * 64 + m * 16 + fq * 4;
;       const int i = bj * 128 + wc * 32 + n * 16 + fr;
;       f4 o;
;       FOR_R {
;         const int j = j0 + r;
;         const float d = (j <= i) ? expf(lgf * (float)(i - j)) : expf(lgb * (float)(j - i));
;         o[r] = acc[ai][bj][m][n][r] * d;
;       }
;       stage2_T(sm, i, j0, to_h4(o));
;     }
;     __builtin_amdgcn_sched_barrier(0);
;   }
	v_pk_add_f32 v[194:195], v[194:195], v[202:203]
	v_pk_add_f32 v[196:197], v[196:197], v[204:205]
	v_exp_f32_e32 v194, v194
	v_exp_f32_e32 v195, v195
	v_exp_f32_e32 v196, v196
	v_exp_f32_e32 v197, v197
	v_cvt_i32_f32_e32 v198, v198
	v_cvt_i32_f32_e32 v199, v199
	v_cvt_i32_f32_e32 v200, v200
	v_cvt_i32_f32_e32 v201, v201
	v_ldexp_f32 v194, v194, v198
	v_ldexp_f32 v195, v195, v199
	v_ldexp_f32 v196, v196, v200
	v_ldexp_f32 v197, v197, v201
	v_pk_mul_f32 v[194:195], v[12:13], v[194:195]
	v_pk_mul_f32 v[196:197], v[14:15], v[196:197]
	v_cvt_pk_f16_f32 v148, v194, v195
	v_cvt_pk_f16_f32 v149, v196, v197
	ds_write_b64 v151, v[148:149] offset:320
	v_add_f32_e32 v134, 0xc1800000, v132
	v_pk_add_f32 v[206:207], v[134:135], v[136:137] op_sel_hi:[0,1]
	v_pk_add_f32 v[208:209], v[134:135], v[138:139] op_sel_hi:[0,1]
	v_pk_mul_f32 v[186:187], v[206:207], v[140:141] op_sel_hi:[1,0]
	v_pk_mul_f32 v[188:189], v[208:209], v[140:141] op_sel_hi:[1,0]
	v_pk_mul_f32 v[190:191], v[206:207], v[142:143] op_sel_hi:[1,0]
	v_pk_mul_f32 v[192:193], v[208:209], v[142:143] op_sel_hi:[1,0]
	v_min_f32_e32 v186, v186, v190
	v_min_f32_e32 v187, v187, v191
	v_min_f32_e32 v188, v188, v192
	v_min_f32_e32 v189, v189, v193
	v_pk_mul_f32 v[194:195], v[186:187], v[144:145] op_sel_hi:[1,0]
	v_pk_mul_f32 v[196:197], v[188:189], v[144:145] op_sel_hi:[1,0]
	v_rndne_f32_e32 v198, v194
	v_rndne_f32_e32 v199, v195
	v_rndne_f32_e32 v200, v196
	v_rndne_f32_e32 v201, v197
	v_pk_fma_f32 v[202:203], v[186:187], v[144:145], v[194:195] op_sel_hi:[1,0,1] neg_lo:[0,0,1] neg_hi:[0,0,1]
	v_pk_fma_f32 v[204:205], v[188:189], v[144:145], v[196:197] op_sel_hi:[1,0,1] neg_lo:[0,0,1] neg_hi:[0,0,1]
	v_pk_add_f32 v[194:195], v[194:195], v[198:199] neg_lo:[0,1] neg_hi:[0,1]
	v_pk_add_f32 v[196:197], v[196:197], v[200:201] neg_lo:[0,1] neg_hi:[0,1]
	v_pk_fma_f32 v[202:203], v[186:187], v[146:147], v[202:203] op_sel_hi:[1,0,1]
	v_pk_fma_f32 v[204:205], v[188:189], v[146:147], v[204:205] op_sel_hi:[1,0,1]
	v_pk_add_f32 v[194:195], v[194:195], v[202:203]
	v_pk_add_f32 v[196:197], v[196:197], v[204:205]
	v_exp_f32_e32 v194, v194
	v_exp_f32_e32 v195, v195
	v_exp_f32_e32 v196, v196
	v_exp_f32_e32 v197, v197
	v_cvt_i32_f32_e32 v198, v198
	v_cvt_i32_f32_e32 v199, v199
	v_cvt_i32_f32_e32 v200, v200
	v_cvt_i32_f32_e32 v201, v201
	v_ldexp_f32 v194, v194, v198
	v_ldexp_f32 v195, v195, v199
	v_ldexp_f32 v196, v196, v200
	v_ldexp_f32 v197, v197, v201
	v_pk_mul_f32 v[194:195], v[8:9], v[194:195]
	v_pk_mul_f32 v[196:197], v[10:11], v[196:197]
	v_cvt_pk_f16_f32 v148, v194, v195
	v_cvt_pk_f16_f32 v149, v196, v197
	ds_write_b64 v151, v[148:149] offset:8768
	v_add_f32_e32 v134, 0xc2400000, v132
	v_pk_add_f32 v[206:207], v[134:135], v[136:137] op_sel_hi:[0,1]
	v_pk_add_f32 v[208:209], v[134:135], v[138:139] op_sel_hi:[0,1]
	v_pk_mul_f32 v[186:187], v[206:207], v[140:141] op_sel_hi:[1,0]
	v_pk_mul_f32 v[188:189], v[208:209], v[140:141] op_sel_hi:[1,0]
	v_pk_mul_f32 v[190:191], v[206:207], v[142:143] op_sel_hi:[1,0]
	v_pk_mul_f32 v[192:193], v[208:209], v[142:143] op_sel_hi:[1,0]
	v_min_f32_e32 v186, v186, v190
	v_min_f32_e32 v187, v187, v191
	v_min_f32_e32 v188, v188, v192
	v_min_f32_e32 v189, v189, v193
	v_pk_mul_f32 v[194:195], v[186:187], v[144:145] op_sel_hi:[1,0]
	v_pk_mul_f32 v[196:197], v[188:189], v[144:145] op_sel_hi:[1,0]
	v_rndne_f32_e32 v198, v194
	v_rndne_f32_e32 v199, v195
	v_rndne_f32_e32 v200, v196
	v_rndne_f32_e32 v201, v197
	v_pk_fma_f32 v[202:203], v[186:187], v[144:145], v[194:195] op_sel_hi:[1,0,1] neg_lo:[0,0,1] neg_hi:[0,0,1]
	v_pk_fma_f32 v[204:205], v[188:189], v[144:145], v[196:197] op_sel_hi:[1,0,1] neg_lo:[0,0,1] neg_hi:[0,0,1]
	v_pk_add_f32 v[194:195], v[194:195], v[198:199] neg_lo:[0,1] neg_hi:[0,1]
	v_pk_add_f32 v[196:197], v[196:197], v[200:201] neg_lo:[0,1] neg_hi:[0,1]
	v_pk_fma_f32 v[202:203], v[186:187], v[146:147], v[202:203] op_sel_hi:[1,0,1]
	v_pk_fma_f32 v[204:205], v[188:189], v[146:147], v[204:205] op_sel_hi:[1,0,1]
	v_pk_add_f32 v[194:195], v[194:195], v[202:203]
	v_pk_add_f32 v[196:197], v[196:197], v[204:205]
	v_exp_f32_e32 v194, v194
	v_exp_f32_e32 v195, v195
	v_exp_f32_e32 v196, v196
	v_exp_f32_e32 v197, v197
	v_cvt_i32_f32_e32 v198, v198
	v_cvt_i32_f32_e32 v199, v199
	v_cvt_i32_f32_e32 v200, v200
	v_cvt_i32_f32_e32 v201, v201
	v_ldexp_f32 v194, v194, v198
	v_ldexp_f32 v195, v195, v199
	v_ldexp_f32 v196, v196, v200
	v_ldexp_f32 v197, v197, v201
	v_pk_mul_f32 v[194:195], v[4:5], v[194:195]
	v_pk_mul_f32 v[196:197], v[6:7], v[196:197]
	v_cvt_pk_f16_f32 v148, v194, v195
	v_cvt_pk_f16_f32 v149, v196, v197
	ds_write_b64 v151, v[148:149] offset:352
	v_add_f32_e32 v134, 0xc2000000, v132
	v_pk_add_f32 v[206:207], v[134:135], v[136:137] op_sel_hi:[0,1]
	v_pk_add_f32 v[208:209], v[134:135], v[138:139] op_sel_hi:[0,1]
	v_pk_mul_f32 v[186:187], v[206:207], v[140:141] op_sel_hi:[1,0]
	v_pk_mul_f32 v[188:189], v[208:209], v[140:141] op_sel_hi:[1,0]
	v_pk_mul_f32 v[190:191], v[206:207], v[142:143] op_sel_hi:[1,0]
	v_pk_mul_f32 v[192:193], v[208:209], v[142:143] op_sel_hi:[1,0]
	v_min_f32_e32 v186, v186, v190
	v_min_f32_e32 v187, v187, v191
	v_min_f32_e32 v188, v188, v192
	v_min_f32_e32 v189, v189, v193
	v_pk_mul_f32 v[194:195], v[186:187], v[144:145] op_sel_hi:[1,0]
	v_pk_mul_f32 v[196:197], v[188:189], v[144:145] op_sel_hi:[1,0]
	v_rndne_f32_e32 v198, v194
	v_rndne_f32_e32 v199, v195
	v_rndne_f32_e32 v200, v196
	v_rndne_f32_e32 v201, v197
	v_pk_fma_f32 v[202:203], v[186:187], v[144:145], v[194:195] op_sel_hi:[1,0,1] neg_lo:[0,0,1] neg_hi:[0,0,1]
	v_pk_fma_f32 v[204:205], v[188:189], v[144:145], v[196:197] op_sel_hi:[1,0,1] neg_lo:[0,0,1] neg_hi:[0,0,1]
	v_pk_add_f32 v[194:195], v[194:195], v[198:199] neg_lo:[0,1] neg_hi:[0,1]
	v_pk_add_f32 v[196:197], v[196:197], v[200:201] neg_lo:[0,1] neg_hi:[0,1]
	v_pk_fma_f32 v[202:203], v[186:187], v[146:147], v[202:203] op_sel_hi:[1,0,1]
	v_pk_fma_f32 v[204:205], v[188:189], v[146:147], v[204:205] op_sel_hi:[1,0,1]
	v_pk_add_f32 v[194:195], v[194:195], v[202:203]
	v_pk_add_f32 v[196:197], v[196:197], v[204:205]
	v_exp_f32_e32 v194, v194
	v_exp_f32_e32 v195, v195
	v_exp_f32_e32 v196, v196
	v_exp_f32_e32 v197, v197
	v_cvt_i32_f32_e32 v198, v198
	v_cvt_i32_f32_e32 v199, v199
	v_cvt_i32_f32_e32 v200, v200
	v_cvt_i32_f32_e32 v201, v201
	v_ldexp_f32 v194, v194, v198
	v_ldexp_f32 v195, v195, v199
	v_ldexp_f32 v196, v196, v200
	v_ldexp_f32 v197, v197, v201
	v_pk_mul_f32 v[194:195], v[0:1], v[194:195]
	v_pk_mul_f32 v[196:197], v[2:3], v[196:197]
	v_cvt_pk_f16_f32 v148, v194, v195
	v_cvt_pk_f16_f32 v149, v196, v197
	ds_write_b64 v151, v[148:149] offset:8800
	v_mov_b32_e32 v0, v155
	s_movk_i32 s0, 0x2000
	s_waitcnt lgkmcnt(0)
	s_barrier
; DEV int opaque_tid512() { int t = threadIdx.x; asm volatile("" : "+v"(t)); return t; }
; template <int CPR, class F>
; DEV void flush2(HALF* S, int NR, F fn) {
; #pragma unroll 4
;   for (int id = opaque_tid512(); id < NR * CPR; id += 512) {
;     const int row = id / CPR, ch = id % CPR;
;     const u4 v = *(const u4*)(S + row * SST2 + ch * 8);
;     __builtin_nontemporal_store(v, (u4*)(fn(row, ch)));
;   }
; }
	s_nop 0
	v_cmp_gt_i32_e32 vcc, s0, v0
	s_and_saveexec_b64 s[0:1], vcc
	s_cbranch_execz .LBB0_390
	s_lshl_b32 s11, s2, 8
	v_max_i32_e32 v1, 0x1e00, v0
	s_add_u32 s2, s8, s3
	v_sub_u32_e32 v1, v1, v0
	s_addc_u32 s3, s9, 0
	v_add_u32_e32 v1, 0x1ff, v1
	s_add_u32 s2, s2, 0x2aeb0000
	v_and_b32_e32 v2, 0x600, v1
	s_movk_i32 s6, 0x600
	s_addc_u32 s3, s3, 0
	v_cmp_ne_u32_e32 vcc, s6, v2
	s_and_saveexec_b64 s[6:7], vcc
	s_cbranch_execz .LBB0_387
	v_lshrrev_b32_e32 v2, 9, v1
	v_add_u32_e32 v2, 1, v2
	v_and_b32_e32 v4, 3, v2
	v_lshl_add_u32 v2, v0, 4, 0
	v_lshlrev_b32_e32 v3, 3, v0
	v_sub_u32_e32 v4, 0, v4
	s_mov_b64 s[8:9], 0
